# P0 weight-transpose items rewritten by hand: all 32 row loads + gains requested together (was one dependent gain load + wait per element); P5 conv tables staged in LDS and row scales requested at tile
# speedup vs baseline: 1.2373x; 1.0299x over previous
.LBB0_7:
	s_or_b64 exec, exec, s[4:5]
	s_load_dwordx16 s[16:31], s[0:1], 0x0
	s_load_dwordx16 s[36:51], s[0:1], 0x40
	s_lshr_b32 s72, s12, 6
	v_mov_b32_e32 v1, v214
	s_lshl_b32 s64, s66, 3
	s_waitcnt lgkmcnt(0)
	v_writelane_b32 v244, s36, 4
	v_and_b32_e32 v2, 63, v1
	v_lshlrev_b32_e32 v66, 3, v2
	v_writelane_b32 v244, s37, 5
	v_writelane_b32 v244, s38, 6
	v_writelane_b32 v244, s39, 7
	v_writelane_b32 v244, s40, 8
	v_writelane_b32 v244, s41, 9
	v_writelane_b32 v244, s42, 10
	v_writelane_b32 v244, s43, 11
	v_writelane_b32 v244, s44, 12
	v_writelane_b32 v244, s45, 13
	v_writelane_b32 v244, s46, 14
	v_writelane_b32 v244, s47, 15
	v_writelane_b32 v244, s48, 16
	v_writelane_b32 v244, s49, 17
	v_writelane_b32 v244, s50, 18
	v_writelane_b32 v244, s51, 19
	v_writelane_b32 v244, s12, 20
	s_nop 0
	v_readlane_b32 s0, v244, 0
	s_lshl_b32 s0, s0, 3
	s_add_i32 s68, s0, s72
	s_cmpk_gt_i32 s68, 0x177f
	s_cbranch_scc1 .LBB0_78
	v_and_b32_e32 v100, 31, v2
	v_lshrrev_b32_e32 v101, 5, v2
	v_and_b32_e32 v103, 7, v2
	v_lshrrev_b32_e32 v104, 3, v2
	s_lshl_b32 s0, s72, 14
	v_mul_u32_u24_e32 v102, 33, v101
	v_add_u32_e32 v102, v102, v100
	v_lshl_add_u32 v102, v102, 2, s0
	v_mul_u32_u24_e32 v106, 0x108, v103
	v_add_u32_e32 v106, v106, v104
	v_lshl_add_u32 v106, v106, 2, s0
	v_lshlrev_b32_e32 v107, 5, v103
	s_mov_b32 s75, s68
.Lp0_item:
	s_cmpk_lt_u32 s75, 0x500
	s_cbranch_scc1 .Lp0_in
	s_cmpk_lt_u32 s75, 0x700
	s_cbranch_scc1 .Lp0_out
	s_cmpk_lt_u32 s75, 0x1200
	s_cbranch_scc1 .Lp0_up
	s_add_i32 s3, s75, 0xffffee00
	s_movk_i32 s4, 0x400
	s_movk_i32 s5, 0xb00
	v_readlane_b32 s8, v244, 18
	v_readlane_b32 s9, v244, 19
	s_add_u32 s10, s86, 0x1500000
	s_addc_u32 s11, s87, 0
	s_mov_b32 s56, 0
	s_mov_b32 s60, 0
	s_lshr_b32 s42, s3, 5
	s_and_b32 s43, s3, 31
	s_branch .Lp0_go
.Lp0_in:
	s_mov_b32 s3, s75
	s_movk_i32 s4, 0xa00
	s_movk_i32 s5, 0x400
	s_mov_b64 s[8:9], s[24:25]
	s_add_u32 s10, s86, 0x200000
	s_addc_u32 s11, s87, 0
	s_mov_b64 s[12:13], s[20:21]
	s_mov_b64 s[36:37], s[20:21]
	s_movk_i32 s33, 0x400
	s_mov_b32 s56, 1
	s_mov_b32 s60, 0
	s_mul_i32 s42, s3, 0xcccd
	s_lshr_b32 s42, s42, 22
	s_mul_i32 s43, s42, 0x50
	s_sub_i32 s43, s3, s43
	s_branch .Lp0_go
.Lp0_out:
	s_add_i32 s3, s75, 0xfffffb00
	s_movk_i32 s4, 0x400
	s_movk_i32 s5, 0x400
	v_readlane_b32 s8, v244, 6
	v_readlane_b32 s9, v244, 7
	s_add_u32 s10, s86, 0x800000
	s_addc_u32 s11, s87, 0
	s_mov_b64 s[12:13], s[30:31]
	v_readlane_b32 s36, v244, 4
	v_readlane_b32 s37, v244, 5
	s_movk_i32 s33, 0x100
	s_mov_b32 s56, 1
	s_mov_b32 s60, 0
	s_lshr_b32 s42, s3, 5
	s_and_b32 s43, s3, 31
	s_branch .Lp0_go
.Lp0_up:
	s_add_i32 s3, s75, 0xfffff900
	s_movk_i32 s4, 0x1600
	s_movk_i32 s5, 0x400
	v_readlane_b32 s8, v244, 12
	v_readlane_b32 s9, v244, 13
	s_add_u32 s10, s86, 0xa00000
	s_addc_u32 s11, s87, 0
	v_readlane_b32 s12, v244, 8
	v_readlane_b32 s13, v244, 9
	s_nop 3
	s_mov_b64 s[36:37], s[12:13]
	s_movk_i32 s33, 0x400
	s_mov_b32 s56, 1
	s_mov_b32 s60, 1
	s_mul_i32 s42, s3, 0x5d18
	s_lshr_b32 s42, s42, 22
	s_mul_i32 s43, s42, 0xb0
	s_sub_i32 s43, s3, s43
.Lp0_go:
	s_nop 3
	s_lshl_b32 s42, s42, 6
	s_lshl_b32 s43, s43, 5
	s_cmp_lt_u32 s42, s33
	s_cselect_b32 s14, s12, s36
	s_cselect_b32 s15, s13, s37
	s_cselect_b32 s0, 0, s33
	s_sub_i32 s0, s42, s0
	s_lshl_b32 s0, s0, 2
	s_add_u32 s14, s14, s0
	s_addc_u32 s15, s15, 0
	s_cmp_eq_u32 s56, 0
	s_cbranch_scc1 .Lp0_nogain
	global_load_dwordx4 v[142:145], v107, s[14:15]
	global_load_dwordx4 v[146:149], v107, s[14:15] offset:16
	s_branch .Lp0_w
.Lp0_nogain:
	v_mov_b32_e32 v142, 1.0
	v_mov_b32_e32 v143, 1.0
	v_mov_b32_e32 v144, 1.0
	v_mov_b32_e32 v145, 1.0
	v_mov_b32_e32 v146, 1.0
	v_mov_b32_e32 v147, 1.0
	v_mov_b32_e32 v148, 1.0
	v_mov_b32_e32 v149, 1.0
.Lp0_w:
	s_mul_i32 s0, s42, s4
	s_add_i32 s0, s0, s43
	s_lshl_b32 s0, s0, 2
	s_add_u32 s14, s8, s0
	s_addc_u32 s15, s9, 0
	v_mad_u32_u24 v105, v101, s4, v100
	s_lshl_b32 s1, s4, 3
	v_lshlrev_b32_e32 v105, 2, v105
	global_load_dword v110, v105, s[14:15] nt
	s_add_u32 s14, s14, s1
	s_addc_u32 s15, s15, 0
	global_load_dword v111, v105, s[14:15] nt
	s_add_u32 s14, s14, s1
	s_addc_u32 s15, s15, 0
	global_load_dword v112, v105, s[14:15] nt
	s_add_u32 s14, s14, s1
	s_addc_u32 s15, s15, 0
	global_load_dword v113, v105, s[14:15] nt
	s_add_u32 s14, s14, s1
	s_addc_u32 s15, s15, 0
	global_load_dword v114, v105, s[14:15] nt
	s_add_u32 s14, s14, s1
	s_addc_u32 s15, s15, 0
	global_load_dword v115, v105, s[14:15] nt
	s_add_u32 s14, s14, s1
	s_addc_u32 s15, s15, 0
	global_load_dword v116, v105, s[14:15] nt
	s_add_u32 s14, s14, s1
	s_addc_u32 s15, s15, 0
	global_load_dword v117, v105, s[14:15] nt
	s_add_u32 s14, s14, s1
	s_addc_u32 s15, s15, 0
	global_load_dword v118, v105, s[14:15] nt
	s_add_u32 s14, s14, s1
	s_addc_u32 s15, s15, 0
	global_load_dword v119, v105, s[14:15] nt
	s_add_u32 s14, s14, s1
	s_addc_u32 s15, s15, 0
	global_load_dword v120, v105, s[14:15] nt
	s_add_u32 s14, s14, s1
	s_addc_u32 s15, s15, 0
	global_load_dword v121, v105, s[14:15] nt
	s_add_u32 s14, s14, s1
	s_addc_u32 s15, s15, 0
	global_load_dword v122, v105, s[14:15] nt
	s_add_u32 s14, s14, s1
	s_addc_u32 s15, s15, 0
	global_load_dword v123, v105, s[14:15] nt
	s_add_u32 s14, s14, s1
	s_addc_u32 s15, s15, 0
	global_load_dword v124, v105, s[14:15] nt
	s_add_u32 s14, s14, s1
	s_addc_u32 s15, s15, 0
	global_load_dword v125, v105, s[14:15] nt
	s_add_u32 s14, s14, s1
	s_addc_u32 s15, s15, 0
	global_load_dword v126, v105, s[14:15] nt
	s_add_u32 s14, s14, s1
	s_addc_u32 s15, s15, 0
	global_load_dword v127, v105, s[14:15] nt
	s_add_u32 s14, s14, s1
	s_addc_u32 s15, s15, 0
	global_load_dword v128, v105, s[14:15] nt
	s_add_u32 s14, s14, s1
	s_addc_u32 s15, s15, 0
	global_load_dword v129, v105, s[14:15] nt
	s_add_u32 s14, s14, s1
	s_addc_u32 s15, s15, 0
	global_load_dword v130, v105, s[14:15] nt
	s_add_u32 s14, s14, s1
	s_addc_u32 s15, s15, 0
	global_load_dword v131, v105, s[14:15] nt
	s_add_u32 s14, s14, s1
	s_addc_u32 s15, s15, 0
	global_load_dword v132, v105, s[14:15] nt
	s_add_u32 s14, s14, s1
	s_addc_u32 s15, s15, 0
	global_load_dword v133, v105, s[14:15] nt
	s_add_u32 s14, s14, s1
	s_addc_u32 s15, s15, 0
	global_load_dword v134, v105, s[14:15] nt
	s_add_u32 s14, s14, s1
	s_addc_u32 s15, s15, 0
	global_load_dword v135, v105, s[14:15] nt
	s_add_u32 s14, s14, s1
	s_addc_u32 s15, s15, 0
	global_load_dword v136, v105, s[14:15] nt
	s_add_u32 s14, s14, s1
	s_addc_u32 s15, s15, 0
	global_load_dword v137, v105, s[14:15] nt
	s_add_u32 s14, s14, s1
	s_addc_u32 s15, s15, 0
	global_load_dword v138, v105, s[14:15] nt
	s_add_u32 s14, s14, s1
	s_addc_u32 s15, s15, 0
	global_load_dword v139, v105, s[14:15] nt
	s_add_u32 s14, s14, s1
	s_addc_u32 s15, s15, 0
	global_load_dword v140, v105, s[14:15] nt
	s_add_u32 s14, s14, s1
	s_addc_u32 s15, s15, 0
	global_load_dword v141, v105, s[14:15] nt
	s_cmpk_ge_u32 s43, 0xb00
	s_cselect_b32 s44, 1, 0
	s_mul_i32 s45, s44, 0xb00
	s_sub_i32 s45, s43, s45
	s_lshr_b32 s38, s45, 7
	s_lshl_b32 s38, s38, 8
	s_lshl_b32 s44, s44, 7
	s_and_b32 s45, s45, 0x7f
	s_add_i32 s38, s38, s44
	s_add_i32 s38, s38, s45
	s_cmp_eq_u32 s60, 0
	s_cselect_b32 s38, s43, s38
	s_mul_i32 s38, s38, s5
	s_add_i32 s38, s38, s42
	s_lshl_b32 s38, s38, 1
	s_add_u32 s40, s10, s38
	s_addc_u32 s41, s11, 0
	v_mul_u32_u24_e32 v108, s5, v104
	v_lshl_add_u32 v108, v103, 3, v108
	v_lshlrev_b32_e32 v108, 1, v108
	s_lshl_b32 s39, s5, 4
	s_waitcnt vmcnt(31)
	ds_write_b32 v102, v110 offset:0
	s_waitcnt vmcnt(30)
	ds_write_b32 v102, v111 offset:264
	s_waitcnt vmcnt(29)
	ds_write_b32 v102, v112 offset:528
	s_waitcnt vmcnt(28)
	ds_write_b32 v102, v113 offset:792
	s_waitcnt vmcnt(27)
	ds_write_b32 v102, v114 offset:1056
	s_waitcnt vmcnt(26)
	ds_write_b32 v102, v115 offset:1320
	s_waitcnt vmcnt(25)
	ds_write_b32 v102, v116 offset:1584
	s_waitcnt vmcnt(24)
	ds_write_b32 v102, v117 offset:1848
	s_waitcnt vmcnt(23)
	ds_write_b32 v102, v118 offset:2112
	s_waitcnt vmcnt(22)
	ds_write_b32 v102, v119 offset:2376
	s_waitcnt vmcnt(21)
	ds_write_b32 v102, v120 offset:2640
	s_waitcnt vmcnt(20)
	ds_write_b32 v102, v121 offset:2904
	s_waitcnt vmcnt(19)
	ds_write_b32 v102, v122 offset:3168
	s_waitcnt vmcnt(18)
	ds_write_b32 v102, v123 offset:3432
	s_waitcnt vmcnt(17)
	ds_write_b32 v102, v124 offset:3696
	s_waitcnt vmcnt(16)
	ds_write_b32 v102, v125 offset:3960
	s_waitcnt vmcnt(15)
	ds_write_b32 v102, v126 offset:4224
	s_waitcnt vmcnt(14)
	ds_write_b32 v102, v127 offset:4488
	s_waitcnt vmcnt(13)
	ds_write_b32 v102, v128 offset:4752
	s_waitcnt vmcnt(12)
	ds_write_b32 v102, v129 offset:5016
	s_waitcnt vmcnt(11)
	ds_write_b32 v102, v130 offset:5280
	s_waitcnt vmcnt(10)
	ds_write_b32 v102, v131 offset:5544
	s_waitcnt vmcnt(9)
	ds_write_b32 v102, v132 offset:5808
	s_waitcnt vmcnt(8)
	ds_write_b32 v102, v133 offset:6072
	s_waitcnt vmcnt(7)
	ds_write_b32 v102, v134 offset:6336
	s_waitcnt vmcnt(6)
	ds_write_b32 v102, v135 offset:6600
	s_waitcnt vmcnt(5)
	ds_write_b32 v102, v136 offset:6864
	s_waitcnt vmcnt(4)
	ds_write_b32 v102, v137 offset:7128
	s_waitcnt vmcnt(3)
	ds_write_b32 v102, v138 offset:7392
	s_waitcnt vmcnt(2)
	ds_write_b32 v102, v139 offset:7656
	s_waitcnt vmcnt(1)
	ds_write_b32 v102, v140 offset:7920
	s_waitcnt vmcnt(0)
	ds_write_b32 v102, v141 offset:8184
	s_waitcnt lgkmcnt(0)
	ds_read2_b32 v[150:151], v106 offset0:0 offset1:33
	ds_read2_b32 v[152:153], v106 offset0:66 offset1:99
	ds_read2_b32 v[154:155], v106 offset0:132 offset1:165
	ds_read2_b32 v[156:157], v106 offset0:198 offset1:231
	s_waitcnt lgkmcnt(0)
	v_mul_f32_e32 v150, v150, v142
	v_mul_f32_e32 v151, v151, v143
	v_mul_f32_e32 v152, v152, v144
	v_mul_f32_e32 v153, v153, v145
	v_mul_f32_e32 v154, v154, v146
	v_mul_f32_e32 v155, v155, v147
	v_mul_f32_e32 v156, v156, v148
	v_mul_f32_e32 v157, v157, v149
	v_cvt_pk_bf16_f32 v160, v150, v151
	v_cvt_pk_bf16_f32 v161, v152, v153
	v_cvt_pk_bf16_f32 v162, v154, v155
	v_cvt_pk_bf16_f32 v163, v156, v157
	global_store_dwordx4 v108, v[160:163], s[40:41]
	s_add_u32 s40, s40, s39
	s_addc_u32 s41, s41, 0
	ds_read2_b32 v[150:151], v106 offset0:8 offset1:41
	ds_read2_b32 v[152:153], v106 offset0:74 offset1:107
	ds_read2_b32 v[154:155], v106 offset0:140 offset1:173
	ds_read2_b32 v[156:157], v106 offset0:206 offset1:239
	s_waitcnt lgkmcnt(0)
	v_mul_f32_e32 v150, v150, v142
	v_mul_f32_e32 v151, v151, v143
	v_mul_f32_e32 v152, v152, v144
	v_mul_f32_e32 v153, v153, v145
	v_mul_f32_e32 v154, v154, v146
	v_mul_f32_e32 v155, v155, v147
	v_mul_f32_e32 v156, v156, v148
	v_mul_f32_e32 v157, v157, v149
	v_cvt_pk_bf16_f32 v160, v150, v151
	v_cvt_pk_bf16_f32 v161, v152, v153
	v_cvt_pk_bf16_f32 v162, v154, v155
	v_cvt_pk_bf16_f32 v163, v156, v157
	global_store_dwordx4 v108, v[160:163], s[40:41]
	s_add_u32 s40, s40, s39
	s_addc_u32 s41, s41, 0
	ds_read2_b32 v[150:151], v106 offset0:16 offset1:49
	ds_read2_b32 v[152:153], v106 offset0:82 offset1:115
	ds_read2_b32 v[154:155], v106 offset0:148 offset1:181
	ds_read2_b32 v[156:157], v106 offset0:214 offset1:247
	s_waitcnt lgkmcnt(0)
	v_mul_f32_e32 v150, v150, v142
	v_mul_f32_e32 v151, v151, v143
	v_mul_f32_e32 v152, v152, v144
	v_mul_f32_e32 v153, v153, v145
	v_mul_f32_e32 v154, v154, v146
	v_mul_f32_e32 v155, v155, v147
	v_mul_f32_e32 v156, v156, v148
	v_mul_f32_e32 v157, v157, v149
	v_cvt_pk_bf16_f32 v160, v150, v151
	v_cvt_pk_bf16_f32 v161, v152, v153
	v_cvt_pk_bf16_f32 v162, v154, v155
	v_cvt_pk_bf16_f32 v163, v156, v157
	global_store_dwordx4 v108, v[160:163], s[40:41]
	s_add_u32 s40, s40, s39
	s_addc_u32 s41, s41, 0
	ds_read2_b32 v[150:151], v106 offset0:24 offset1:57
	ds_read2_b32 v[152:153], v106 offset0:90 offset1:123
	ds_read2_b32 v[154:155], v106 offset0:156 offset1:189
	ds_read2_b32 v[156:157], v106 offset0:222 offset1:255
	s_waitcnt lgkmcnt(0)
	v_mul_f32_e32 v150, v150, v142
	v_mul_f32_e32 v151, v151, v143
	v_mul_f32_e32 v152, v152, v144
	v_mul_f32_e32 v153, v153, v145
	v_mul_f32_e32 v154, v154, v146
	v_mul_f32_e32 v155, v155, v147
	v_mul_f32_e32 v156, v156, v148
	v_mul_f32_e32 v157, v157, v149
	v_cvt_pk_bf16_f32 v160, v150, v151
	v_cvt_pk_bf16_f32 v161, v152, v153
	v_cvt_pk_bf16_f32 v162, v154, v155
	v_cvt_pk_bf16_f32 v163, v156, v157
	global_store_dwordx4 v108, v[160:163], s[40:41]
	s_add_i32 s75, s75, s64
	s_cmpk_lt_i32 s75, 0x1780
	s_cbranch_scc1 .Lp0_item

.LBB0_533:
	s_add_i32 s97, s97, 1
	v_readlane_b32 s20, v244, 14
	v_readlane_b32 s21, v244, 15
	v_readlane_b32 s22, v244, 16
	v_readlane_b32 s23, v244, 17
	s_mul_i32 s16, s33, 0xfe
	v_and_b32_e32 v100, 15, v214
	s_add_i32 s16, s16, -1
	v_lshl_add_u32 v100, v100, 2, s3
	v_add_u32_e32 v100, s16, v100
	v_mov_b32_e32 v101, v100
	v_med3_i32 v101, v101, 0, v220
	v_lshlrev_b32_e32 v101, 2, v101
	v_add_u32_e32 v102, 1, v100
	v_med3_i32 v102, v102, 0, v220
	v_lshlrev_b32_e32 v102, 2, v102
	v_add_u32_e32 v103, 2, v100
	v_med3_i32 v103, v103, 0, v220
	v_lshlrev_b32_e32 v103, 2, v103
	v_add_u32_e32 v104, 3, v100
	v_med3_i32 v104, v104, 0, v220
	v_lshlrev_b32_e32 v104, 2, v104
	v_add_u32_e32 v105, 128, v100
	v_med3_i32 v105, v105, 0, v220
	v_lshlrev_b32_e32 v105, 2, v105
	v_add_u32_e32 v106, 129, v100
	v_med3_i32 v106, v106, 0, v220
	v_lshlrev_b32_e32 v106, 2, v106
	v_add_u32_e32 v107, 130, v100
	v_med3_i32 v107, v107, 0, v220
	v_lshlrev_b32_e32 v107, 2, v107
	v_add_u32_e32 v108, 131, v100
	v_med3_i32 v108, v108, 0, v220
	v_lshlrev_b32_e32 v108, 2, v108
	global_load_dword v248, v101, s[62:63]
	global_load_dword v249, v102, s[62:63]
	global_load_dword v250, v103, s[62:63]
	global_load_dword v251, v104, s[62:63]
	global_load_dword v252, v105, s[62:63]
	global_load_dword v253, v106, s[62:63]
	global_load_dword v254, v107, s[62:63]
	global_load_dword v255, v108, s[62:63]
	s_lshr_b32 s19, s3, 4
	s_lshr_b32 s16, s60, 5
	s_add_i32 s19, s19, s16
	s_add_i32 s17, s19, -6
	s_cmp_lt_u32 s19, 6
	s_cselect_b32 s20, s20, s22
	s_cselect_b32 s21, s21, s23
	s_cselect_b32 s16, s19, s17
	s_mul_i32 s16, s16, 0x2c00
	s_add_u32 s20, s20, s16
	s_addc_u32 s21, s21, 0
	v_and_b32_e32 v109, 63, v214
	s_lshl_b32 s16, s10, 9
	v_lshl_add_u32 v109, v109, 2, s16
	s_and_b32 s16, s97, 1
	s_lshl_b32 s16, s16, 12
	s_lshl_b32 s17, s19, 9
	s_add_i32 s16, s16, s17
	s_add_i32 m0, s16, 0x22400
	s_nop 0
	global_load_lds_dword v109, s[20:21]
	global_load_lds_dword v109, s[20:21] offset:256
	s_mul_i32 s6, s97, s83
	s_mul_hi_u32 s7, s97, s84
	s_add_i32 s7, s7, s6
	s_mul_i32 s6, s97, s84
	s_add_u32 s6, s6, s2
	s_addc_u32 s7, s7, s85
	v_cmp_gt_i64_e32 vcc, s[6:7], v[150:151]
	v_cmp_lt_i64_e64 s[8:9], s[6:7], v[148:149]
	s_cbranch_vccnz .LBB0_539
	s_ashr_i32 s7, s6, 31
	s_lshr_b32 s7, s7, 29
	s_add_i32 s11, s6, s7
	s_and_b32 s7, s11, -8
	s_sub_i32 s16, s6, s7
	s_cmp_gt_i32 s16, 3
	s_mov_b64 s[6:7], -1
	s_cbranch_scc0 .LBB0_536
	s_mul_i32 s6, s16, 0x215
	s_add_i32 s17, s6, 4
	s_mov_b64 s[6:7], 0

.LBB0_545:
	s_mul_i32 s28, s33, 0xfe
	s_add_i32 s8, s28, -1
	v_and_b32_e32 v223, 15, v214
	v_lshrrev_b32_e32 v225, 1, v214
	s_lshl_b32 s9, s3, 5
	v_and_or_b32 v225, v225, 24, s60
	s_add_i32 s9, s9, 0x20400
	v_lshl_or_b32 v226, s10, 7, v225
	v_lshl_add_u32 v227, v223, 2, s3
	v_lshl_add_u32 v229, v225, 2, s9
	v_add_u32_e32 v228, s8, v227
	v_lshlrev_b32_e32 v230, 1, v226
	v_mad_u32_u24 v230, v228, s61, v230
	s_and_b32 s11, s97, 1
	s_lshl_b32 s11, s11, 12
	s_add_i32 s11, s11, 0x22400
	v_lshl_add_u32 v226, v225, 2, s11
	ds_read_b128 v[176:179], v226 offset:0
	ds_read_b128 v[180:183], v226 offset:512
	ds_read_b128 v[184:187], v226 offset:1024
	ds_read_b128 v[188:191], v226 offset:1536
	ds_read_b128 v[192:195], v226 offset:2048
	ds_read_b128 v[196:199], v226 offset:2560
	ds_read_b128 v[200:203], v226 offset:3072
	ds_read_b128 v[204:207], v226 offset:3584
	s_lshr_b32 s11, s3, 6
	s_max_u32 s29, s11, 1
	s_lshl_b32 s29, s29, 11
	s_add_i32 s29, s29, 0x20000
	v_lshl_add_u32 v231, v225, 2, s29
	s_lshl_b32 s29, s11, 11
	s_add_i32 s29, s29, 0x21000
	v_lshl_add_u32 v232, v225, 2, s29
	s_addk_i32 s29, 0xfc00
	v_lshl_add_u32 v233, v225, 2, s29
	v_lshlrev_b32_e32 v234, 2, v225
	v_add_u32_e32 v234, 0x21c00, v234
	v_mov_b32_e32 v236, s94
	v_pk_mul_f32 v[48:49], v[48:49], v[248:249] op_sel_hi:[1,0]
	v_pk_mul_f32 v[50:51], v[50:51], v[248:249] op_sel_hi:[1,0]
	v_pk_mul_f32 v[24:25], v[24:25], v[248:249] op_sel_hi:[1,0]
	v_pk_mul_f32 v[26:27], v[26:27], v[248:249] op_sel_hi:[1,0]
	v_pk_mul_f32 v[52:53], v[52:53], v[248:249] op_sel_hi:[1,0]
	v_pk_mul_f32 v[54:55], v[54:55], v[248:249] op_sel_hi:[1,0]
	v_pk_mul_f32 v[28:29], v[28:29], v[248:249] op_sel_hi:[1,0]
	v_pk_mul_f32 v[30:31], v[30:31], v[248:249] op_sel_hi:[1,0]
	v_pk_mul_f32 v[124:125], v[124:125], v[248:249] op_sel:[0,1] op_sel_hi:[1,1]
	v_pk_mul_f32 v[126:127], v[126:127], v[248:249] op_sel:[0,1] op_sel_hi:[1,1]
	v_pk_mul_f32 v[120:121], v[120:121], v[248:249] op_sel:[0,1] op_sel_hi:[1,1]
	v_pk_mul_f32 v[122:123], v[122:123], v[248:249] op_sel:[0,1] op_sel_hi:[1,1]
	v_pk_mul_f32 v[116:117], v[116:117], v[248:249] op_sel:[0,1] op_sel_hi:[1,1]
	v_pk_mul_f32 v[118:119], v[118:119], v[248:249] op_sel:[0,1] op_sel_hi:[1,1]
	v_pk_mul_f32 v[108:109], v[108:109], v[248:249] op_sel:[0,1] op_sel_hi:[1,1]
	v_pk_mul_f32 v[110:111], v[110:111], v[248:249] op_sel:[0,1] op_sel_hi:[1,1]
	v_pk_mul_f32 v[112:113], v[112:113], v[250:251] op_sel_hi:[1,0]
	v_pk_mul_f32 v[114:115], v[114:115], v[250:251] op_sel_hi:[1,0]
	v_pk_mul_f32 v[104:105], v[104:105], v[250:251] op_sel_hi:[1,0]
	v_pk_mul_f32 v[106:107], v[106:107], v[250:251] op_sel_hi:[1,0]
	v_pk_mul_f32 v[100:101], v[100:101], v[250:251] op_sel_hi:[1,0]
	v_pk_mul_f32 v[102:103], v[102:103], v[250:251] op_sel_hi:[1,0]
	v_pk_mul_f32 v[96:97], v[96:97], v[250:251] op_sel_hi:[1,0]
	v_pk_mul_f32 v[98:99], v[98:99], v[250:251] op_sel_hi:[1,0]
	v_pk_mul_f32 v[60:61], v[60:61], v[250:251] op_sel:[0,1] op_sel_hi:[1,1]
	v_pk_mul_f32 v[62:63], v[62:63], v[250:251] op_sel:[0,1] op_sel_hi:[1,1]
	v_pk_mul_f32 v[16:17], v[16:17], v[250:251] op_sel:[0,1] op_sel_hi:[1,1]
	v_pk_mul_f32 v[18:19], v[18:19], v[250:251] op_sel:[0,1] op_sel_hi:[1,1]
	v_pk_mul_f32 v[44:45], v[44:45], v[250:251] op_sel:[0,1] op_sel_hi:[1,1]
	v_pk_mul_f32 v[46:47], v[46:47], v[250:251] op_sel:[0,1] op_sel_hi:[1,1]
	v_pk_mul_f32 v[20:21], v[20:21], v[250:251] op_sel:[0,1] op_sel_hi:[1,1]
	v_pk_mul_f32 v[22:23], v[22:23], v[250:251] op_sel:[0,1] op_sel_hi:[1,1]
	v_pk_mul_f32 v[12:13], v[12:13], v[252:253] op_sel_hi:[1,0]
	v_pk_mul_f32 v[14:15], v[14:15], v[252:253] op_sel_hi:[1,0]
	v_pk_mul_f32 v[8:9], v[8:9], v[252:253] op_sel_hi:[1,0]
	v_pk_mul_f32 v[10:11], v[10:11], v[252:253] op_sel_hi:[1,0]
	v_pk_mul_f32 v[40:41], v[40:41], v[252:253] op_sel_hi:[1,0]
	v_pk_mul_f32 v[42:43], v[42:43], v[252:253] op_sel_hi:[1,0]
	v_pk_mul_f32 v[36:37], v[36:37], v[252:253] op_sel_hi:[1,0]
	v_pk_mul_f32 v[38:39], v[38:39], v[252:253] op_sel_hi:[1,0]
	v_pk_mul_f32 v[92:93], v[92:93], v[252:253] op_sel:[0,1] op_sel_hi:[1,1]
	v_pk_mul_f32 v[94:95], v[94:95], v[252:253] op_sel:[0,1] op_sel_hi:[1,1]
	v_pk_mul_f32 v[88:89], v[88:89], v[252:253] op_sel:[0,1] op_sel_hi:[1,1]
	v_pk_mul_f32 v[90:91], v[90:91], v[252:253] op_sel:[0,1] op_sel_hi:[1,1]
	v_pk_mul_f32 v[84:85], v[84:85], v[252:253] op_sel:[0,1] op_sel_hi:[1,1]
	v_pk_mul_f32 v[86:87], v[86:87], v[252:253] op_sel:[0,1] op_sel_hi:[1,1]
	v_pk_mul_f32 v[76:77], v[76:77], v[252:253] op_sel:[0,1] op_sel_hi:[1,1]
	v_pk_mul_f32 v[78:79], v[78:79], v[252:253] op_sel:[0,1] op_sel_hi:[1,1]
	v_pk_mul_f32 v[80:81], v[80:81], v[254:255] op_sel_hi:[1,0]
	v_pk_mul_f32 v[82:83], v[82:83], v[254:255] op_sel_hi:[1,0]
	v_pk_mul_f32 v[72:73], v[72:73], v[254:255] op_sel_hi:[1,0]
	v_pk_mul_f32 v[74:75], v[74:75], v[254:255] op_sel_hi:[1,0]
	v_pk_mul_f32 v[68:69], v[68:69], v[254:255] op_sel_hi:[1,0]
	v_pk_mul_f32 v[70:71], v[70:71], v[254:255] op_sel_hi:[1,0]
	v_pk_mul_f32 v[64:65], v[64:65], v[254:255] op_sel_hi:[1,0]
	v_pk_mul_f32 v[66:67], v[66:67], v[254:255] op_sel_hi:[1,0]
	v_pk_mul_f32 v[4:5], v[4:5], v[254:255] op_sel:[0,1] op_sel_hi:[1,1]
	v_pk_mul_f32 v[6:7], v[6:7], v[254:255] op_sel:[0,1] op_sel_hi:[1,1]
	v_pk_mul_f32 v[0:1], v[0:1], v[254:255] op_sel:[0,1] op_sel_hi:[1,1]
	v_pk_mul_f32 v[2:3], v[2:3], v[254:255] op_sel:[0,1] op_sel_hi:[1,1]
	v_pk_mul_f32 v[32:33], v[32:33], v[254:255] op_sel:[0,1] op_sel_hi:[1,1]
	v_pk_mul_f32 v[34:35], v[34:35], v[254:255] op_sel:[0,1] op_sel_hi:[1,1]
	v_pk_mul_f32 v[128:129], v[128:129], v[254:255] op_sel:[0,1] op_sel_hi:[1,1]
	v_pk_mul_f32 v[130:131], v[130:131], v[254:255] op_sel:[0,1] op_sel_hi:[1,1]
	v_cmp_eq_u32_e32 vcc, 0, v223
	s_and_saveexec_b64 s[30:31], vcc
	ds_write_b128 v229, v[48:51] offset:0
	ds_write_b128 v229, v[24:27] offset:16
	ds_write_b128 v229, v[52:55] offset:512
	ds_write_b128 v229, v[28:31] offset:528
	ds_write_b128 v229, v[12:15] offset:4096
	ds_write_b128 v229, v[8:11] offset:4112
	ds_write_b128 v229, v[40:43] offset:4608
	ds_write_b128 v229, v[36:39] offset:4624
	s_mov_b64 exec, s[30:31]
	v_cmp_eq_u32_e32 vcc, 15, v223
	s_and_saveexec_b64 s[30:31], vcc
	ds_write_b128 v229, v[60:63] offset:1024
	ds_write_b128 v229, v[16:19] offset:1040
	ds_write_b128 v229, v[44:47] offset:1536
	ds_write_b128 v229, v[20:23] offset:1552
	ds_write_b128 v229, v[4:7] offset:5120
	ds_write_b128 v229, v[0:3] offset:5136
	ds_write_b128 v229, v[32:35] offset:5632
	ds_write_b128 v229, v[128:131] offset:5648
	s_mov_b64 exec, s[30:31]
	s_waitcnt lgkmcnt(0)
	s_barrier
	s_cmp_eq_u32 s33, 64
	s_cbranch_scc1 .Lp5_edge
	s_cmp_lt_i32 s33, 64
	s_cselect_b32 s9, 11, 14
	s_lshl_b32 s11, 1, s9
	s_add_i32 s11, s11, s28
	s_add_i32 s11, s11, -2
	s_ashr_i32 s11, s11, s9
	s_add_i32 s29, s28, 0xff
	s_ashr_i32 s29, s29, s9
	s_cmp_lt_i32 s29, s11
	s_cbranch_scc0 .Lp5_edge
	ds_read_b128 v[56:59], v231 offset:0
	ds_read_b128 v[132:135], v231 offset:512
	ds_read_b128 v[152:155], v233 offset:0
	ds_read_b128 v[156:159], v233 offset:512
	s_waitcnt lgkmcnt(0)
	v_mov_b32_dpp v56, v60 row_shr:1 row_mask:0xf bank_mask:0xf
	v_mov_b32_dpp v57, v61 row_shr:1 row_mask:0xf bank_mask:0xf
	v_mov_b32_dpp v58, v62 row_shr:1 row_mask:0xf bank_mask:0xf
	v_mov_b32_dpp v59, v63 row_shr:1 row_mask:0xf bank_mask:0xf
	v_mov_b32_dpp v132, v44 row_shr:1 row_mask:0xf bank_mask:0xf
	v_mov_b32_dpp v133, v45 row_shr:1 row_mask:0xf bank_mask:0xf
	v_mov_b32_dpp v134, v46 row_shr:1 row_mask:0xf bank_mask:0xf
	v_mov_b32_dpp v135, v47 row_shr:1 row_mask:0xf bank_mask:0xf
	v_mov_b32_dpp v152, v48 row_shl:1 row_mask:0xf bank_mask:0xf
	v_mov_b32_dpp v153, v49 row_shl:1 row_mask:0xf bank_mask:0xf
	v_mov_b32_dpp v154, v50 row_shl:1 row_mask:0xf bank_mask:0xf
	v_mov_b32_dpp v155, v51 row_shl:1 row_mask:0xf bank_mask:0xf
	v_mov_b32_dpp v156, v52 row_shl:1 row_mask:0xf bank_mask:0xf
	v_mov_b32_dpp v157, v53 row_shl:1 row_mask:0xf bank_mask:0xf
	v_mov_b32_dpp v158, v54 row_shl:1 row_mask:0xf bank_mask:0xf
	v_mov_b32_dpp v159, v55 row_shl:1 row_mask:0xf bank_mask:0xf
	v_pk_fma_f32 v[56:57], v[176:177], v[56:57], v[200:201]
	v_pk_fma_f32 v[58:59], v[178:179], v[58:59], v[202:203]
	v_pk_fma_f32 v[132:133], v[180:181], v[132:133], v[204:205]
	v_pk_fma_f32 v[134:135], v[182:183], v[134:135], v[206:207]
	v_pk_fma_f32 v[56:57], v[48:49], v[184:185], v[56:57]
	v_pk_fma_f32 v[58:59], v[50:51], v[186:187], v[58:59]
	v_pk_fma_f32 v[132:133], v[52:53], v[188:189], v[132:133]
	v_pk_fma_f32 v[134:135], v[54:55], v[190:191], v[134:135]
	v_pk_fma_f32 v[56:57], v[192:193], v[124:125], v[56:57]
	v_pk_fma_f32 v[58:59], v[194:195], v[126:127], v[58:59]
	v_pk_fma_f32 v[132:133], v[196:197], v[116:117], v[132:133]
	v_pk_fma_f32 v[134:135], v[198:199], v[118:119], v[134:135]
	v_and_b32_e32 v212, 0x7fffffff, v56
	v_and_b32_e32 v213, 0x7fffffff, v57
	v_and_b32_e32 v166, 0x7fffffff, v58
	v_and_b32_e32 v167, 0x7fffffff, v59
	v_pk_fma_f32 v[238:239], v[212:213], s[90:91], 1.0 op_sel_hi:[1,0,0]
	v_pk_fma_f32 v[168:169], v[166:167], s[90:91], 1.0 op_sel_hi:[1,0,0]
	v_pk_mul_f32 v[164:165], v[56:57], v[56:57]
	v_pk_mul_f32 v[172:173], v[58:59], v[58:59]
	v_rcp_f32_e32 v238, v238
	v_rcp_f32_e32 v239, v239
	v_rcp_f32_e32 v168, v168
	v_rcp_f32_e32 v169, v169
	v_pk_mul_f32 v[164:165], v[164:165], s[44:45] op_sel_hi:[1,0]
	v_pk_mul_f32 v[172:173], v[172:173], s[44:45] op_sel_hi:[1,0]
	v_pk_fma_f32 v[246:247], v[238:239], s[92:93], v[236:237] op_sel_hi:[1,0,0]
	v_pk_fma_f32 v[170:171], v[168:169], s[92:93], v[236:237] op_sel_hi:[1,0,0]
	v_exp_f32_e32 v164, v164
	v_exp_f32_e32 v165, v165
	v_exp_f32_e32 v172, v172
	v_exp_f32_e32 v173, v173
	v_pk_fma_f32 v[246:247], v[238:239], v[246:247], s[96:97] op_sel_hi:[1,1,0]
	v_pk_fma_f32 v[170:171], v[168:169], v[170:171], s[96:97] op_sel_hi:[1,1,0]
	v_pk_fma_f32 v[246:247], v[238:239], v[246:247], s[0:1] op_sel_hi:[1,1,0]
	v_pk_fma_f32 v[170:171], v[168:169], v[170:171], s[0:1] op_sel_hi:[1,1,0]
	v_pk_fma_f32 v[246:247], v[238:239], v[246:247], s[4:5] op_sel_hi:[1,1,0]
	v_pk_fma_f32 v[170:171], v[168:169], v[170:171], s[4:5] op_sel_hi:[1,1,0]
	v_pk_mul_f32 v[246:247], v[238:239], v[246:247]
	v_pk_mul_f32 v[170:171], v[168:169], v[170:171]
	v_max_f32_e32 v238, 0, v56
	v_max_f32_e32 v239, 0, v57
	v_max_f32_e32 v168, 0, v58
	v_max_f32_e32 v169, 0, v59
	v_pk_mul_f32 v[246:247], v[164:165], v[246:247]
	v_pk_mul_f32 v[170:171], v[172:173], v[170:171]
	v_pk_fma_f32 v[164:165], v[212:213], v[246:247], v[238:239] neg_lo:[1,0,0] neg_hi:[1,0,0]
	v_pk_fma_f32 v[172:173], v[166:167], v[170:171], v[168:169] neg_lo:[1,0,0] neg_hi:[1,0,0]
	v_pk_mul_f32 v[246:247], v[164:165], v[132:133]
	v_pk_mul_f32 v[170:171], v[172:173], v[134:135]
	v_cvt_pk_bf16_f32 v160, v246, v247
	v_cvt_pk_bf16_f32 v161, v170, v171
	v_pk_fma_f32 v[48:49], v[176:177], v[48:49], v[200:201]
	v_pk_fma_f32 v[50:51], v[178:179], v[50:51], v[202:203]
	v_pk_fma_f32 v[52:53], v[180:181], v[52:53], v[204:205]
	v_pk_fma_f32 v[54:55], v[182:183], v[54:55], v[206:207]
	v_pk_fma_f32 v[48:49], v[124:125], v[184:185], v[48:49]
	v_pk_fma_f32 v[50:51], v[126:127], v[186:187], v[50:51]
	v_pk_fma_f32 v[52:53], v[116:117], v[188:189], v[52:53]
	v_pk_fma_f32 v[54:55], v[118:119], v[190:191], v[54:55]
	v_pk_fma_f32 v[48:49], v[192:193], v[112:113], v[48:49]
	v_pk_fma_f32 v[50:51], v[194:195], v[114:115], v[50:51]
	v_pk_fma_f32 v[52:53], v[196:197], v[100:101], v[52:53]
	v_pk_fma_f32 v[54:55], v[198:199], v[102:103], v[54:55]
	v_and_b32_e32 v212, 0x7fffffff, v48
	v_and_b32_e32 v213, 0x7fffffff, v49
	v_and_b32_e32 v134, 0x7fffffff, v50
	v_and_b32_e32 v135, 0x7fffffff, v51
	v_pk_fma_f32 v[238:239], v[212:213], s[90:91], 1.0 op_sel_hi:[1,0,0]
	v_pk_fma_f32 v[164:165], v[134:135], s[90:91], 1.0 op_sel_hi:[1,0,0]
	v_pk_mul_f32 v[132:133], v[48:49], v[48:49]
	v_pk_mul_f32 v[168:169], v[50:51], v[50:51]
	v_rcp_f32_e32 v238, v238
	v_rcp_f32_e32 v239, v239
	v_rcp_f32_e32 v164, v164
	v_rcp_f32_e32 v165, v165
	v_pk_mul_f32 v[132:133], v[132:133], s[44:45] op_sel_hi:[1,0]
	v_pk_mul_f32 v[168:169], v[168:169], s[44:45] op_sel_hi:[1,0]
	v_pk_fma_f32 v[246:247], v[238:239], s[92:93], v[236:237] op_sel_hi:[1,0,0]
	v_pk_fma_f32 v[166:167], v[164:165], s[92:93], v[236:237] op_sel_hi:[1,0,0]
	v_exp_f32_e32 v132, v132
	v_exp_f32_e32 v133, v133
	v_exp_f32_e32 v168, v168
	v_exp_f32_e32 v169, v169
	v_pk_fma_f32 v[246:247], v[238:239], v[246:247], s[96:97] op_sel_hi:[1,1,0]
	v_pk_fma_f32 v[166:167], v[164:165], v[166:167], s[96:97] op_sel_hi:[1,1,0]
	v_pk_fma_f32 v[246:247], v[238:239], v[246:247], s[0:1] op_sel_hi:[1,1,0]
	v_pk_fma_f32 v[166:167], v[164:165], v[166:167], s[0:1] op_sel_hi:[1,1,0]
	v_pk_fma_f32 v[246:247], v[238:239], v[246:247], s[4:5] op_sel_hi:[1,1,0]
	v_pk_fma_f32 v[166:167], v[164:165], v[166:167], s[4:5] op_sel_hi:[1,1,0]
	v_pk_mul_f32 v[246:247], v[238:239], v[246:247]
	v_pk_mul_f32 v[166:167], v[164:165], v[166:167]
	v_max_f32_e32 v238, 0, v48
	v_max_f32_e32 v239, 0, v49
	v_max_f32_e32 v164, 0, v50
	v_max_f32_e32 v165, 0, v51
	v_pk_mul_f32 v[246:247], v[132:133], v[246:247]
	v_pk_mul_f32 v[166:167], v[168:169], v[166:167]
	v_pk_fma_f32 v[132:133], v[212:213], v[246:247], v[238:239] neg_lo:[1,0,0] neg_hi:[1,0,0]
	v_pk_fma_f32 v[168:169], v[134:135], v[166:167], v[164:165] neg_lo:[1,0,0] neg_hi:[1,0,0]
	v_pk_mul_f32 v[246:247], v[132:133], v[52:53]
	v_pk_mul_f32 v[166:167], v[168:169], v[54:55]
	v_cvt_pk_bf16_f32 v56, v246, v247
	v_cvt_pk_bf16_f32 v57, v166, v167
	v_pk_fma_f32 v[124:125], v[176:177], v[124:125], v[200:201]
	v_pk_fma_f32 v[126:127], v[178:179], v[126:127], v[202:203]
	v_pk_fma_f32 v[116:117], v[180:181], v[116:117], v[204:205]
	v_pk_fma_f32 v[118:119], v[182:183], v[118:119], v[206:207]
	v_pk_fma_f32 v[124:125], v[112:113], v[184:185], v[124:125]
	v_pk_fma_f32 v[126:127], v[114:115], v[186:187], v[126:127]
	v_pk_fma_f32 v[116:117], v[100:101], v[188:189], v[116:117]
	v_pk_fma_f32 v[118:119], v[102:103], v[190:191], v[118:119]
	v_pk_fma_f32 v[124:125], v[192:193], v[60:61], v[124:125]
	v_pk_fma_f32 v[126:127], v[194:195], v[62:63], v[126:127]
	v_pk_fma_f32 v[116:117], v[196:197], v[44:45], v[116:117]
	v_pk_fma_f32 v[118:119], v[198:199], v[46:47], v[118:119]
	v_and_b32_e32 v212, 0x7fffffff, v124
	v_and_b32_e32 v213, 0x7fffffff, v125
	v_and_b32_e32 v54, 0x7fffffff, v126
	v_and_b32_e32 v55, 0x7fffffff, v127
	v_pk_fma_f32 v[238:239], v[212:213], s[90:91], 1.0 op_sel_hi:[1,0,0]
	v_pk_fma_f32 v[132:133], v[54:55], s[90:91], 1.0 op_sel_hi:[1,0,0]
	v_pk_mul_f32 v[52:53], v[124:125], v[124:125]
	v_pk_mul_f32 v[164:165], v[126:127], v[126:127]
	v_rcp_f32_e32 v238, v238
	v_rcp_f32_e32 v239, v239
	v_rcp_f32_e32 v132, v132
	v_rcp_f32_e32 v133, v133
	v_pk_mul_f32 v[52:53], v[52:53], s[44:45] op_sel_hi:[1,0]
	v_pk_mul_f32 v[164:165], v[164:165], s[44:45] op_sel_hi:[1,0]
	v_pk_fma_f32 v[246:247], v[238:239], s[92:93], v[236:237] op_sel_hi:[1,0,0]
	v_pk_fma_f32 v[134:135], v[132:133], s[92:93], v[236:237] op_sel_hi:[1,0,0]
	v_exp_f32_e32 v52, v52
	v_exp_f32_e32 v53, v53
	v_exp_f32_e32 v164, v164
	v_exp_f32_e32 v165, v165
	v_pk_fma_f32 v[246:247], v[238:239], v[246:247], s[96:97] op_sel_hi:[1,1,0]
	v_pk_fma_f32 v[134:135], v[132:133], v[134:135], s[96:97] op_sel_hi:[1,1,0]
	v_pk_fma_f32 v[246:247], v[238:239], v[246:247], s[0:1] op_sel_hi:[1,1,0]
	v_pk_fma_f32 v[134:135], v[132:133], v[134:135], s[0:1] op_sel_hi:[1,1,0]
	v_pk_fma_f32 v[246:247], v[238:239], v[246:247], s[4:5] op_sel_hi:[1,1,0]
	v_pk_fma_f32 v[134:135], v[132:133], v[134:135], s[4:5] op_sel_hi:[1,1,0]
	v_pk_mul_f32 v[246:247], v[238:239], v[246:247]
	v_pk_mul_f32 v[134:135], v[132:133], v[134:135]
	v_max_f32_e32 v238, 0, v124
	v_max_f32_e32 v239, 0, v125
	v_max_f32_e32 v132, 0, v126
	v_max_f32_e32 v133, 0, v127
	v_pk_mul_f32 v[246:247], v[52:53], v[246:247]
	v_pk_mul_f32 v[134:135], v[164:165], v[134:135]
	v_pk_fma_f32 v[52:53], v[212:213], v[246:247], v[238:239] neg_lo:[1,0,0] neg_hi:[1,0,0]
	v_pk_fma_f32 v[164:165], v[54:55], v[134:135], v[132:133] neg_lo:[1,0,0] neg_hi:[1,0,0]
	v_pk_mul_f32 v[246:247], v[52:53], v[116:117]
	v_pk_mul_f32 v[134:135], v[164:165], v[118:119]
	v_cvt_pk_bf16_f32 v48, v246, v247
	v_cvt_pk_bf16_f32 v49, v134, v135
	v_pk_fma_f32 v[112:113], v[176:177], v[112:113], v[200:201]
	v_pk_fma_f32 v[114:115], v[178:179], v[114:115], v[202:203]
	v_pk_fma_f32 v[100:101], v[180:181], v[100:101], v[204:205]
	v_pk_fma_f32 v[102:103], v[182:183], v[102:103], v[206:207]
	v_pk_fma_f32 v[112:113], v[60:61], v[184:185], v[112:113]
	v_pk_fma_f32 v[114:115], v[62:63], v[186:187], v[114:115]
	v_pk_fma_f32 v[100:101], v[44:45], v[188:189], v[100:101]
	v_pk_fma_f32 v[102:103], v[46:47], v[190:191], v[102:103]
	v_pk_fma_f32 v[112:113], v[192:193], v[152:153], v[112:113]
	v_pk_fma_f32 v[114:115], v[194:195], v[154:155], v[114:115]
	v_pk_fma_f32 v[100:101], v[196:197], v[156:157], v[100:101]
	v_pk_fma_f32 v[102:103], v[198:199], v[158:159], v[102:103]
	v_and_b32_e32 v212, 0x7fffffff, v112
	v_and_b32_e32 v213, 0x7fffffff, v113
	v_and_b32_e32 v118, 0x7fffffff, v114
	v_and_b32_e32 v119, 0x7fffffff, v115
	v_pk_fma_f32 v[238:239], v[212:213], s[90:91], 1.0 op_sel_hi:[1,0,0]
	v_pk_fma_f32 v[124:125], v[118:119], s[90:91], 1.0 op_sel_hi:[1,0,0]
	v_pk_mul_f32 v[116:117], v[112:113], v[112:113]
	v_pk_mul_f32 v[132:133], v[114:115], v[114:115]
	v_rcp_f32_e32 v238, v238
	v_rcp_f32_e32 v239, v239
	v_rcp_f32_e32 v124, v124
	v_rcp_f32_e32 v125, v125
	v_pk_mul_f32 v[116:117], v[116:117], s[44:45] op_sel_hi:[1,0]
	v_pk_mul_f32 v[132:133], v[132:133], s[44:45] op_sel_hi:[1,0]
	v_pk_fma_f32 v[246:247], v[238:239], s[92:93], v[236:237] op_sel_hi:[1,0,0]
	v_pk_fma_f32 v[126:127], v[124:125], s[92:93], v[236:237] op_sel_hi:[1,0,0]
	v_exp_f32_e32 v116, v116
	v_exp_f32_e32 v117, v117
	v_exp_f32_e32 v132, v132
	v_exp_f32_e32 v133, v133
	v_pk_fma_f32 v[246:247], v[238:239], v[246:247], s[96:97] op_sel_hi:[1,1,0]
	v_pk_fma_f32 v[126:127], v[124:125], v[126:127], s[96:97] op_sel_hi:[1,1,0]
	v_pk_fma_f32 v[246:247], v[238:239], v[246:247], s[0:1] op_sel_hi:[1,1,0]
	v_pk_fma_f32 v[126:127], v[124:125], v[126:127], s[0:1] op_sel_hi:[1,1,0]
	v_pk_fma_f32 v[246:247], v[238:239], v[246:247], s[4:5] op_sel_hi:[1,1,0]
	v_pk_fma_f32 v[126:127], v[124:125], v[126:127], s[4:5] op_sel_hi:[1,1,0]
	v_pk_mul_f32 v[246:247], v[238:239], v[246:247]
	v_pk_mul_f32 v[126:127], v[124:125], v[126:127]
	v_max_f32_e32 v238, 0, v112
	v_max_f32_e32 v239, 0, v113
	v_max_f32_e32 v124, 0, v114
	v_max_f32_e32 v125, 0, v115
	v_pk_mul_f32 v[246:247], v[116:117], v[246:247]
	v_pk_mul_f32 v[126:127], v[132:133], v[126:127]
	v_pk_fma_f32 v[116:117], v[212:213], v[246:247], v[238:239] neg_lo:[1,0,0] neg_hi:[1,0,0]
	v_pk_fma_f32 v[132:133], v[118:119], v[126:127], v[124:125] neg_lo:[1,0,0] neg_hi:[1,0,0]
	v_pk_mul_f32 v[246:247], v[116:117], v[100:101]
	v_pk_mul_f32 v[126:127], v[132:133], v[102:103]
	v_cvt_pk_bf16_f32 v52, v246, v247
	v_cvt_pk_bf16_f32 v53, v126, v127
	ds_read_b128 v[44:47], v232 offset:0
	ds_read_b128 v[60:63], v232 offset:512
	ds_read_b128 v[100:103], v234 offset:0
	ds_read_b128 v[112:115], v234 offset:512
	s_waitcnt lgkmcnt(0)
	v_mov_b32_dpp v44, v4 row_shr:1 row_mask:0xf bank_mask:0xf
	v_mov_b32_dpp v45, v5 row_shr:1 row_mask:0xf bank_mask:0xf
	v_mov_b32_dpp v46, v6 row_shr:1 row_mask:0xf bank_mask:0xf
	v_mov_b32_dpp v47, v7 row_shr:1 row_mask:0xf bank_mask:0xf
	v_mov_b32_dpp v60, v32 row_shr:1 row_mask:0xf bank_mask:0xf
	v_mov_b32_dpp v61, v33 row_shr:1 row_mask:0xf bank_mask:0xf
	v_mov_b32_dpp v62, v34 row_shr:1 row_mask:0xf bank_mask:0xf
	v_mov_b32_dpp v63, v35 row_shr:1 row_mask:0xf bank_mask:0xf
	v_mov_b32_dpp v100, v12 row_shl:1 row_mask:0xf bank_mask:0xf
	v_mov_b32_dpp v101, v13 row_shl:1 row_mask:0xf bank_mask:0xf
	v_mov_b32_dpp v102, v14 row_shl:1 row_mask:0xf bank_mask:0xf
	v_mov_b32_dpp v103, v15 row_shl:1 row_mask:0xf bank_mask:0xf
	v_mov_b32_dpp v112, v40 row_shl:1 row_mask:0xf bank_mask:0xf
	v_mov_b32_dpp v113, v41 row_shl:1 row_mask:0xf bank_mask:0xf
	v_mov_b32_dpp v114, v42 row_shl:1 row_mask:0xf bank_mask:0xf
	v_mov_b32_dpp v115, v43 row_shl:1 row_mask:0xf bank_mask:0xf
	v_pk_fma_f32 v[44:45], v[176:177], v[44:45], v[200:201]
	v_pk_fma_f32 v[46:47], v[178:179], v[46:47], v[202:203]
	v_pk_fma_f32 v[60:61], v[180:181], v[60:61], v[204:205]
	v_pk_fma_f32 v[62:63], v[182:183], v[62:63], v[206:207]
	v_pk_fma_f32 v[44:45], v[12:13], v[184:185], v[44:45]
	v_pk_fma_f32 v[46:47], v[14:15], v[186:187], v[46:47]
	v_pk_fma_f32 v[60:61], v[40:41], v[188:189], v[60:61]
	v_pk_fma_f32 v[62:63], v[42:43], v[190:191], v[62:63]
	v_pk_fma_f32 v[44:45], v[192:193], v[92:93], v[44:45]
	v_pk_fma_f32 v[46:47], v[194:195], v[94:95], v[46:47]
	v_pk_fma_f32 v[60:61], v[196:197], v[84:85], v[60:61]
	v_pk_fma_f32 v[62:63], v[198:199], v[86:87], v[62:63]
	v_and_b32_e32 v212, 0x7fffffff, v44
	v_and_b32_e32 v213, 0x7fffffff, v45
	v_and_b32_e32 v126, 0x7fffffff, v46
	v_and_b32_e32 v127, 0x7fffffff, v47
	v_pk_fma_f32 v[238:239], v[212:213], s[90:91], 1.0 op_sel_hi:[1,0,0]
	v_pk_fma_f32 v[132:133], v[126:127], s[90:91], 1.0 op_sel_hi:[1,0,0]
	v_pk_mul_f32 v[124:125], v[44:45], v[44:45]
	v_pk_mul_f32 v[152:153], v[46:47], v[46:47]
	v_rcp_f32_e32 v238, v238
	v_rcp_f32_e32 v239, v239
	v_rcp_f32_e32 v132, v132
	v_rcp_f32_e32 v133, v133
	v_pk_mul_f32 v[124:125], v[124:125], s[44:45] op_sel_hi:[1,0]
	v_pk_mul_f32 v[152:153], v[152:153], s[44:45] op_sel_hi:[1,0]
	v_pk_fma_f32 v[246:247], v[238:239], s[92:93], v[236:237] op_sel_hi:[1,0,0]
	v_pk_fma_f32 v[134:135], v[132:133], s[92:93], v[236:237] op_sel_hi:[1,0,0]
	v_exp_f32_e32 v124, v124
	v_exp_f32_e32 v125, v125
	v_exp_f32_e32 v152, v152
	v_exp_f32_e32 v153, v153
	v_pk_fma_f32 v[246:247], v[238:239], v[246:247], s[96:97] op_sel_hi:[1,1,0]
	v_pk_fma_f32 v[134:135], v[132:133], v[134:135], s[96:97] op_sel_hi:[1,1,0]
	v_pk_fma_f32 v[246:247], v[238:239], v[246:247], s[0:1] op_sel_hi:[1,1,0]
	v_pk_fma_f32 v[134:135], v[132:133], v[134:135], s[0:1] op_sel_hi:[1,1,0]
	v_pk_fma_f32 v[246:247], v[238:239], v[246:247], s[4:5] op_sel_hi:[1,1,0]
	v_pk_fma_f32 v[134:135], v[132:133], v[134:135], s[4:5] op_sel_hi:[1,1,0]
	v_pk_mul_f32 v[246:247], v[238:239], v[246:247]
	v_pk_mul_f32 v[134:135], v[132:133], v[134:135]
	v_max_f32_e32 v238, 0, v44
	v_max_f32_e32 v239, 0, v45
	v_max_f32_e32 v132, 0, v46
	v_max_f32_e32 v133, 0, v47
	v_pk_mul_f32 v[246:247], v[124:125], v[246:247]
	v_pk_mul_f32 v[134:135], v[152:153], v[134:135]
	v_pk_fma_f32 v[124:125], v[212:213], v[246:247], v[238:239] neg_lo:[1,0,0] neg_hi:[1,0,0]
	v_pk_fma_f32 v[152:153], v[126:127], v[134:135], v[132:133] neg_lo:[1,0,0] neg_hi:[1,0,0]
	v_pk_mul_f32 v[246:247], v[124:125], v[60:61]
	v_pk_mul_f32 v[134:135], v[152:153], v[62:63]
	v_cvt_pk_bf16_f32 v116, v246, v247
	v_cvt_pk_bf16_f32 v117, v134, v135
	v_pk_fma_f32 v[12:13], v[176:177], v[12:13], v[200:201]
	v_pk_fma_f32 v[14:15], v[178:179], v[14:15], v[202:203]
	v_pk_fma_f32 v[40:41], v[180:181], v[40:41], v[204:205]
	v_pk_fma_f32 v[42:43], v[182:183], v[42:43], v[206:207]
	v_pk_fma_f32 v[12:13], v[92:93], v[184:185], v[12:13]
	v_pk_fma_f32 v[14:15], v[94:95], v[186:187], v[14:15]
	v_pk_fma_f32 v[40:41], v[84:85], v[188:189], v[40:41]
	v_pk_fma_f32 v[42:43], v[86:87], v[190:191], v[42:43]
	v_pk_fma_f32 v[12:13], v[192:193], v[80:81], v[12:13]
	v_pk_fma_f32 v[14:15], v[194:195], v[82:83], v[14:15]
	v_pk_fma_f32 v[40:41], v[196:197], v[68:69], v[40:41]
	v_pk_fma_f32 v[42:43], v[198:199], v[70:71], v[42:43]
	v_and_b32_e32 v212, 0x7fffffff, v12
	v_and_b32_e32 v213, 0x7fffffff, v13
	v_and_b32_e32 v62, 0x7fffffff, v14
	v_and_b32_e32 v63, 0x7fffffff, v15
	v_pk_fma_f32 v[238:239], v[212:213], s[90:91], 1.0 op_sel_hi:[1,0,0]
	v_pk_fma_f32 v[124:125], v[62:63], s[90:91], 1.0 op_sel_hi:[1,0,0]
	v_pk_mul_f32 v[60:61], v[12:13], v[12:13]
	v_pk_mul_f32 v[132:133], v[14:15], v[14:15]
	v_rcp_f32_e32 v238, v238
	v_rcp_f32_e32 v239, v239
	v_rcp_f32_e32 v124, v124
	v_rcp_f32_e32 v125, v125
	v_pk_mul_f32 v[60:61], v[60:61], s[44:45] op_sel_hi:[1,0]
	v_pk_mul_f32 v[132:133], v[132:133], s[44:45] op_sel_hi:[1,0]
	v_pk_fma_f32 v[246:247], v[238:239], s[92:93], v[236:237] op_sel_hi:[1,0,0]
	v_pk_fma_f32 v[126:127], v[124:125], s[92:93], v[236:237] op_sel_hi:[1,0,0]
	v_exp_f32_e32 v60, v60
	v_exp_f32_e32 v61, v61
	v_exp_f32_e32 v132, v132
	v_exp_f32_e32 v133, v133
	v_pk_fma_f32 v[246:247], v[238:239], v[246:247], s[96:97] op_sel_hi:[1,1,0]
	v_pk_fma_f32 v[126:127], v[124:125], v[126:127], s[96:97] op_sel_hi:[1,1,0]
	v_pk_fma_f32 v[246:247], v[238:239], v[246:247], s[0:1] op_sel_hi:[1,1,0]
	v_pk_fma_f32 v[126:127], v[124:125], v[126:127], s[0:1] op_sel_hi:[1,1,0]
	v_pk_fma_f32 v[246:247], v[238:239], v[246:247], s[4:5] op_sel_hi:[1,1,0]
	v_pk_fma_f32 v[126:127], v[124:125], v[126:127], s[4:5] op_sel_hi:[1,1,0]
	v_pk_mul_f32 v[246:247], v[238:239], v[246:247]
	v_pk_mul_f32 v[126:127], v[124:125], v[126:127]
	v_max_f32_e32 v238, 0, v12
	v_max_f32_e32 v239, 0, v13
	v_max_f32_e32 v124, 0, v14
	v_max_f32_e32 v125, 0, v15
	v_pk_mul_f32 v[246:247], v[60:61], v[246:247]
	v_pk_mul_f32 v[126:127], v[132:133], v[126:127]
	v_pk_fma_f32 v[60:61], v[212:213], v[246:247], v[238:239] neg_lo:[1,0,0] neg_hi:[1,0,0]
	v_pk_fma_f32 v[132:133], v[62:63], v[126:127], v[124:125] neg_lo:[1,0,0] neg_hi:[1,0,0]
	v_pk_mul_f32 v[246:247], v[60:61], v[40:41]
	v_pk_mul_f32 v[126:127], v[132:133], v[42:43]
	v_cvt_pk_bf16_f32 v44, v246, v247
	v_cvt_pk_bf16_f32 v45, v126, v127
	v_pk_fma_f32 v[92:93], v[176:177], v[92:93], v[200:201]
	v_pk_fma_f32 v[94:95], v[178:179], v[94:95], v[202:203]
	v_pk_fma_f32 v[84:85], v[180:181], v[84:85], v[204:205]
	v_pk_fma_f32 v[86:87], v[182:183], v[86:87], v[206:207]
	v_pk_fma_f32 v[92:93], v[80:81], v[184:185], v[92:93]
	v_pk_fma_f32 v[94:95], v[82:83], v[186:187], v[94:95]
	v_pk_fma_f32 v[84:85], v[68:69], v[188:189], v[84:85]
	v_pk_fma_f32 v[86:87], v[70:71], v[190:191], v[86:87]
	v_pk_fma_f32 v[92:93], v[192:193], v[4:5], v[92:93]
	v_pk_fma_f32 v[94:95], v[194:195], v[6:7], v[94:95]
	v_pk_fma_f32 v[84:85], v[196:197], v[32:33], v[84:85]
	v_pk_fma_f32 v[86:87], v[198:199], v[34:35], v[86:87]
	v_and_b32_e32 v212, 0x7fffffff, v92
	v_and_b32_e32 v213, 0x7fffffff, v93
	v_and_b32_e32 v42, 0x7fffffff, v94
	v_and_b32_e32 v43, 0x7fffffff, v95
	v_pk_fma_f32 v[238:239], v[212:213], s[90:91], 1.0 op_sel_hi:[1,0,0]
	v_pk_fma_f32 v[60:61], v[42:43], s[90:91], 1.0 op_sel_hi:[1,0,0]
	v_pk_mul_f32 v[40:41], v[92:93], v[92:93]
	v_pk_mul_f32 v[124:125], v[94:95], v[94:95]
	v_rcp_f32_e32 v238, v238
	v_rcp_f32_e32 v239, v239
	v_rcp_f32_e32 v60, v60
	v_rcp_f32_e32 v61, v61
	v_pk_mul_f32 v[40:41], v[40:41], s[44:45] op_sel_hi:[1,0]
	v_pk_mul_f32 v[124:125], v[124:125], s[44:45] op_sel_hi:[1,0]
	v_pk_fma_f32 v[246:247], v[238:239], s[92:93], v[236:237] op_sel_hi:[1,0,0]
	v_pk_fma_f32 v[62:63], v[60:61], s[92:93], v[236:237] op_sel_hi:[1,0,0]
	v_exp_f32_e32 v40, v40
	v_exp_f32_e32 v41, v41
	v_exp_f32_e32 v124, v124
	v_exp_f32_e32 v125, v125
	v_pk_fma_f32 v[246:247], v[238:239], v[246:247], s[96:97] op_sel_hi:[1,1,0]
	v_pk_fma_f32 v[62:63], v[60:61], v[62:63], s[96:97] op_sel_hi:[1,1,0]
	v_pk_fma_f32 v[246:247], v[238:239], v[246:247], s[0:1] op_sel_hi:[1,1,0]
	v_pk_fma_f32 v[62:63], v[60:61], v[62:63], s[0:1] op_sel_hi:[1,1,0]
	v_pk_fma_f32 v[246:247], v[238:239], v[246:247], s[4:5] op_sel_hi:[1,1,0]
	v_pk_fma_f32 v[62:63], v[60:61], v[62:63], s[4:5] op_sel_hi:[1,1,0]
	v_pk_mul_f32 v[246:247], v[238:239], v[246:247]
	v_pk_mul_f32 v[62:63], v[60:61], v[62:63]
	v_max_f32_e32 v238, 0, v92
	v_max_f32_e32 v239, 0, v93
	v_max_f32_e32 v60, 0, v94
	v_max_f32_e32 v61, 0, v95
	v_pk_mul_f32 v[246:247], v[40:41], v[246:247]
	v_pk_mul_f32 v[62:63], v[124:125], v[62:63]
	v_pk_fma_f32 v[40:41], v[212:213], v[246:247], v[238:239] neg_lo:[1,0,0] neg_hi:[1,0,0]
	v_pk_fma_f32 v[124:125], v[42:43], v[62:63], v[60:61] neg_lo:[1,0,0] neg_hi:[1,0,0]
	v_pk_mul_f32 v[246:247], v[40:41], v[84:85]
	v_pk_mul_f32 v[62:63], v[124:125], v[86:87]
	v_cvt_pk_bf16_f32 v12, v246, v247
	v_cvt_pk_bf16_f32 v13, v62, v63
	ds_read_b128 v[40:43], v226 offset:16
	ds_read_b128 v[60:63], v226 offset:528
	ds_read_b128 v[84:87], v226 offset:1040
	ds_read_b128 v[92:95], v226 offset:1552
	ds_read_b128 v[124:127], v226 offset:2064
	ds_read_b128 v[132:135], v226 offset:2576
	ds_read_b128 v[152:155], v226 offset:3088
	ds_read_b128 v[156:159], v226 offset:3600
	v_pk_fma_f32 v[80:81], v[176:177], v[80:81], v[200:201]
	v_pk_fma_f32 v[82:83], v[178:179], v[82:83], v[202:203]
	v_pk_fma_f32 v[68:69], v[180:181], v[68:69], v[204:205]
	v_pk_fma_f32 v[70:71], v[182:183], v[70:71], v[206:207]
	v_pk_fma_f32 v[80:81], v[4:5], v[184:185], v[80:81]
	v_pk_fma_f32 v[82:83], v[6:7], v[186:187], v[82:83]
	v_pk_fma_f32 v[68:69], v[32:33], v[188:189], v[68:69]
	v_pk_fma_f32 v[70:71], v[34:35], v[190:191], v[70:71]
	v_pk_fma_f32 v[80:81], v[192:193], v[100:101], v[80:81]
	v_pk_fma_f32 v[82:83], v[194:195], v[102:103], v[82:83]
	v_pk_fma_f32 v[68:69], v[196:197], v[112:113], v[68:69]
	v_pk_fma_f32 v[70:71], v[198:199], v[114:115], v[70:71]
	v_and_b32_e32 v212, 0x7fffffff, v80
	v_and_b32_e32 v213, 0x7fffffff, v81
	v_and_b32_e32 v170, 0x7fffffff, v82
	v_and_b32_e32 v171, 0x7fffffff, v83
	v_pk_fma_f32 v[238:239], v[212:213], s[90:91], 1.0 op_sel_hi:[1,0,0]
	v_pk_fma_f32 v[172:173], v[170:171], s[90:91], 1.0 op_sel_hi:[1,0,0]
	v_pk_mul_f32 v[168:169], v[80:81], v[80:81]
	v_pk_mul_f32 v[208:209], v[82:83], v[82:83]
	v_rcp_f32_e32 v238, v238
	v_rcp_f32_e32 v239, v239
	v_rcp_f32_e32 v172, v172
	v_rcp_f32_e32 v173, v173
	v_pk_mul_f32 v[168:169], v[168:169], s[44:45] op_sel_hi:[1,0]
	v_pk_mul_f32 v[208:209], v[208:209], s[44:45] op_sel_hi:[1,0]
	v_pk_fma_f32 v[246:247], v[238:239], s[92:93], v[236:237] op_sel_hi:[1,0,0]
	v_pk_fma_f32 v[174:175], v[172:173], s[92:93], v[236:237] op_sel_hi:[1,0,0]
	v_exp_f32_e32 v168, v168
	v_exp_f32_e32 v169, v169
	v_exp_f32_e32 v208, v208
	v_exp_f32_e32 v209, v209
	v_pk_fma_f32 v[246:247], v[238:239], v[246:247], s[96:97] op_sel_hi:[1,1,0]
	v_pk_fma_f32 v[174:175], v[172:173], v[174:175], s[96:97] op_sel_hi:[1,1,0]
	v_pk_fma_f32 v[246:247], v[238:239], v[246:247], s[0:1] op_sel_hi:[1,1,0]
	v_pk_fma_f32 v[174:175], v[172:173], v[174:175], s[0:1] op_sel_hi:[1,1,0]
	v_pk_fma_f32 v[246:247], v[238:239], v[246:247], s[4:5] op_sel_hi:[1,1,0]
	v_pk_fma_f32 v[174:175], v[172:173], v[174:175], s[4:5] op_sel_hi:[1,1,0]
	v_pk_mul_f32 v[246:247], v[238:239], v[246:247]
	v_pk_mul_f32 v[174:175], v[172:173], v[174:175]
	v_max_f32_e32 v238, 0, v80
	v_max_f32_e32 v239, 0, v81
	v_max_f32_e32 v172, 0, v82
	v_max_f32_e32 v173, 0, v83
	v_pk_mul_f32 v[246:247], v[168:169], v[246:247]
	v_pk_mul_f32 v[174:175], v[208:209], v[174:175]
	v_pk_fma_f32 v[168:169], v[212:213], v[246:247], v[238:239] neg_lo:[1,0,0] neg_hi:[1,0,0]
	v_pk_fma_f32 v[208:209], v[170:171], v[174:175], v[172:173] neg_lo:[1,0,0] neg_hi:[1,0,0]
	v_pk_mul_f32 v[246:247], v[168:169], v[68:69]
	v_pk_mul_f32 v[174:175], v[208:209], v[70:71]
	v_cvt_pk_bf16_f32 v164, v246, v247
	v_cvt_pk_bf16_f32 v165, v174, v175
	ds_read_b128 v[4:7], v231 offset:16
	ds_read_b128 v[32:35], v231 offset:528
	ds_read_b128 v[68:71], v233 offset:16
	ds_read_b128 v[80:83], v233 offset:528
	s_waitcnt lgkmcnt(0)
	v_mov_b32_dpp v4, v16 row_shr:1 row_mask:0xf bank_mask:0xf
	v_mov_b32_dpp v5, v17 row_shr:1 row_mask:0xf bank_mask:0xf
	v_mov_b32_dpp v6, v18 row_shr:1 row_mask:0xf bank_mask:0xf
	v_mov_b32_dpp v7, v19 row_shr:1 row_mask:0xf bank_mask:0xf
	v_mov_b32_dpp v32, v20 row_shr:1 row_mask:0xf bank_mask:0xf
	v_mov_b32_dpp v33, v21 row_shr:1 row_mask:0xf bank_mask:0xf
	v_mov_b32_dpp v34, v22 row_shr:1 row_mask:0xf bank_mask:0xf
	v_mov_b32_dpp v35, v23 row_shr:1 row_mask:0xf bank_mask:0xf
	v_mov_b32_dpp v68, v24 row_shl:1 row_mask:0xf bank_mask:0xf
	v_mov_b32_dpp v69, v25 row_shl:1 row_mask:0xf bank_mask:0xf
	v_mov_b32_dpp v70, v26 row_shl:1 row_mask:0xf bank_mask:0xf
	v_mov_b32_dpp v71, v27 row_shl:1 row_mask:0xf bank_mask:0xf
	v_mov_b32_dpp v80, v28 row_shl:1 row_mask:0xf bank_mask:0xf
	v_mov_b32_dpp v81, v29 row_shl:1 row_mask:0xf bank_mask:0xf
	v_mov_b32_dpp v82, v30 row_shl:1 row_mask:0xf bank_mask:0xf
	v_mov_b32_dpp v83, v31 row_shl:1 row_mask:0xf bank_mask:0xf
	v_pk_fma_f32 v[4:5], v[40:41], v[4:5], v[152:153]
	v_pk_fma_f32 v[6:7], v[42:43], v[6:7], v[154:155]
	v_pk_fma_f32 v[32:33], v[60:61], v[32:33], v[156:157]
	v_pk_fma_f32 v[34:35], v[62:63], v[34:35], v[158:159]
	v_pk_fma_f32 v[4:5], v[24:25], v[84:85], v[4:5]
	v_pk_fma_f32 v[6:7], v[26:27], v[86:87], v[6:7]
	v_pk_fma_f32 v[32:33], v[28:29], v[92:93], v[32:33]
	v_pk_fma_f32 v[34:35], v[30:31], v[94:95], v[34:35]
	v_pk_fma_f32 v[4:5], v[124:125], v[120:121], v[4:5]
	v_pk_fma_f32 v[6:7], v[126:127], v[122:123], v[6:7]
	v_pk_fma_f32 v[32:33], v[132:133], v[108:109], v[32:33]
	v_pk_fma_f32 v[34:35], v[134:135], v[110:111], v[34:35]
	v_and_b32_e32 v212, 0x7fffffff, v4
	v_and_b32_e32 v213, 0x7fffffff, v5
	v_and_b32_e32 v102, 0x7fffffff, v6
	v_and_b32_e32 v103, 0x7fffffff, v7
	v_pk_fma_f32 v[238:239], v[212:213], s[90:91], 1.0 op_sel_hi:[1,0,0]
	v_pk_fma_f32 v[112:113], v[102:103], s[90:91], 1.0 op_sel_hi:[1,0,0]
	v_pk_mul_f32 v[100:101], v[4:5], v[4:5]
	v_pk_mul_f32 v[168:169], v[6:7], v[6:7]
	v_rcp_f32_e32 v238, v238
	v_rcp_f32_e32 v239, v239
	v_rcp_f32_e32 v112, v112
	v_rcp_f32_e32 v113, v113
	v_pk_mul_f32 v[100:101], v[100:101], s[44:45] op_sel_hi:[1,0]
	v_pk_mul_f32 v[168:169], v[168:169], s[44:45] op_sel_hi:[1,0]
	v_pk_fma_f32 v[246:247], v[238:239], s[92:93], v[236:237] op_sel_hi:[1,0,0]
	v_pk_fma_f32 v[114:115], v[112:113], s[92:93], v[236:237] op_sel_hi:[1,0,0]
	v_exp_f32_e32 v100, v100
	v_exp_f32_e32 v101, v101
	v_exp_f32_e32 v168, v168
	v_exp_f32_e32 v169, v169
	v_pk_fma_f32 v[246:247], v[238:239], v[246:247], s[96:97] op_sel_hi:[1,1,0]
	v_pk_fma_f32 v[114:115], v[112:113], v[114:115], s[96:97] op_sel_hi:[1,1,0]
	v_pk_fma_f32 v[246:247], v[238:239], v[246:247], s[0:1] op_sel_hi:[1,1,0]
	v_pk_fma_f32 v[114:115], v[112:113], v[114:115], s[0:1] op_sel_hi:[1,1,0]
	v_pk_fma_f32 v[246:247], v[238:239], v[246:247], s[4:5] op_sel_hi:[1,1,0]
	v_pk_fma_f32 v[114:115], v[112:113], v[114:115], s[4:5] op_sel_hi:[1,1,0]
	v_pk_mul_f32 v[246:247], v[238:239], v[246:247]
	v_pk_mul_f32 v[114:115], v[112:113], v[114:115]
	v_max_f32_e32 v238, 0, v4
	v_max_f32_e32 v239, 0, v5
	v_max_f32_e32 v112, 0, v6
	v_max_f32_e32 v113, 0, v7
	v_pk_mul_f32 v[246:247], v[100:101], v[246:247]
	v_pk_mul_f32 v[114:115], v[168:169], v[114:115]
	v_pk_fma_f32 v[100:101], v[212:213], v[246:247], v[238:239] neg_lo:[1,0,0] neg_hi:[1,0,0]
	v_pk_fma_f32 v[168:169], v[102:103], v[114:115], v[112:113] neg_lo:[1,0,0] neg_hi:[1,0,0]
	v_pk_mul_f32 v[246:247], v[100:101], v[32:33]
	v_pk_mul_f32 v[114:115], v[168:169], v[34:35]
	v_cvt_pk_bf16_f32 v162, v246, v247
	v_cvt_pk_bf16_f32 v163, v114, v115
	v_add_u32_e32 v235, -1, v227
	v_mov_b32_e32 v245, v228
	v_cmp_gt_u32_e64 s[38:39], s64, v235
	v_cmp_gt_u32_e32 vcc, s88, v245
	v_mov_b32_e32 v235, v230
	s_and_b64 s[38:39], s[38:39], vcc
	s_and_saveexec_b64 s[30:31], s[38:39]
	global_store_dwordx4 v235, v[160:163], s[50:51]
	s_mov_b64 exec, s[30:31]
	s_nop 1
	v_pk_fma_f32 v[24:25], v[40:41], v[24:25], v[152:153]
	v_pk_fma_f32 v[26:27], v[42:43], v[26:27], v[154:155]
	v_pk_fma_f32 v[28:29], v[60:61], v[28:29], v[156:157]
	v_pk_fma_f32 v[30:31], v[62:63], v[30:31], v[158:159]
	v_pk_fma_f32 v[24:25], v[120:121], v[84:85], v[24:25]
	v_pk_fma_f32 v[26:27], v[122:123], v[86:87], v[26:27]
	v_pk_fma_f32 v[28:29], v[108:109], v[92:93], v[28:29]
	v_pk_fma_f32 v[30:31], v[110:111], v[94:95], v[30:31]
	v_pk_fma_f32 v[24:25], v[124:125], v[104:105], v[24:25]
	v_pk_fma_f32 v[26:27], v[126:127], v[106:107], v[26:27]
	v_pk_fma_f32 v[28:29], v[132:133], v[96:97], v[28:29]
	v_pk_fma_f32 v[30:31], v[134:135], v[98:99], v[30:31]
	v_and_b32_e32 v212, 0x7fffffff, v24
	v_and_b32_e32 v213, 0x7fffffff, v25
	v_and_b32_e32 v6, 0x7fffffff, v26
	v_and_b32_e32 v7, 0x7fffffff, v27
	v_pk_fma_f32 v[238:239], v[212:213], s[90:91], 1.0 op_sel_hi:[1,0,0]
	v_pk_fma_f32 v[32:33], v[6:7], s[90:91], 1.0 op_sel_hi:[1,0,0]
	v_pk_mul_f32 v[4:5], v[24:25], v[24:25]
	v_pk_mul_f32 v[100:101], v[26:27], v[26:27]
	v_rcp_f32_e32 v238, v238
	v_rcp_f32_e32 v239, v239
	v_rcp_f32_e32 v32, v32
	v_rcp_f32_e32 v33, v33
	v_pk_mul_f32 v[4:5], v[4:5], s[44:45] op_sel_hi:[1,0]
	v_pk_mul_f32 v[100:101], v[100:101], s[44:45] op_sel_hi:[1,0]
	v_pk_fma_f32 v[246:247], v[238:239], s[92:93], v[236:237] op_sel_hi:[1,0,0]
	v_pk_fma_f32 v[34:35], v[32:33], s[92:93], v[236:237] op_sel_hi:[1,0,0]
	v_exp_f32_e32 v4, v4
	v_exp_f32_e32 v5, v5
	v_exp_f32_e32 v100, v100
	v_exp_f32_e32 v101, v101
	v_pk_fma_f32 v[246:247], v[238:239], v[246:247], s[96:97] op_sel_hi:[1,1,0]
	v_pk_fma_f32 v[34:35], v[32:33], v[34:35], s[96:97] op_sel_hi:[1,1,0]
	v_pk_fma_f32 v[246:247], v[238:239], v[246:247], s[0:1] op_sel_hi:[1,1,0]
	v_pk_fma_f32 v[34:35], v[32:33], v[34:35], s[0:1] op_sel_hi:[1,1,0]
	v_pk_fma_f32 v[246:247], v[238:239], v[246:247], s[4:5] op_sel_hi:[1,1,0]
	v_pk_fma_f32 v[34:35], v[32:33], v[34:35], s[4:5] op_sel_hi:[1,1,0]
	v_pk_mul_f32 v[246:247], v[238:239], v[246:247]
	v_pk_mul_f32 v[34:35], v[32:33], v[34:35]
	v_max_f32_e32 v238, 0, v24
	v_max_f32_e32 v239, 0, v25
	v_max_f32_e32 v32, 0, v26
	v_max_f32_e32 v33, 0, v27
	v_pk_mul_f32 v[246:247], v[4:5], v[246:247]
	v_pk_mul_f32 v[34:35], v[100:101], v[34:35]
	v_pk_fma_f32 v[4:5], v[212:213], v[246:247], v[238:239] neg_lo:[1,0,0] neg_hi:[1,0,0]
	v_pk_fma_f32 v[100:101], v[6:7], v[34:35], v[32:33] neg_lo:[1,0,0] neg_hi:[1,0,0]
	v_pk_mul_f32 v[246:247], v[4:5], v[28:29]
	v_pk_mul_f32 v[34:35], v[100:101], v[30:31]
	v_cvt_pk_bf16_f32 v58, v246, v247
	v_cvt_pk_bf16_f32 v59, v34, v35
	v_add_u32_e32 v235, 0, v227
	v_add_u32_e32 v245, 1, v228
	v_cmp_gt_u32_e64 s[38:39], s64, v235
	v_cmp_gt_u32_e32 vcc, s88, v245
	v_add_u32_e32 v235, 5632, v230
	s_and_b64 s[38:39], s[38:39], vcc
	s_and_saveexec_b64 s[30:31], s[38:39]
	global_store_dwordx4 v235, v[56:59], s[50:51]
	s_mov_b64 exec, s[30:31]
	s_nop 1
	v_pk_fma_f32 v[120:121], v[40:41], v[120:121], v[152:153]
	v_pk_fma_f32 v[122:123], v[42:43], v[122:123], v[154:155]
	v_pk_fma_f32 v[108:109], v[60:61], v[108:109], v[156:157]
	v_pk_fma_f32 v[110:111], v[62:63], v[110:111], v[158:159]
	v_pk_fma_f32 v[120:121], v[104:105], v[84:85], v[120:121]
	v_pk_fma_f32 v[122:123], v[106:107], v[86:87], v[122:123]
	v_pk_fma_f32 v[108:109], v[96:97], v[92:93], v[108:109]
	v_pk_fma_f32 v[110:111], v[98:99], v[94:95], v[110:111]
	v_pk_fma_f32 v[120:121], v[124:125], v[16:17], v[120:121]
	v_pk_fma_f32 v[122:123], v[126:127], v[18:19], v[122:123]
	v_pk_fma_f32 v[108:109], v[132:133], v[20:21], v[108:109]
	v_pk_fma_f32 v[110:111], v[134:135], v[22:23], v[110:111]
	v_and_b32_e32 v212, 0x7fffffff, v120
	v_and_b32_e32 v213, 0x7fffffff, v121
	v_and_b32_e32 v6, 0x7fffffff, v122
	v_and_b32_e32 v7, 0x7fffffff, v123
	v_pk_fma_f32 v[238:239], v[212:213], s[90:91], 1.0 op_sel_hi:[1,0,0]
	v_pk_fma_f32 v[24:25], v[6:7], s[90:91], 1.0 op_sel_hi:[1,0,0]
	v_pk_mul_f32 v[4:5], v[120:121], v[120:121]
	v_pk_mul_f32 v[28:29], v[122:123], v[122:123]
	v_rcp_f32_e32 v238, v238
	v_rcp_f32_e32 v239, v239
	v_rcp_f32_e32 v24, v24
	v_rcp_f32_e32 v25, v25
	v_pk_mul_f32 v[4:5], v[4:5], s[44:45] op_sel_hi:[1,0]
	v_pk_mul_f32 v[28:29], v[28:29], s[44:45] op_sel_hi:[1,0]
	v_pk_fma_f32 v[246:247], v[238:239], s[92:93], v[236:237] op_sel_hi:[1,0,0]
	v_pk_fma_f32 v[26:27], v[24:25], s[92:93], v[236:237] op_sel_hi:[1,0,0]
	v_exp_f32_e32 v4, v4
	v_exp_f32_e32 v5, v5
	v_exp_f32_e32 v28, v28
	v_exp_f32_e32 v29, v29
	v_pk_fma_f32 v[246:247], v[238:239], v[246:247], s[96:97] op_sel_hi:[1,1,0]
	v_pk_fma_f32 v[26:27], v[24:25], v[26:27], s[96:97] op_sel_hi:[1,1,0]
	v_pk_fma_f32 v[246:247], v[238:239], v[246:247], s[0:1] op_sel_hi:[1,1,0]
	v_pk_fma_f32 v[26:27], v[24:25], v[26:27], s[0:1] op_sel_hi:[1,1,0]
	v_pk_fma_f32 v[246:247], v[238:239], v[246:247], s[4:5] op_sel_hi:[1,1,0]
	v_pk_fma_f32 v[26:27], v[24:25], v[26:27], s[4:5] op_sel_hi:[1,1,0]
	v_pk_mul_f32 v[246:247], v[238:239], v[246:247]
	v_pk_mul_f32 v[26:27], v[24:25], v[26:27]
	v_max_f32_e32 v238, 0, v120
	v_max_f32_e32 v239, 0, v121
	v_max_f32_e32 v24, 0, v122
	v_max_f32_e32 v25, 0, v123
	v_pk_mul_f32 v[246:247], v[4:5], v[246:247]
	v_pk_mul_f32 v[26:27], v[28:29], v[26:27]
	v_pk_fma_f32 v[4:5], v[212:213], v[246:247], v[238:239] neg_lo:[1,0,0] neg_hi:[1,0,0]
	v_pk_fma_f32 v[28:29], v[6:7], v[26:27], v[24:25] neg_lo:[1,0,0] neg_hi:[1,0,0]
	v_pk_mul_f32 v[246:247], v[4:5], v[108:109]
	v_pk_mul_f32 v[26:27], v[28:29], v[110:111]
	v_cvt_pk_bf16_f32 v50, v246, v247
	v_cvt_pk_bf16_f32 v51, v26, v27
	v_add_u32_e32 v235, 1, v227
	v_add_u32_e32 v245, 2, v228
	v_cmp_gt_u32_e64 s[38:39], s64, v235
	v_cmp_gt_u32_e32 vcc, s88, v245
	v_add_u32_e32 v235, 11264, v230
	s_and_b64 s[38:39], s[38:39], vcc
	s_and_saveexec_b64 s[30:31], s[38:39]
	global_store_dwordx4 v235, v[48:51], s[50:51]
	s_mov_b64 exec, s[30:31]
	s_nop 1
	v_pk_fma_f32 v[104:105], v[40:41], v[104:105], v[152:153]
	v_pk_fma_f32 v[106:107], v[42:43], v[106:107], v[154:155]
	v_pk_fma_f32 v[96:97], v[60:61], v[96:97], v[156:157]
	v_pk_fma_f32 v[98:99], v[62:63], v[98:99], v[158:159]
	v_pk_fma_f32 v[104:105], v[16:17], v[84:85], v[104:105]
	v_pk_fma_f32 v[106:107], v[18:19], v[86:87], v[106:107]
	v_pk_fma_f32 v[96:97], v[20:21], v[92:93], v[96:97]
	v_pk_fma_f32 v[98:99], v[22:23], v[94:95], v[98:99]
	v_pk_fma_f32 v[104:105], v[124:125], v[68:69], v[104:105]
	v_pk_fma_f32 v[106:107], v[126:127], v[70:71], v[106:107]
	v_pk_fma_f32 v[96:97], v[132:133], v[80:81], v[96:97]
	v_pk_fma_f32 v[98:99], v[134:135], v[82:83], v[98:99]
	v_and_b32_e32 v212, 0x7fffffff, v104
	v_and_b32_e32 v213, 0x7fffffff, v105
	v_and_b32_e32 v6, 0x7fffffff, v106
	v_and_b32_e32 v7, 0x7fffffff, v107
	v_pk_fma_f32 v[238:239], v[212:213], s[90:91], 1.0 op_sel_hi:[1,0,0]
	v_pk_fma_f32 v[24:25], v[6:7], s[90:91], 1.0 op_sel_hi:[1,0,0]
	v_pk_mul_f32 v[4:5], v[104:105], v[104:105]
	v_pk_mul_f32 v[28:29], v[106:107], v[106:107]
	v_rcp_f32_e32 v238, v238
	v_rcp_f32_e32 v239, v239
	v_rcp_f32_e32 v24, v24
	v_rcp_f32_e32 v25, v25
	v_pk_mul_f32 v[4:5], v[4:5], s[44:45] op_sel_hi:[1,0]
	v_pk_mul_f32 v[28:29], v[28:29], s[44:45] op_sel_hi:[1,0]
	v_pk_fma_f32 v[246:247], v[238:239], s[92:93], v[236:237] op_sel_hi:[1,0,0]
	v_pk_fma_f32 v[26:27], v[24:25], s[92:93], v[236:237] op_sel_hi:[1,0,0]
	v_exp_f32_e32 v4, v4
	v_exp_f32_e32 v5, v5
	v_exp_f32_e32 v28, v28
	v_exp_f32_e32 v29, v29
	v_pk_fma_f32 v[246:247], v[238:239], v[246:247], s[96:97] op_sel_hi:[1,1,0]
	v_pk_fma_f32 v[26:27], v[24:25], v[26:27], s[96:97] op_sel_hi:[1,1,0]
	v_pk_fma_f32 v[246:247], v[238:239], v[246:247], s[0:1] op_sel_hi:[1,1,0]
	v_pk_fma_f32 v[26:27], v[24:25], v[26:27], s[0:1] op_sel_hi:[1,1,0]
	v_pk_fma_f32 v[246:247], v[238:239], v[246:247], s[4:5] op_sel_hi:[1,1,0]
	v_pk_fma_f32 v[26:27], v[24:25], v[26:27], s[4:5] op_sel_hi:[1,1,0]
	v_pk_mul_f32 v[246:247], v[238:239], v[246:247]
	v_pk_mul_f32 v[26:27], v[24:25], v[26:27]
	v_max_f32_e32 v238, 0, v104
	v_max_f32_e32 v239, 0, v105
	v_max_f32_e32 v24, 0, v106
	v_max_f32_e32 v25, 0, v107
	v_pk_mul_f32 v[246:247], v[4:5], v[246:247]
	v_pk_mul_f32 v[26:27], v[28:29], v[26:27]
	v_pk_fma_f32 v[4:5], v[212:213], v[246:247], v[238:239] neg_lo:[1,0,0] neg_hi:[1,0,0]
	v_pk_fma_f32 v[28:29], v[6:7], v[26:27], v[24:25] neg_lo:[1,0,0] neg_hi:[1,0,0]
	v_pk_mul_f32 v[246:247], v[4:5], v[96:97]
	v_pk_mul_f32 v[26:27], v[28:29], v[98:99]
	v_cvt_pk_bf16_f32 v54, v246, v247
	v_cvt_pk_bf16_f32 v55, v26, v27
	v_add_u32_e32 v235, 2, v227
	v_add_u32_e32 v245, 3, v228
	v_cmp_gt_u32_e64 s[38:39], s64, v235
	v_cmp_gt_u32_e32 vcc, s88, v245
	v_add_u32_e32 v235, 16896, v230
	s_and_b64 s[38:39], s[38:39], vcc
	s_and_saveexec_b64 s[30:31], s[38:39]
	global_store_dwordx4 v235, v[52:55], s[50:51]
	s_mov_b64 exec, s[30:31]
	s_nop 1
	ds_read_b128 v[4:7], v232 offset:16
	ds_read_b128 v[16:19], v232 offset:528
	ds_read_b128 v[20:23], v234 offset:16
	ds_read_b128 v[24:27], v234 offset:528
	s_waitcnt lgkmcnt(0)
	v_mov_b32_dpp v4, v0 row_shr:1 row_mask:0xf bank_mask:0xf
	v_mov_b32_dpp v5, v1 row_shr:1 row_mask:0xf bank_mask:0xf
	v_mov_b32_dpp v6, v2 row_shr:1 row_mask:0xf bank_mask:0xf
	v_mov_b32_dpp v7, v3 row_shr:1 row_mask:0xf bank_mask:0xf
	v_mov_b32_dpp v16, v128 row_shr:1 row_mask:0xf bank_mask:0xf
	v_mov_b32_dpp v17, v129 row_shr:1 row_mask:0xf bank_mask:0xf
	v_mov_b32_dpp v18, v130 row_shr:1 row_mask:0xf bank_mask:0xf
	v_mov_b32_dpp v19, v131 row_shr:1 row_mask:0xf bank_mask:0xf
	v_mov_b32_dpp v20, v8 row_shl:1 row_mask:0xf bank_mask:0xf
	v_mov_b32_dpp v21, v9 row_shl:1 row_mask:0xf bank_mask:0xf
	v_mov_b32_dpp v22, v10 row_shl:1 row_mask:0xf bank_mask:0xf
	v_mov_b32_dpp v23, v11 row_shl:1 row_mask:0xf bank_mask:0xf
	v_mov_b32_dpp v24, v36 row_shl:1 row_mask:0xf bank_mask:0xf
	v_mov_b32_dpp v25, v37 row_shl:1 row_mask:0xf bank_mask:0xf
	v_mov_b32_dpp v26, v38 row_shl:1 row_mask:0xf bank_mask:0xf
	v_mov_b32_dpp v27, v39 row_shl:1 row_mask:0xf bank_mask:0xf
	v_pk_fma_f32 v[4:5], v[40:41], v[4:5], v[152:153]
	v_pk_fma_f32 v[6:7], v[42:43], v[6:7], v[154:155]
	v_pk_fma_f32 v[16:17], v[60:61], v[16:17], v[156:157]
	v_pk_fma_f32 v[18:19], v[62:63], v[18:19], v[158:159]
	v_pk_fma_f32 v[4:5], v[8:9], v[84:85], v[4:5]
	v_pk_fma_f32 v[6:7], v[10:11], v[86:87], v[6:7]
	v_pk_fma_f32 v[16:17], v[36:37], v[92:93], v[16:17]
	v_pk_fma_f32 v[18:19], v[38:39], v[94:95], v[18:19]
	v_pk_fma_f32 v[4:5], v[124:125], v[88:89], v[4:5]
	v_pk_fma_f32 v[6:7], v[126:127], v[90:91], v[6:7]
	v_pk_fma_f32 v[16:17], v[132:133], v[76:77], v[16:17]
	v_pk_fma_f32 v[18:19], v[134:135], v[78:79], v[18:19]
	v_and_b32_e32 v212, 0x7fffffff, v4
	v_and_b32_e32 v213, 0x7fffffff, v5
	v_and_b32_e32 v30, 0x7fffffff, v6
	v_and_b32_e32 v31, 0x7fffffff, v7
	v_pk_fma_f32 v[238:239], v[212:213], s[90:91], 1.0 op_sel_hi:[1,0,0]
	v_pk_fma_f32 v[32:33], v[30:31], s[90:91], 1.0 op_sel_hi:[1,0,0]
	v_pk_mul_f32 v[28:29], v[4:5], v[4:5]
	v_pk_mul_f32 v[48:49], v[6:7], v[6:7]
	v_rcp_f32_e32 v238, v238
	v_rcp_f32_e32 v239, v239
	v_rcp_f32_e32 v32, v32
	v_rcp_f32_e32 v33, v33
	v_pk_mul_f32 v[28:29], v[28:29], s[44:45] op_sel_hi:[1,0]
	v_pk_mul_f32 v[48:49], v[48:49], s[44:45] op_sel_hi:[1,0]
	v_pk_fma_f32 v[246:247], v[238:239], s[92:93], v[236:237] op_sel_hi:[1,0,0]
	v_pk_fma_f32 v[34:35], v[32:33], s[92:93], v[236:237] op_sel_hi:[1,0,0]
	v_exp_f32_e32 v28, v28
	v_exp_f32_e32 v29, v29
	v_exp_f32_e32 v48, v48
	v_exp_f32_e32 v49, v49
	v_pk_fma_f32 v[246:247], v[238:239], v[246:247], s[96:97] op_sel_hi:[1,1,0]
	v_pk_fma_f32 v[34:35], v[32:33], v[34:35], s[96:97] op_sel_hi:[1,1,0]
	v_pk_fma_f32 v[246:247], v[238:239], v[246:247], s[0:1] op_sel_hi:[1,1,0]
	v_pk_fma_f32 v[34:35], v[32:33], v[34:35], s[0:1] op_sel_hi:[1,1,0]
	v_pk_fma_f32 v[246:247], v[238:239], v[246:247], s[4:5] op_sel_hi:[1,1,0]
	v_pk_fma_f32 v[34:35], v[32:33], v[34:35], s[4:5] op_sel_hi:[1,1,0]
	v_pk_mul_f32 v[246:247], v[238:239], v[246:247]
	v_pk_mul_f32 v[34:35], v[32:33], v[34:35]
	v_max_f32_e32 v238, 0, v4
	v_max_f32_e32 v239, 0, v5
	v_max_f32_e32 v32, 0, v6
	v_max_f32_e32 v33, 0, v7
	v_pk_mul_f32 v[246:247], v[28:29], v[246:247]
	v_pk_mul_f32 v[34:35], v[48:49], v[34:35]
	v_pk_fma_f32 v[28:29], v[212:213], v[246:247], v[238:239] neg_lo:[1,0,0] neg_hi:[1,0,0]
	v_pk_fma_f32 v[48:49], v[30:31], v[34:35], v[32:33] neg_lo:[1,0,0] neg_hi:[1,0,0]
	v_pk_mul_f32 v[246:247], v[28:29], v[16:17]
	v_pk_mul_f32 v[34:35], v[48:49], v[18:19]
	v_cvt_pk_bf16_f32 v118, v246, v247
	v_cvt_pk_bf16_f32 v119, v34, v35
	v_add_u32_e32 v235, 127, v227
	v_add_u32_e32 v245, 128, v228
	v_cmp_gt_u32_e64 s[38:39], s64, v235
	v_cmp_gt_u32_e32 vcc, s88, v245
	v_add_u32_e32 v235, 720896, v230
	s_and_b64 s[38:39], s[38:39], vcc
	s_and_saveexec_b64 s[30:31], s[38:39]
	global_store_dwordx4 v235, v[116:119], s[50:51]
	s_mov_b64 exec, s[30:31]
	s_nop 1
	v_pk_fma_f32 v[8:9], v[40:41], v[8:9], v[152:153]
	v_pk_fma_f32 v[10:11], v[42:43], v[10:11], v[154:155]
	v_pk_fma_f32 v[36:37], v[60:61], v[36:37], v[156:157]
	v_pk_fma_f32 v[38:39], v[62:63], v[38:39], v[158:159]
	v_pk_fma_f32 v[8:9], v[88:89], v[84:85], v[8:9]
	v_pk_fma_f32 v[10:11], v[90:91], v[86:87], v[10:11]
	v_pk_fma_f32 v[36:37], v[76:77], v[92:93], v[36:37]
	v_pk_fma_f32 v[38:39], v[78:79], v[94:95], v[38:39]
	v_pk_fma_f32 v[8:9], v[124:125], v[72:73], v[8:9]
	v_pk_fma_f32 v[10:11], v[126:127], v[74:75], v[10:11]
	v_pk_fma_f32 v[36:37], v[132:133], v[64:65], v[36:37]
	v_pk_fma_f32 v[38:39], v[134:135], v[66:67], v[38:39]
	v_and_b32_e32 v212, 0x7fffffff, v8
	v_and_b32_e32 v213, 0x7fffffff, v9
	v_and_b32_e32 v6, 0x7fffffff, v10
	v_and_b32_e32 v7, 0x7fffffff, v11
	v_pk_fma_f32 v[238:239], v[212:213], s[90:91], 1.0 op_sel_hi:[1,0,0]
	v_pk_fma_f32 v[16:17], v[6:7], s[90:91], 1.0 op_sel_hi:[1,0,0]
	v_pk_mul_f32 v[4:5], v[8:9], v[8:9]
	v_pk_mul_f32 v[28:29], v[10:11], v[10:11]
	v_rcp_f32_e32 v238, v238
	v_rcp_f32_e32 v239, v239
	v_rcp_f32_e32 v16, v16
	v_rcp_f32_e32 v17, v17
	v_pk_mul_f32 v[4:5], v[4:5], s[44:45] op_sel_hi:[1,0]
	v_pk_mul_f32 v[28:29], v[28:29], s[44:45] op_sel_hi:[1,0]
	v_pk_fma_f32 v[246:247], v[238:239], s[92:93], v[236:237] op_sel_hi:[1,0,0]
	v_pk_fma_f32 v[18:19], v[16:17], s[92:93], v[236:237] op_sel_hi:[1,0,0]
	v_exp_f32_e32 v4, v4
	v_exp_f32_e32 v5, v5
	v_exp_f32_e32 v28, v28
	v_exp_f32_e32 v29, v29
	v_pk_fma_f32 v[246:247], v[238:239], v[246:247], s[96:97] op_sel_hi:[1,1,0]
	v_pk_fma_f32 v[18:19], v[16:17], v[18:19], s[96:97] op_sel_hi:[1,1,0]
	v_pk_fma_f32 v[246:247], v[238:239], v[246:247], s[0:1] op_sel_hi:[1,1,0]
	v_pk_fma_f32 v[18:19], v[16:17], v[18:19], s[0:1] op_sel_hi:[1,1,0]
	v_pk_fma_f32 v[246:247], v[238:239], v[246:247], s[4:5] op_sel_hi:[1,1,0]
	v_pk_fma_f32 v[18:19], v[16:17], v[18:19], s[4:5] op_sel_hi:[1,1,0]
	v_pk_mul_f32 v[246:247], v[238:239], v[246:247]
	v_pk_mul_f32 v[18:19], v[16:17], v[18:19]
	v_max_f32_e32 v238, 0, v8
	v_max_f32_e32 v239, 0, v9
	v_max_f32_e32 v16, 0, v10
	v_max_f32_e32 v17, 0, v11
	v_pk_mul_f32 v[246:247], v[4:5], v[246:247]
	v_pk_mul_f32 v[18:19], v[28:29], v[18:19]
	v_pk_fma_f32 v[4:5], v[212:213], v[246:247], v[238:239] neg_lo:[1,0,0] neg_hi:[1,0,0]
	v_pk_fma_f32 v[28:29], v[6:7], v[18:19], v[16:17] neg_lo:[1,0,0] neg_hi:[1,0,0]
	v_pk_mul_f32 v[246:247], v[4:5], v[36:37]
	v_pk_mul_f32 v[18:19], v[28:29], v[38:39]
	v_cvt_pk_bf16_f32 v46, v246, v247
	v_cvt_pk_bf16_f32 v47, v18, v19
	v_add_u32_e32 v235, 128, v227
	v_add_u32_e32 v245, 129, v228
	v_cmp_gt_u32_e64 s[38:39], s64, v235
	v_cmp_gt_u32_e32 vcc, s88, v245
	v_add_u32_e32 v235, 726528, v230
	s_and_b64 s[38:39], s[38:39], vcc
	s_and_saveexec_b64 s[30:31], s[38:39]
	global_store_dwordx4 v235, v[44:47], s[50:51]
	s_mov_b64 exec, s[30:31]
	s_nop 1
	v_pk_fma_f32 v[88:89], v[40:41], v[88:89], v[152:153]
	v_pk_fma_f32 v[90:91], v[42:43], v[90:91], v[154:155]
	v_pk_fma_f32 v[76:77], v[60:61], v[76:77], v[156:157]
	v_pk_fma_f32 v[78:79], v[62:63], v[78:79], v[158:159]
	v_pk_fma_f32 v[88:89], v[72:73], v[84:85], v[88:89]
	v_pk_fma_f32 v[90:91], v[74:75], v[86:87], v[90:91]
	v_pk_fma_f32 v[76:77], v[64:65], v[92:93], v[76:77]
	v_pk_fma_f32 v[78:79], v[66:67], v[94:95], v[78:79]
	v_pk_fma_f32 v[88:89], v[124:125], v[0:1], v[88:89]
	v_pk_fma_f32 v[90:91], v[126:127], v[2:3], v[90:91]
	v_pk_fma_f32 v[76:77], v[132:133], v[128:129], v[76:77]
	v_pk_fma_f32 v[78:79], v[134:135], v[130:131], v[78:79]
	v_and_b32_e32 v212, 0x7fffffff, v88
	v_and_b32_e32 v213, 0x7fffffff, v89
	v_and_b32_e32 v6, 0x7fffffff, v90
	v_and_b32_e32 v7, 0x7fffffff, v91
	v_pk_fma_f32 v[238:239], v[212:213], s[90:91], 1.0 op_sel_hi:[1,0,0]
	v_pk_fma_f32 v[8:9], v[6:7], s[90:91], 1.0 op_sel_hi:[1,0,0]
	v_pk_mul_f32 v[4:5], v[88:89], v[88:89]
	v_pk_mul_f32 v[16:17], v[90:91], v[90:91]
	v_rcp_f32_e32 v238, v238
	v_rcp_f32_e32 v239, v239
	v_rcp_f32_e32 v8, v8
	v_rcp_f32_e32 v9, v9
	v_pk_mul_f32 v[4:5], v[4:5], s[44:45] op_sel_hi:[1,0]
	v_pk_mul_f32 v[16:17], v[16:17], s[44:45] op_sel_hi:[1,0]
	v_pk_fma_f32 v[246:247], v[238:239], s[92:93], v[236:237] op_sel_hi:[1,0,0]
	v_pk_fma_f32 v[10:11], v[8:9], s[92:93], v[236:237] op_sel_hi:[1,0,0]
	v_exp_f32_e32 v4, v4
	v_exp_f32_e32 v5, v5
	v_exp_f32_e32 v16, v16
	v_exp_f32_e32 v17, v17
	v_pk_fma_f32 v[246:247], v[238:239], v[246:247], s[96:97] op_sel_hi:[1,1,0]
	v_pk_fma_f32 v[10:11], v[8:9], v[10:11], s[96:97] op_sel_hi:[1,1,0]
	v_pk_fma_f32 v[246:247], v[238:239], v[246:247], s[0:1] op_sel_hi:[1,1,0]
	v_pk_fma_f32 v[10:11], v[8:9], v[10:11], s[0:1] op_sel_hi:[1,1,0]
	v_pk_fma_f32 v[246:247], v[238:239], v[246:247], s[4:5] op_sel_hi:[1,1,0]
	v_pk_fma_f32 v[10:11], v[8:9], v[10:11], s[4:5] op_sel_hi:[1,1,0]
	v_pk_mul_f32 v[246:247], v[238:239], v[246:247]
	v_pk_mul_f32 v[10:11], v[8:9], v[10:11]
	v_max_f32_e32 v238, 0, v88
	v_max_f32_e32 v239, 0, v89
	v_max_f32_e32 v8, 0, v90
	v_max_f32_e32 v9, 0, v91
	v_pk_mul_f32 v[246:247], v[4:5], v[246:247]
	v_pk_mul_f32 v[10:11], v[16:17], v[10:11]
	v_pk_fma_f32 v[4:5], v[212:213], v[246:247], v[238:239] neg_lo:[1,0,0] neg_hi:[1,0,0]
	v_pk_fma_f32 v[16:17], v[6:7], v[10:11], v[8:9] neg_lo:[1,0,0] neg_hi:[1,0,0]
	v_pk_mul_f32 v[246:247], v[4:5], v[76:77]
	v_pk_mul_f32 v[10:11], v[16:17], v[78:79]
	v_cvt_pk_bf16_f32 v14, v246, v247
	v_cvt_pk_bf16_f32 v15, v10, v11
	v_add_u32_e32 v235, 129, v227
	v_add_u32_e32 v245, 130, v228
	v_cmp_gt_u32_e64 s[38:39], s64, v235
	v_cmp_gt_u32_e32 vcc, s88, v245
	v_add_u32_e32 v235, 732160, v230
	s_and_b64 s[38:39], s[38:39], vcc
	s_and_saveexec_b64 s[30:31], s[38:39]
	global_store_dwordx4 v235, v[12:15], s[50:51]
	s_mov_b64 exec, s[30:31]
	s_nop 1
	v_pk_fma_f32 v[72:73], v[40:41], v[72:73], v[152:153]
	v_pk_fma_f32 v[74:75], v[42:43], v[74:75], v[154:155]
	v_pk_fma_f32 v[64:65], v[60:61], v[64:65], v[156:157]
	v_pk_fma_f32 v[66:67], v[62:63], v[66:67], v[158:159]
	v_pk_fma_f32 v[72:73], v[0:1], v[84:85], v[72:73]
	v_pk_fma_f32 v[74:75], v[2:3], v[86:87], v[74:75]
	v_pk_fma_f32 v[64:65], v[128:129], v[92:93], v[64:65]
	v_pk_fma_f32 v[66:67], v[130:131], v[94:95], v[66:67]
	v_pk_fma_f32 v[72:73], v[124:125], v[20:21], v[72:73]
	v_pk_fma_f32 v[74:75], v[126:127], v[22:23], v[74:75]
	v_pk_fma_f32 v[64:65], v[132:133], v[24:25], v[64:65]
	v_pk_fma_f32 v[66:67], v[134:135], v[26:27], v[66:67]
	v_and_b32_e32 v212, 0x7fffffff, v72
	v_and_b32_e32 v213, 0x7fffffff, v73
	v_and_b32_e32 v6, 0x7fffffff, v74
	v_and_b32_e32 v7, 0x7fffffff, v75
	v_pk_fma_f32 v[238:239], v[212:213], s[90:91], 1.0 op_sel_hi:[1,0,0]
	v_pk_fma_f32 v[8:9], v[6:7], s[90:91], 1.0 op_sel_hi:[1,0,0]
	v_pk_mul_f32 v[4:5], v[72:73], v[72:73]
	v_pk_mul_f32 v[12:13], v[74:75], v[74:75]
	v_rcp_f32_e32 v238, v238
	v_rcp_f32_e32 v239, v239
	v_rcp_f32_e32 v8, v8
	v_rcp_f32_e32 v9, v9
	v_pk_mul_f32 v[4:5], v[4:5], s[44:45] op_sel_hi:[1,0]
	v_pk_mul_f32 v[12:13], v[12:13], s[44:45] op_sel_hi:[1,0]
	v_pk_fma_f32 v[246:247], v[238:239], s[92:93], v[236:237] op_sel_hi:[1,0,0]
	v_pk_fma_f32 v[10:11], v[8:9], s[92:93], v[236:237] op_sel_hi:[1,0,0]
	v_exp_f32_e32 v4, v4
	v_exp_f32_e32 v5, v5
	v_exp_f32_e32 v12, v12
	v_exp_f32_e32 v13, v13
	v_pk_fma_f32 v[246:247], v[238:239], v[246:247], s[96:97] op_sel_hi:[1,1,0]
	v_pk_fma_f32 v[10:11], v[8:9], v[10:11], s[96:97] op_sel_hi:[1,1,0]
	v_pk_fma_f32 v[246:247], v[238:239], v[246:247], s[0:1] op_sel_hi:[1,1,0]
	v_pk_fma_f32 v[10:11], v[8:9], v[10:11], s[0:1] op_sel_hi:[1,1,0]
	v_pk_fma_f32 v[246:247], v[238:239], v[246:247], s[4:5] op_sel_hi:[1,1,0]
	v_pk_fma_f32 v[10:11], v[8:9], v[10:11], s[4:5] op_sel_hi:[1,1,0]
	v_pk_mul_f32 v[246:247], v[238:239], v[246:247]
	v_pk_mul_f32 v[10:11], v[8:9], v[10:11]
	v_max_f32_e32 v238, 0, v72
	v_max_f32_e32 v239, 0, v73
	v_max_f32_e32 v8, 0, v74
	v_max_f32_e32 v9, 0, v75
	v_pk_mul_f32 v[246:247], v[4:5], v[246:247]
	v_pk_mul_f32 v[10:11], v[12:13], v[10:11]
	v_pk_fma_f32 v[4:5], v[212:213], v[246:247], v[238:239] neg_lo:[1,0,0] neg_hi:[1,0,0]
	v_pk_fma_f32 v[12:13], v[6:7], v[10:11], v[8:9] neg_lo:[1,0,0] neg_hi:[1,0,0]
	v_pk_mul_f32 v[246:247], v[4:5], v[64:65]
	v_pk_mul_f32 v[10:11], v[12:13], v[66:67]
	v_cvt_pk_bf16_f32 v166, v246, v247
	v_cvt_pk_bf16_f32 v167, v10, v11
	v_add_u32_e32 v235, 130, v227
	v_add_u32_e32 v245, 131, v228
	v_cmp_gt_u32_e64 s[38:39], s64, v235
	v_cmp_gt_u32_e32 vcc, s88, v245
	v_add_u32_e32 v235, 737792, v230
	s_and_b64 s[38:39], s[38:39], vcc
	s_and_saveexec_b64 s[30:31], s[38:39]
	global_store_dwordx4 v235, v[164:167], s[50:51]
	s_mov_b64 exec, s[30:31]
	s_nop 1
	s_branch .Lp5_done
.Lp5_edge:
	ds_read_b128 v[56:59], v231 offset:0
	ds_read_b128 v[132:135], v231 offset:512
	ds_read_b128 v[152:155], v233 offset:0
	ds_read_b128 v[156:159], v233 offset:512
	s_waitcnt lgkmcnt(0)
	v_mov_b32_dpp v56, v60 row_shr:1 row_mask:0xf bank_mask:0xf
	v_mov_b32_dpp v57, v61 row_shr:1 row_mask:0xf bank_mask:0xf
	v_mov_b32_dpp v58, v62 row_shr:1 row_mask:0xf bank_mask:0xf
	v_mov_b32_dpp v59, v63 row_shr:1 row_mask:0xf bank_mask:0xf
	v_mov_b32_dpp v132, v44 row_shr:1 row_mask:0xf bank_mask:0xf
	v_mov_b32_dpp v133, v45 row_shr:1 row_mask:0xf bank_mask:0xf
	v_mov_b32_dpp v134, v46 row_shr:1 row_mask:0xf bank_mask:0xf
	v_mov_b32_dpp v135, v47 row_shr:1 row_mask:0xf bank_mask:0xf
	v_mov_b32_dpp v152, v48 row_shl:1 row_mask:0xf bank_mask:0xf
	v_mov_b32_dpp v153, v49 row_shl:1 row_mask:0xf bank_mask:0xf
	v_mov_b32_dpp v154, v50 row_shl:1 row_mask:0xf bank_mask:0xf
	v_mov_b32_dpp v155, v51 row_shl:1 row_mask:0xf bank_mask:0xf
	v_mov_b32_dpp v156, v52 row_shl:1 row_mask:0xf bank_mask:0xf
	v_mov_b32_dpp v157, v53 row_shl:1 row_mask:0xf bank_mask:0xf
	v_mov_b32_dpp v158, v54 row_shl:1 row_mask:0xf bank_mask:0xf
	v_mov_b32_dpp v159, v55 row_shl:1 row_mask:0xf bank_mask:0xf
	v_mov_b32_e32 v235, v228
	v_cmp_gt_i32_e32 vcc, 0x4000, v235
	s_nop 1
	v_cndmask_b32_e32 v245, v222, v221, vcc
	v_and_b32_e32 v235, v235, v245
	v_cmp_eq_u32_e64 s[34:35], 0, v235
	v_cmp_eq_u32_e64 s[36:37], v235, v245
	s_nop 1
	v_cndmask_b32_e64 v56, v56, 0, s[34:35]
	v_cndmask_b32_e64 v57, v57, 0, s[34:35]
	v_cndmask_b32_e64 v58, v58, 0, s[34:35]
	v_cndmask_b32_e64 v59, v59, 0, s[34:35]
	v_cndmask_b32_e64 v132, v132, 0, s[34:35]
	v_cndmask_b32_e64 v133, v133, 0, s[34:35]
	v_cndmask_b32_e64 v134, v134, 0, s[34:35]
	v_cndmask_b32_e64 v135, v135, 0, s[34:35]
	v_pk_fma_f32 v[56:57], v[176:177], v[56:57], v[200:201]
	v_pk_fma_f32 v[58:59], v[178:179], v[58:59], v[202:203]
	v_pk_fma_f32 v[132:133], v[180:181], v[132:133], v[204:205]
	v_pk_fma_f32 v[134:135], v[182:183], v[134:135], v[206:207]
	v_pk_fma_f32 v[56:57], v[48:49], v[184:185], v[56:57]
	v_pk_fma_f32 v[58:59], v[50:51], v[186:187], v[58:59]
	v_pk_fma_f32 v[132:133], v[52:53], v[188:189], v[132:133]
	v_pk_fma_f32 v[134:135], v[54:55], v[190:191], v[134:135]
	s_mov_b64 s[30:31], exec
	s_andn2_b64 exec, exec, s[36:37]
	v_pk_fma_f32 v[56:57], v[192:193], v[124:125], v[56:57]
	v_pk_fma_f32 v[58:59], v[194:195], v[126:127], v[58:59]
	v_pk_fma_f32 v[132:133], v[196:197], v[116:117], v[132:133]
	v_pk_fma_f32 v[134:135], v[198:199], v[118:119], v[134:135]
	s_mov_b64 exec, s[30:31]
	v_and_b32_e32 v212, 0x7fffffff, v56
	v_and_b32_e32 v213, 0x7fffffff, v57
	v_and_b32_e32 v166, 0x7fffffff, v58
	v_and_b32_e32 v167, 0x7fffffff, v59
	v_pk_fma_f32 v[238:239], v[212:213], s[90:91], 1.0 op_sel_hi:[1,0,0]
	v_pk_fma_f32 v[168:169], v[166:167], s[90:91], 1.0 op_sel_hi:[1,0,0]
	v_pk_mul_f32 v[164:165], v[56:57], v[56:57]
	v_pk_mul_f32 v[172:173], v[58:59], v[58:59]
	v_rcp_f32_e32 v238, v238
	v_rcp_f32_e32 v239, v239
	v_rcp_f32_e32 v168, v168
	v_rcp_f32_e32 v169, v169
	v_pk_mul_f32 v[164:165], v[164:165], s[44:45] op_sel_hi:[1,0]
	v_pk_mul_f32 v[172:173], v[172:173], s[44:45] op_sel_hi:[1,0]
	v_pk_fma_f32 v[246:247], v[238:239], s[92:93], v[236:237] op_sel_hi:[1,0,0]
	v_pk_fma_f32 v[170:171], v[168:169], s[92:93], v[236:237] op_sel_hi:[1,0,0]
	v_exp_f32_e32 v164, v164
	v_exp_f32_e32 v165, v165
	v_exp_f32_e32 v172, v172
	v_exp_f32_e32 v173, v173
	v_pk_fma_f32 v[246:247], v[238:239], v[246:247], s[96:97] op_sel_hi:[1,1,0]
	v_pk_fma_f32 v[170:171], v[168:169], v[170:171], s[96:97] op_sel_hi:[1,1,0]
	v_pk_fma_f32 v[246:247], v[238:239], v[246:247], s[0:1] op_sel_hi:[1,1,0]
	v_pk_fma_f32 v[170:171], v[168:169], v[170:171], s[0:1] op_sel_hi:[1,1,0]
	v_pk_fma_f32 v[246:247], v[238:239], v[246:247], s[4:5] op_sel_hi:[1,1,0]
	v_pk_fma_f32 v[170:171], v[168:169], v[170:171], s[4:5] op_sel_hi:[1,1,0]
	v_pk_mul_f32 v[246:247], v[238:239], v[246:247]
	v_pk_mul_f32 v[170:171], v[168:169], v[170:171]
	v_max_f32_e32 v238, 0, v56
	v_max_f32_e32 v239, 0, v57
	v_max_f32_e32 v168, 0, v58
	v_max_f32_e32 v169, 0, v59
	v_pk_mul_f32 v[246:247], v[164:165], v[246:247]
	v_pk_mul_f32 v[170:171], v[172:173], v[170:171]
	v_pk_fma_f32 v[164:165], v[212:213], v[246:247], v[238:239] neg_lo:[1,0,0] neg_hi:[1,0,0]
	v_pk_fma_f32 v[172:173], v[166:167], v[170:171], v[168:169] neg_lo:[1,0,0] neg_hi:[1,0,0]
	v_pk_mul_f32 v[246:247], v[164:165], v[132:133]
	v_pk_mul_f32 v[170:171], v[172:173], v[134:135]
	v_cvt_pk_bf16_f32 v160, v246, v247
	v_cvt_pk_bf16_f32 v161, v170, v171
	v_add_u32_e32 v235, 1, v228
	v_cmp_gt_i32_e32 vcc, 0x4000, v235
	s_nop 1
	v_cndmask_b32_e32 v245, v222, v221, vcc
	v_and_b32_e32 v235, v235, v245
	v_cmp_eq_u32_e64 s[34:35], 0, v235
	v_cmp_eq_u32_e64 s[36:37], v235, v245
	s_nop 1
	v_cndmask_b32_e64 v48, v48, 0, s[34:35]
	v_cndmask_b32_e64 v49, v49, 0, s[34:35]
	v_cndmask_b32_e64 v50, v50, 0, s[34:35]
	v_cndmask_b32_e64 v51, v51, 0, s[34:35]
	v_cndmask_b32_e64 v52, v52, 0, s[34:35]
	v_cndmask_b32_e64 v53, v53, 0, s[34:35]
	v_cndmask_b32_e64 v54, v54, 0, s[34:35]
	v_cndmask_b32_e64 v55, v55, 0, s[34:35]
	v_pk_fma_f32 v[48:49], v[176:177], v[48:49], v[200:201]
	v_pk_fma_f32 v[50:51], v[178:179], v[50:51], v[202:203]
	v_pk_fma_f32 v[52:53], v[180:181], v[52:53], v[204:205]
	v_pk_fma_f32 v[54:55], v[182:183], v[54:55], v[206:207]
	v_pk_fma_f32 v[48:49], v[124:125], v[184:185], v[48:49]
	v_pk_fma_f32 v[50:51], v[126:127], v[186:187], v[50:51]
	v_pk_fma_f32 v[52:53], v[116:117], v[188:189], v[52:53]
	v_pk_fma_f32 v[54:55], v[118:119], v[190:191], v[54:55]
	s_mov_b64 s[30:31], exec
	s_andn2_b64 exec, exec, s[36:37]
	v_pk_fma_f32 v[48:49], v[192:193], v[112:113], v[48:49]
	v_pk_fma_f32 v[50:51], v[194:195], v[114:115], v[50:51]
	v_pk_fma_f32 v[52:53], v[196:197], v[100:101], v[52:53]
	v_pk_fma_f32 v[54:55], v[198:199], v[102:103], v[54:55]
	s_mov_b64 exec, s[30:31]
	v_and_b32_e32 v212, 0x7fffffff, v48
	v_and_b32_e32 v213, 0x7fffffff, v49
	v_and_b32_e32 v134, 0x7fffffff, v50
	v_and_b32_e32 v135, 0x7fffffff, v51
	v_pk_fma_f32 v[238:239], v[212:213], s[90:91], 1.0 op_sel_hi:[1,0,0]
	v_pk_fma_f32 v[164:165], v[134:135], s[90:91], 1.0 op_sel_hi:[1,0,0]
	v_pk_mul_f32 v[132:133], v[48:49], v[48:49]
	v_pk_mul_f32 v[168:169], v[50:51], v[50:51]
	v_rcp_f32_e32 v238, v238
	v_rcp_f32_e32 v239, v239
	v_rcp_f32_e32 v164, v164
	v_rcp_f32_e32 v165, v165
	v_pk_mul_f32 v[132:133], v[132:133], s[44:45] op_sel_hi:[1,0]
	v_pk_mul_f32 v[168:169], v[168:169], s[44:45] op_sel_hi:[1,0]
	v_pk_fma_f32 v[246:247], v[238:239], s[92:93], v[236:237] op_sel_hi:[1,0,0]
	v_pk_fma_f32 v[166:167], v[164:165], s[92:93], v[236:237] op_sel_hi:[1,0,0]
	v_exp_f32_e32 v132, v132
	v_exp_f32_e32 v133, v133
	v_exp_f32_e32 v168, v168
	v_exp_f32_e32 v169, v169
	v_pk_fma_f32 v[246:247], v[238:239], v[246:247], s[96:97] op_sel_hi:[1,1,0]
	v_pk_fma_f32 v[166:167], v[164:165], v[166:167], s[96:97] op_sel_hi:[1,1,0]
	v_pk_fma_f32 v[246:247], v[238:239], v[246:247], s[0:1] op_sel_hi:[1,1,0]
	v_pk_fma_f32 v[166:167], v[164:165], v[166:167], s[0:1] op_sel_hi:[1,1,0]
	v_pk_fma_f32 v[246:247], v[238:239], v[246:247], s[4:5] op_sel_hi:[1,1,0]
	v_pk_fma_f32 v[166:167], v[164:165], v[166:167], s[4:5] op_sel_hi:[1,1,0]
	v_pk_mul_f32 v[246:247], v[238:239], v[246:247]
	v_pk_mul_f32 v[166:167], v[164:165], v[166:167]
	v_max_f32_e32 v238, 0, v48
	v_max_f32_e32 v239, 0, v49
	v_max_f32_e32 v164, 0, v50
	v_max_f32_e32 v165, 0, v51
	v_pk_mul_f32 v[246:247], v[132:133], v[246:247]
	v_pk_mul_f32 v[166:167], v[168:169], v[166:167]
	v_pk_fma_f32 v[132:133], v[212:213], v[246:247], v[238:239] neg_lo:[1,0,0] neg_hi:[1,0,0]
	v_pk_fma_f32 v[168:169], v[134:135], v[166:167], v[164:165] neg_lo:[1,0,0] neg_hi:[1,0,0]
	v_pk_mul_f32 v[246:247], v[132:133], v[52:53]
	v_pk_mul_f32 v[166:167], v[168:169], v[54:55]
	v_cvt_pk_bf16_f32 v56, v246, v247
	v_cvt_pk_bf16_f32 v57, v166, v167
	v_add_u32_e32 v235, 2, v228
	v_cmp_gt_i32_e32 vcc, 0x4000, v235
	s_nop 1
	v_cndmask_b32_e32 v245, v222, v221, vcc
	v_and_b32_e32 v235, v235, v245
	v_cmp_eq_u32_e64 s[34:35], 0, v235
	v_cmp_eq_u32_e64 s[36:37], v235, v245
	s_nop 1
	v_cndmask_b32_e64 v124, v124, 0, s[34:35]
	v_cndmask_b32_e64 v125, v125, 0, s[34:35]
	v_cndmask_b32_e64 v126, v126, 0, s[34:35]
	v_cndmask_b32_e64 v127, v127, 0, s[34:35]
	v_cndmask_b32_e64 v116, v116, 0, s[34:35]
	v_cndmask_b32_e64 v117, v117, 0, s[34:35]
	v_cndmask_b32_e64 v118, v118, 0, s[34:35]
	v_cndmask_b32_e64 v119, v119, 0, s[34:35]
	v_pk_fma_f32 v[124:125], v[176:177], v[124:125], v[200:201]
	v_pk_fma_f32 v[126:127], v[178:179], v[126:127], v[202:203]
	v_pk_fma_f32 v[116:117], v[180:181], v[116:117], v[204:205]
	v_pk_fma_f32 v[118:119], v[182:183], v[118:119], v[206:207]
	v_pk_fma_f32 v[124:125], v[112:113], v[184:185], v[124:125]
	v_pk_fma_f32 v[126:127], v[114:115], v[186:187], v[126:127]
	v_pk_fma_f32 v[116:117], v[100:101], v[188:189], v[116:117]
	v_pk_fma_f32 v[118:119], v[102:103], v[190:191], v[118:119]
	s_mov_b64 s[30:31], exec
	s_andn2_b64 exec, exec, s[36:37]
	v_pk_fma_f32 v[124:125], v[192:193], v[60:61], v[124:125]
	v_pk_fma_f32 v[126:127], v[194:195], v[62:63], v[126:127]
	v_pk_fma_f32 v[116:117], v[196:197], v[44:45], v[116:117]
	v_pk_fma_f32 v[118:119], v[198:199], v[46:47], v[118:119]
	s_mov_b64 exec, s[30:31]
	v_and_b32_e32 v212, 0x7fffffff, v124
	v_and_b32_e32 v213, 0x7fffffff, v125
	v_and_b32_e32 v54, 0x7fffffff, v126
	v_and_b32_e32 v55, 0x7fffffff, v127
	v_pk_fma_f32 v[238:239], v[212:213], s[90:91], 1.0 op_sel_hi:[1,0,0]
	v_pk_fma_f32 v[132:133], v[54:55], s[90:91], 1.0 op_sel_hi:[1,0,0]
	v_pk_mul_f32 v[52:53], v[124:125], v[124:125]
	v_pk_mul_f32 v[164:165], v[126:127], v[126:127]
	v_rcp_f32_e32 v238, v238
	v_rcp_f32_e32 v239, v239
	v_rcp_f32_e32 v132, v132
	v_rcp_f32_e32 v133, v133
	v_pk_mul_f32 v[52:53], v[52:53], s[44:45] op_sel_hi:[1,0]
	v_pk_mul_f32 v[164:165], v[164:165], s[44:45] op_sel_hi:[1,0]
	v_pk_fma_f32 v[246:247], v[238:239], s[92:93], v[236:237] op_sel_hi:[1,0,0]
	v_pk_fma_f32 v[134:135], v[132:133], s[92:93], v[236:237] op_sel_hi:[1,0,0]
	v_exp_f32_e32 v52, v52
	v_exp_f32_e32 v53, v53
	v_exp_f32_e32 v164, v164
	v_exp_f32_e32 v165, v165
	v_pk_fma_f32 v[246:247], v[238:239], v[246:247], s[96:97] op_sel_hi:[1,1,0]
	v_pk_fma_f32 v[134:135], v[132:133], v[134:135], s[96:97] op_sel_hi:[1,1,0]
	v_pk_fma_f32 v[246:247], v[238:239], v[246:247], s[0:1] op_sel_hi:[1,1,0]
	v_pk_fma_f32 v[134:135], v[132:133], v[134:135], s[0:1] op_sel_hi:[1,1,0]
	v_pk_fma_f32 v[246:247], v[238:239], v[246:247], s[4:5] op_sel_hi:[1,1,0]
	v_pk_fma_f32 v[134:135], v[132:133], v[134:135], s[4:5] op_sel_hi:[1,1,0]
	v_pk_mul_f32 v[246:247], v[238:239], v[246:247]
	v_pk_mul_f32 v[134:135], v[132:133], v[134:135]
	v_max_f32_e32 v238, 0, v124
	v_max_f32_e32 v239, 0, v125
	v_max_f32_e32 v132, 0, v126
	v_max_f32_e32 v133, 0, v127
	v_pk_mul_f32 v[246:247], v[52:53], v[246:247]
	v_pk_mul_f32 v[134:135], v[164:165], v[134:135]
	v_pk_fma_f32 v[52:53], v[212:213], v[246:247], v[238:239] neg_lo:[1,0,0] neg_hi:[1,0,0]
	v_pk_fma_f32 v[164:165], v[54:55], v[134:135], v[132:133] neg_lo:[1,0,0] neg_hi:[1,0,0]
	v_pk_mul_f32 v[246:247], v[52:53], v[116:117]
	v_pk_mul_f32 v[134:135], v[164:165], v[118:119]
	v_cvt_pk_bf16_f32 v48, v246, v247
	v_cvt_pk_bf16_f32 v49, v134, v135
	v_add_u32_e32 v235, 3, v228
	v_cmp_gt_i32_e32 vcc, 0x4000, v235
	s_nop 1
	v_cndmask_b32_e32 v245, v222, v221, vcc
	v_and_b32_e32 v235, v235, v245
	v_cmp_eq_u32_e64 s[34:35], 0, v235
	v_cmp_eq_u32_e64 s[36:37], v235, v245
	s_nop 1
	v_cndmask_b32_e64 v112, v112, 0, s[34:35]
	v_cndmask_b32_e64 v113, v113, 0, s[34:35]
	v_cndmask_b32_e64 v114, v114, 0, s[34:35]
	v_cndmask_b32_e64 v115, v115, 0, s[34:35]
	v_cndmask_b32_e64 v100, v100, 0, s[34:35]
	v_cndmask_b32_e64 v101, v101, 0, s[34:35]
	v_cndmask_b32_e64 v102, v102, 0, s[34:35]
	v_cndmask_b32_e64 v103, v103, 0, s[34:35]
	v_pk_fma_f32 v[112:113], v[176:177], v[112:113], v[200:201]
	v_pk_fma_f32 v[114:115], v[178:179], v[114:115], v[202:203]
	v_pk_fma_f32 v[100:101], v[180:181], v[100:101], v[204:205]
	v_pk_fma_f32 v[102:103], v[182:183], v[102:103], v[206:207]
	v_pk_fma_f32 v[112:113], v[60:61], v[184:185], v[112:113]
	v_pk_fma_f32 v[114:115], v[62:63], v[186:187], v[114:115]
	v_pk_fma_f32 v[100:101], v[44:45], v[188:189], v[100:101]
	v_pk_fma_f32 v[102:103], v[46:47], v[190:191], v[102:103]
	s_mov_b64 s[30:31], exec
	s_andn2_b64 exec, exec, s[36:37]
	v_pk_fma_f32 v[112:113], v[192:193], v[152:153], v[112:113]
	v_pk_fma_f32 v[114:115], v[194:195], v[154:155], v[114:115]
	v_pk_fma_f32 v[100:101], v[196:197], v[156:157], v[100:101]
	v_pk_fma_f32 v[102:103], v[198:199], v[158:159], v[102:103]
	s_mov_b64 exec, s[30:31]
	v_and_b32_e32 v212, 0x7fffffff, v112
	v_and_b32_e32 v213, 0x7fffffff, v113
	v_and_b32_e32 v118, 0x7fffffff, v114
	v_and_b32_e32 v119, 0x7fffffff, v115
	v_pk_fma_f32 v[238:239], v[212:213], s[90:91], 1.0 op_sel_hi:[1,0,0]
	v_pk_fma_f32 v[124:125], v[118:119], s[90:91], 1.0 op_sel_hi:[1,0,0]
	v_pk_mul_f32 v[116:117], v[112:113], v[112:113]
	v_pk_mul_f32 v[132:133], v[114:115], v[114:115]
	v_rcp_f32_e32 v238, v238
	v_rcp_f32_e32 v239, v239
	v_rcp_f32_e32 v124, v124
	v_rcp_f32_e32 v125, v125
	v_pk_mul_f32 v[116:117], v[116:117], s[44:45] op_sel_hi:[1,0]
	v_pk_mul_f32 v[132:133], v[132:133], s[44:45] op_sel_hi:[1,0]
	v_pk_fma_f32 v[246:247], v[238:239], s[92:93], v[236:237] op_sel_hi:[1,0,0]
	v_pk_fma_f32 v[126:127], v[124:125], s[92:93], v[236:237] op_sel_hi:[1,0,0]
	v_exp_f32_e32 v116, v116
	v_exp_f32_e32 v117, v117
	v_exp_f32_e32 v132, v132
	v_exp_f32_e32 v133, v133
	v_pk_fma_f32 v[246:247], v[238:239], v[246:247], s[96:97] op_sel_hi:[1,1,0]
	v_pk_fma_f32 v[126:127], v[124:125], v[126:127], s[96:97] op_sel_hi:[1,1,0]
	v_pk_fma_f32 v[246:247], v[238:239], v[246:247], s[0:1] op_sel_hi:[1,1,0]
	v_pk_fma_f32 v[126:127], v[124:125], v[126:127], s[0:1] op_sel_hi:[1,1,0]
	v_pk_fma_f32 v[246:247], v[238:239], v[246:247], s[4:5] op_sel_hi:[1,1,0]
	v_pk_fma_f32 v[126:127], v[124:125], v[126:127], s[4:5] op_sel_hi:[1,1,0]
	v_pk_mul_f32 v[246:247], v[238:239], v[246:247]
	v_pk_mul_f32 v[126:127], v[124:125], v[126:127]
	v_max_f32_e32 v238, 0, v112
	v_max_f32_e32 v239, 0, v113
	v_max_f32_e32 v124, 0, v114
	v_max_f32_e32 v125, 0, v115
	v_pk_mul_f32 v[246:247], v[116:117], v[246:247]
	v_pk_mul_f32 v[126:127], v[132:133], v[126:127]
	v_pk_fma_f32 v[116:117], v[212:213], v[246:247], v[238:239] neg_lo:[1,0,0] neg_hi:[1,0,0]
	v_pk_fma_f32 v[132:133], v[118:119], v[126:127], v[124:125] neg_lo:[1,0,0] neg_hi:[1,0,0]
	v_pk_mul_f32 v[246:247], v[116:117], v[100:101]
	v_pk_mul_f32 v[126:127], v[132:133], v[102:103]
	v_cvt_pk_bf16_f32 v52, v246, v247
	v_cvt_pk_bf16_f32 v53, v126, v127
	ds_read_b128 v[44:47], v232 offset:0
	ds_read_b128 v[60:63], v232 offset:512
	ds_read_b128 v[100:103], v234 offset:0
	ds_read_b128 v[112:115], v234 offset:512
	s_waitcnt lgkmcnt(0)
	v_mov_b32_dpp v44, v4 row_shr:1 row_mask:0xf bank_mask:0xf
	v_mov_b32_dpp v45, v5 row_shr:1 row_mask:0xf bank_mask:0xf
	v_mov_b32_dpp v46, v6 row_shr:1 row_mask:0xf bank_mask:0xf
	v_mov_b32_dpp v47, v7 row_shr:1 row_mask:0xf bank_mask:0xf
	v_mov_b32_dpp v60, v32 row_shr:1 row_mask:0xf bank_mask:0xf
	v_mov_b32_dpp v61, v33 row_shr:1 row_mask:0xf bank_mask:0xf
	v_mov_b32_dpp v62, v34 row_shr:1 row_mask:0xf bank_mask:0xf
	v_mov_b32_dpp v63, v35 row_shr:1 row_mask:0xf bank_mask:0xf
	v_mov_b32_dpp v100, v12 row_shl:1 row_mask:0xf bank_mask:0xf
	v_mov_b32_dpp v101, v13 row_shl:1 row_mask:0xf bank_mask:0xf
	v_mov_b32_dpp v102, v14 row_shl:1 row_mask:0xf bank_mask:0xf
	v_mov_b32_dpp v103, v15 row_shl:1 row_mask:0xf bank_mask:0xf
	v_mov_b32_dpp v112, v40 row_shl:1 row_mask:0xf bank_mask:0xf
	v_mov_b32_dpp v113, v41 row_shl:1 row_mask:0xf bank_mask:0xf
	v_mov_b32_dpp v114, v42 row_shl:1 row_mask:0xf bank_mask:0xf
	v_mov_b32_dpp v115, v43 row_shl:1 row_mask:0xf bank_mask:0xf
	v_add_u32_e32 v235, 128, v228
	v_cmp_gt_i32_e32 vcc, 0x4000, v235
	s_nop 1
	v_cndmask_b32_e32 v245, v222, v221, vcc
	v_and_b32_e32 v235, v235, v245
	v_cmp_eq_u32_e64 s[34:35], 0, v235
	v_cmp_eq_u32_e64 s[36:37], v235, v245
	s_nop 1
	v_cndmask_b32_e64 v44, v44, 0, s[34:35]
	v_cndmask_b32_e64 v45, v45, 0, s[34:35]
	v_cndmask_b32_e64 v46, v46, 0, s[34:35]
	v_cndmask_b32_e64 v47, v47, 0, s[34:35]
	v_cndmask_b32_e64 v60, v60, 0, s[34:35]
	v_cndmask_b32_e64 v61, v61, 0, s[34:35]
	v_cndmask_b32_e64 v62, v62, 0, s[34:35]
	v_cndmask_b32_e64 v63, v63, 0, s[34:35]
	v_pk_fma_f32 v[44:45], v[176:177], v[44:45], v[200:201]
	v_pk_fma_f32 v[46:47], v[178:179], v[46:47], v[202:203]
	v_pk_fma_f32 v[60:61], v[180:181], v[60:61], v[204:205]
	v_pk_fma_f32 v[62:63], v[182:183], v[62:63], v[206:207]
	v_pk_fma_f32 v[44:45], v[12:13], v[184:185], v[44:45]
	v_pk_fma_f32 v[46:47], v[14:15], v[186:187], v[46:47]
	v_pk_fma_f32 v[60:61], v[40:41], v[188:189], v[60:61]
	v_pk_fma_f32 v[62:63], v[42:43], v[190:191], v[62:63]
	s_mov_b64 s[30:31], exec
	s_andn2_b64 exec, exec, s[36:37]
	v_pk_fma_f32 v[44:45], v[192:193], v[92:93], v[44:45]
	v_pk_fma_f32 v[46:47], v[194:195], v[94:95], v[46:47]
	v_pk_fma_f32 v[60:61], v[196:197], v[84:85], v[60:61]
	v_pk_fma_f32 v[62:63], v[198:199], v[86:87], v[62:63]
	s_mov_b64 exec, s[30:31]
	v_and_b32_e32 v212, 0x7fffffff, v44
	v_and_b32_e32 v213, 0x7fffffff, v45
	v_and_b32_e32 v126, 0x7fffffff, v46
	v_and_b32_e32 v127, 0x7fffffff, v47
	v_pk_fma_f32 v[238:239], v[212:213], s[90:91], 1.0 op_sel_hi:[1,0,0]
	v_pk_fma_f32 v[132:133], v[126:127], s[90:91], 1.0 op_sel_hi:[1,0,0]
	v_pk_mul_f32 v[124:125], v[44:45], v[44:45]
	v_pk_mul_f32 v[152:153], v[46:47], v[46:47]
	v_rcp_f32_e32 v238, v238
	v_rcp_f32_e32 v239, v239
	v_rcp_f32_e32 v132, v132
	v_rcp_f32_e32 v133, v133
	v_pk_mul_f32 v[124:125], v[124:125], s[44:45] op_sel_hi:[1,0]
	v_pk_mul_f32 v[152:153], v[152:153], s[44:45] op_sel_hi:[1,0]
	v_pk_fma_f32 v[246:247], v[238:239], s[92:93], v[236:237] op_sel_hi:[1,0,0]
	v_pk_fma_f32 v[134:135], v[132:133], s[92:93], v[236:237] op_sel_hi:[1,0,0]
	v_exp_f32_e32 v124, v124
	v_exp_f32_e32 v125, v125
	v_exp_f32_e32 v152, v152
	v_exp_f32_e32 v153, v153
	v_pk_fma_f32 v[246:247], v[238:239], v[246:247], s[96:97] op_sel_hi:[1,1,0]
	v_pk_fma_f32 v[134:135], v[132:133], v[134:135], s[96:97] op_sel_hi:[1,1,0]
	v_pk_fma_f32 v[246:247], v[238:239], v[246:247], s[0:1] op_sel_hi:[1,1,0]
	v_pk_fma_f32 v[134:135], v[132:133], v[134:135], s[0:1] op_sel_hi:[1,1,0]
	v_pk_fma_f32 v[246:247], v[238:239], v[246:247], s[4:5] op_sel_hi:[1,1,0]
	v_pk_fma_f32 v[134:135], v[132:133], v[134:135], s[4:5] op_sel_hi:[1,1,0]
	v_pk_mul_f32 v[246:247], v[238:239], v[246:247]
	v_pk_mul_f32 v[134:135], v[132:133], v[134:135]
	v_max_f32_e32 v238, 0, v44
	v_max_f32_e32 v239, 0, v45
	v_max_f32_e32 v132, 0, v46
	v_max_f32_e32 v133, 0, v47
	v_pk_mul_f32 v[246:247], v[124:125], v[246:247]
	v_pk_mul_f32 v[134:135], v[152:153], v[134:135]
	v_pk_fma_f32 v[124:125], v[212:213], v[246:247], v[238:239] neg_lo:[1,0,0] neg_hi:[1,0,0]
	v_pk_fma_f32 v[152:153], v[126:127], v[134:135], v[132:133] neg_lo:[1,0,0] neg_hi:[1,0,0]
	v_pk_mul_f32 v[246:247], v[124:125], v[60:61]
	v_pk_mul_f32 v[134:135], v[152:153], v[62:63]
	v_cvt_pk_bf16_f32 v116, v246, v247
	v_cvt_pk_bf16_f32 v117, v134, v135
	v_add_u32_e32 v235, 129, v228
	v_cmp_gt_i32_e32 vcc, 0x4000, v235
	s_nop 1
	v_cndmask_b32_e32 v245, v222, v221, vcc
	v_and_b32_e32 v235, v235, v245
	v_cmp_eq_u32_e64 s[34:35], 0, v235
	v_cmp_eq_u32_e64 s[36:37], v235, v245
	s_nop 1
	v_cndmask_b32_e64 v12, v12, 0, s[34:35]
	v_cndmask_b32_e64 v13, v13, 0, s[34:35]
	v_cndmask_b32_e64 v14, v14, 0, s[34:35]
	v_cndmask_b32_e64 v15, v15, 0, s[34:35]
	v_cndmask_b32_e64 v40, v40, 0, s[34:35]
	v_cndmask_b32_e64 v41, v41, 0, s[34:35]
	v_cndmask_b32_e64 v42, v42, 0, s[34:35]
	v_cndmask_b32_e64 v43, v43, 0, s[34:35]
	v_pk_fma_f32 v[12:13], v[176:177], v[12:13], v[200:201]
	v_pk_fma_f32 v[14:15], v[178:179], v[14:15], v[202:203]
	v_pk_fma_f32 v[40:41], v[180:181], v[40:41], v[204:205]
	v_pk_fma_f32 v[42:43], v[182:183], v[42:43], v[206:207]
	v_pk_fma_f32 v[12:13], v[92:93], v[184:185], v[12:13]
	v_pk_fma_f32 v[14:15], v[94:95], v[186:187], v[14:15]
	v_pk_fma_f32 v[40:41], v[84:85], v[188:189], v[40:41]
	v_pk_fma_f32 v[42:43], v[86:87], v[190:191], v[42:43]
	s_mov_b64 s[30:31], exec
	s_andn2_b64 exec, exec, s[36:37]
	v_pk_fma_f32 v[12:13], v[192:193], v[80:81], v[12:13]
	v_pk_fma_f32 v[14:15], v[194:195], v[82:83], v[14:15]
	v_pk_fma_f32 v[40:41], v[196:197], v[68:69], v[40:41]
	v_pk_fma_f32 v[42:43], v[198:199], v[70:71], v[42:43]
	s_mov_b64 exec, s[30:31]
	v_and_b32_e32 v212, 0x7fffffff, v12
	v_and_b32_e32 v213, 0x7fffffff, v13
	v_and_b32_e32 v62, 0x7fffffff, v14
	v_and_b32_e32 v63, 0x7fffffff, v15
	v_pk_fma_f32 v[238:239], v[212:213], s[90:91], 1.0 op_sel_hi:[1,0,0]
	v_pk_fma_f32 v[124:125], v[62:63], s[90:91], 1.0 op_sel_hi:[1,0,0]
	v_pk_mul_f32 v[60:61], v[12:13], v[12:13]
	v_pk_mul_f32 v[132:133], v[14:15], v[14:15]
	v_rcp_f32_e32 v238, v238
	v_rcp_f32_e32 v239, v239
	v_rcp_f32_e32 v124, v124
	v_rcp_f32_e32 v125, v125
	v_pk_mul_f32 v[60:61], v[60:61], s[44:45] op_sel_hi:[1,0]
	v_pk_mul_f32 v[132:133], v[132:133], s[44:45] op_sel_hi:[1,0]
	v_pk_fma_f32 v[246:247], v[238:239], s[92:93], v[236:237] op_sel_hi:[1,0,0]
	v_pk_fma_f32 v[126:127], v[124:125], s[92:93], v[236:237] op_sel_hi:[1,0,0]
	v_exp_f32_e32 v60, v60
	v_exp_f32_e32 v61, v61
	v_exp_f32_e32 v132, v132
	v_exp_f32_e32 v133, v133
	v_pk_fma_f32 v[246:247], v[238:239], v[246:247], s[96:97] op_sel_hi:[1,1,0]
	v_pk_fma_f32 v[126:127], v[124:125], v[126:127], s[96:97] op_sel_hi:[1,1,0]
	v_pk_fma_f32 v[246:247], v[238:239], v[246:247], s[0:1] op_sel_hi:[1,1,0]
	v_pk_fma_f32 v[126:127], v[124:125], v[126:127], s[0:1] op_sel_hi:[1,1,0]
	v_pk_fma_f32 v[246:247], v[238:239], v[246:247], s[4:5] op_sel_hi:[1,1,0]
	v_pk_fma_f32 v[126:127], v[124:125], v[126:127], s[4:5] op_sel_hi:[1,1,0]
	v_pk_mul_f32 v[246:247], v[238:239], v[246:247]
	v_pk_mul_f32 v[126:127], v[124:125], v[126:127]
	v_max_f32_e32 v238, 0, v12
	v_max_f32_e32 v239, 0, v13
	v_max_f32_e32 v124, 0, v14
	v_max_f32_e32 v125, 0, v15
	v_pk_mul_f32 v[246:247], v[60:61], v[246:247]
	v_pk_mul_f32 v[126:127], v[132:133], v[126:127]
	v_pk_fma_f32 v[60:61], v[212:213], v[246:247], v[238:239] neg_lo:[1,0,0] neg_hi:[1,0,0]
	v_pk_fma_f32 v[132:133], v[62:63], v[126:127], v[124:125] neg_lo:[1,0,0] neg_hi:[1,0,0]
	v_pk_mul_f32 v[246:247], v[60:61], v[40:41]
	v_pk_mul_f32 v[126:127], v[132:133], v[42:43]
	v_cvt_pk_bf16_f32 v44, v246, v247
	v_cvt_pk_bf16_f32 v45, v126, v127
	v_add_u32_e32 v235, 130, v228
	v_cmp_gt_i32_e32 vcc, 0x4000, v235
	s_nop 1
	v_cndmask_b32_e32 v245, v222, v221, vcc
	v_and_b32_e32 v235, v235, v245
	v_cmp_eq_u32_e64 s[34:35], 0, v235
	v_cmp_eq_u32_e64 s[36:37], v235, v245
	s_nop 1
	v_cndmask_b32_e64 v92, v92, 0, s[34:35]
	v_cndmask_b32_e64 v93, v93, 0, s[34:35]
	v_cndmask_b32_e64 v94, v94, 0, s[34:35]
	v_cndmask_b32_e64 v95, v95, 0, s[34:35]
	v_cndmask_b32_e64 v84, v84, 0, s[34:35]
	v_cndmask_b32_e64 v85, v85, 0, s[34:35]
	v_cndmask_b32_e64 v86, v86, 0, s[34:35]
	v_cndmask_b32_e64 v87, v87, 0, s[34:35]
	v_pk_fma_f32 v[92:93], v[176:177], v[92:93], v[200:201]
	v_pk_fma_f32 v[94:95], v[178:179], v[94:95], v[202:203]
	v_pk_fma_f32 v[84:85], v[180:181], v[84:85], v[204:205]
	v_pk_fma_f32 v[86:87], v[182:183], v[86:87], v[206:207]
	v_pk_fma_f32 v[92:93], v[80:81], v[184:185], v[92:93]
	v_pk_fma_f32 v[94:95], v[82:83], v[186:187], v[94:95]
	v_pk_fma_f32 v[84:85], v[68:69], v[188:189], v[84:85]
	v_pk_fma_f32 v[86:87], v[70:71], v[190:191], v[86:87]
	s_mov_b64 s[30:31], exec
	s_andn2_b64 exec, exec, s[36:37]
	v_pk_fma_f32 v[92:93], v[192:193], v[4:5], v[92:93]
	v_pk_fma_f32 v[94:95], v[194:195], v[6:7], v[94:95]
	v_pk_fma_f32 v[84:85], v[196:197], v[32:33], v[84:85]
	v_pk_fma_f32 v[86:87], v[198:199], v[34:35], v[86:87]
	s_mov_b64 exec, s[30:31]
	v_and_b32_e32 v212, 0x7fffffff, v92
	v_and_b32_e32 v213, 0x7fffffff, v93
	v_and_b32_e32 v42, 0x7fffffff, v94
	v_and_b32_e32 v43, 0x7fffffff, v95
	v_pk_fma_f32 v[238:239], v[212:213], s[90:91], 1.0 op_sel_hi:[1,0,0]
	v_pk_fma_f32 v[60:61], v[42:43], s[90:91], 1.0 op_sel_hi:[1,0,0]
	v_pk_mul_f32 v[40:41], v[92:93], v[92:93]
	v_pk_mul_f32 v[124:125], v[94:95], v[94:95]
	v_rcp_f32_e32 v238, v238
	v_rcp_f32_e32 v239, v239
	v_rcp_f32_e32 v60, v60
	v_rcp_f32_e32 v61, v61
	v_pk_mul_f32 v[40:41], v[40:41], s[44:45] op_sel_hi:[1,0]
	v_pk_mul_f32 v[124:125], v[124:125], s[44:45] op_sel_hi:[1,0]
	v_pk_fma_f32 v[246:247], v[238:239], s[92:93], v[236:237] op_sel_hi:[1,0,0]
	v_pk_fma_f32 v[62:63], v[60:61], s[92:93], v[236:237] op_sel_hi:[1,0,0]
	v_exp_f32_e32 v40, v40
	v_exp_f32_e32 v41, v41
	v_exp_f32_e32 v124, v124
	v_exp_f32_e32 v125, v125
	v_pk_fma_f32 v[246:247], v[238:239], v[246:247], s[96:97] op_sel_hi:[1,1,0]
	v_pk_fma_f32 v[62:63], v[60:61], v[62:63], s[96:97] op_sel_hi:[1,1,0]
	v_pk_fma_f32 v[246:247], v[238:239], v[246:247], s[0:1] op_sel_hi:[1,1,0]
	v_pk_fma_f32 v[62:63], v[60:61], v[62:63], s[0:1] op_sel_hi:[1,1,0]
	v_pk_fma_f32 v[246:247], v[238:239], v[246:247], s[4:5] op_sel_hi:[1,1,0]
	v_pk_fma_f32 v[62:63], v[60:61], v[62:63], s[4:5] op_sel_hi:[1,1,0]
	v_pk_mul_f32 v[246:247], v[238:239], v[246:247]
	v_pk_mul_f32 v[62:63], v[60:61], v[62:63]
	v_max_f32_e32 v238, 0, v92
	v_max_f32_e32 v239, 0, v93
	v_max_f32_e32 v60, 0, v94
	v_max_f32_e32 v61, 0, v95
	v_pk_mul_f32 v[246:247], v[40:41], v[246:247]
	v_pk_mul_f32 v[62:63], v[124:125], v[62:63]
	v_pk_fma_f32 v[40:41], v[212:213], v[246:247], v[238:239] neg_lo:[1,0,0] neg_hi:[1,0,0]
	v_pk_fma_f32 v[124:125], v[42:43], v[62:63], v[60:61] neg_lo:[1,0,0] neg_hi:[1,0,0]
	v_pk_mul_f32 v[246:247], v[40:41], v[84:85]
	v_pk_mul_f32 v[62:63], v[124:125], v[86:87]
	v_cvt_pk_bf16_f32 v12, v246, v247
	v_cvt_pk_bf16_f32 v13, v62, v63
	ds_read_b128 v[40:43], v226 offset:16
	ds_read_b128 v[60:63], v226 offset:528
	ds_read_b128 v[84:87], v226 offset:1040
	ds_read_b128 v[92:95], v226 offset:1552
	ds_read_b128 v[124:127], v226 offset:2064
	ds_read_b128 v[132:135], v226 offset:2576
	ds_read_b128 v[152:155], v226 offset:3088
	ds_read_b128 v[156:159], v226 offset:3600
	v_add_u32_e32 v235, 131, v228
	v_cmp_gt_i32_e32 vcc, 0x4000, v235
	s_nop 1
	v_cndmask_b32_e32 v245, v222, v221, vcc
	v_and_b32_e32 v235, v235, v245
	v_cmp_eq_u32_e64 s[34:35], 0, v235
	v_cmp_eq_u32_e64 s[36:37], v235, v245
	s_nop 1
	v_cndmask_b32_e64 v80, v80, 0, s[34:35]
	v_cndmask_b32_e64 v81, v81, 0, s[34:35]
	v_cndmask_b32_e64 v82, v82, 0, s[34:35]
	v_cndmask_b32_e64 v83, v83, 0, s[34:35]
	v_cndmask_b32_e64 v68, v68, 0, s[34:35]
	v_cndmask_b32_e64 v69, v69, 0, s[34:35]
	v_cndmask_b32_e64 v70, v70, 0, s[34:35]
	v_cndmask_b32_e64 v71, v71, 0, s[34:35]
	v_pk_fma_f32 v[80:81], v[176:177], v[80:81], v[200:201]
	v_pk_fma_f32 v[82:83], v[178:179], v[82:83], v[202:203]
	v_pk_fma_f32 v[68:69], v[180:181], v[68:69], v[204:205]
	v_pk_fma_f32 v[70:71], v[182:183], v[70:71], v[206:207]
	v_pk_fma_f32 v[80:81], v[4:5], v[184:185], v[80:81]
	v_pk_fma_f32 v[82:83], v[6:7], v[186:187], v[82:83]
	v_pk_fma_f32 v[68:69], v[32:33], v[188:189], v[68:69]
	v_pk_fma_f32 v[70:71], v[34:35], v[190:191], v[70:71]
	s_mov_b64 s[30:31], exec
	s_andn2_b64 exec, exec, s[36:37]
	v_pk_fma_f32 v[80:81], v[192:193], v[100:101], v[80:81]
	v_pk_fma_f32 v[82:83], v[194:195], v[102:103], v[82:83]
	v_pk_fma_f32 v[68:69], v[196:197], v[112:113], v[68:69]
	v_pk_fma_f32 v[70:71], v[198:199], v[114:115], v[70:71]
	s_mov_b64 exec, s[30:31]
	v_and_b32_e32 v212, 0x7fffffff, v80
	v_and_b32_e32 v213, 0x7fffffff, v81
	v_and_b32_e32 v170, 0x7fffffff, v82
	v_and_b32_e32 v171, 0x7fffffff, v83
	v_pk_fma_f32 v[238:239], v[212:213], s[90:91], 1.0 op_sel_hi:[1,0,0]
	v_pk_fma_f32 v[172:173], v[170:171], s[90:91], 1.0 op_sel_hi:[1,0,0]
	v_pk_mul_f32 v[168:169], v[80:81], v[80:81]
	v_pk_mul_f32 v[208:209], v[82:83], v[82:83]
	v_rcp_f32_e32 v238, v238
	v_rcp_f32_e32 v239, v239
	v_rcp_f32_e32 v172, v172
	v_rcp_f32_e32 v173, v173
	v_pk_mul_f32 v[168:169], v[168:169], s[44:45] op_sel_hi:[1,0]
	v_pk_mul_f32 v[208:209], v[208:209], s[44:45] op_sel_hi:[1,0]
	v_pk_fma_f32 v[246:247], v[238:239], s[92:93], v[236:237] op_sel_hi:[1,0,0]
	v_pk_fma_f32 v[174:175], v[172:173], s[92:93], v[236:237] op_sel_hi:[1,0,0]
	v_exp_f32_e32 v168, v168
	v_exp_f32_e32 v169, v169
	v_exp_f32_e32 v208, v208
	v_exp_f32_e32 v209, v209
	v_pk_fma_f32 v[246:247], v[238:239], v[246:247], s[96:97] op_sel_hi:[1,1,0]
	v_pk_fma_f32 v[174:175], v[172:173], v[174:175], s[96:97] op_sel_hi:[1,1,0]
	v_pk_fma_f32 v[246:247], v[238:239], v[246:247], s[0:1] op_sel_hi:[1,1,0]
	v_pk_fma_f32 v[174:175], v[172:173], v[174:175], s[0:1] op_sel_hi:[1,1,0]
	v_pk_fma_f32 v[246:247], v[238:239], v[246:247], s[4:5] op_sel_hi:[1,1,0]
	v_pk_fma_f32 v[174:175], v[172:173], v[174:175], s[4:5] op_sel_hi:[1,1,0]
	v_pk_mul_f32 v[246:247], v[238:239], v[246:247]
	v_pk_mul_f32 v[174:175], v[172:173], v[174:175]
	v_max_f32_e32 v238, 0, v80
	v_max_f32_e32 v239, 0, v81
	v_max_f32_e32 v172, 0, v82
	v_max_f32_e32 v173, 0, v83
	v_pk_mul_f32 v[246:247], v[168:169], v[246:247]
	v_pk_mul_f32 v[174:175], v[208:209], v[174:175]
	v_pk_fma_f32 v[168:169], v[212:213], v[246:247], v[238:239] neg_lo:[1,0,0] neg_hi:[1,0,0]
	v_pk_fma_f32 v[208:209], v[170:171], v[174:175], v[172:173] neg_lo:[1,0,0] neg_hi:[1,0,0]
	v_pk_mul_f32 v[246:247], v[168:169], v[68:69]
	v_pk_mul_f32 v[174:175], v[208:209], v[70:71]
	v_cvt_pk_bf16_f32 v164, v246, v247
	v_cvt_pk_bf16_f32 v165, v174, v175
	ds_read_b128 v[4:7], v231 offset:16
	ds_read_b128 v[32:35], v231 offset:528
	ds_read_b128 v[68:71], v233 offset:16
	ds_read_b128 v[80:83], v233 offset:528
	s_waitcnt lgkmcnt(0)
	v_mov_b32_dpp v4, v16 row_shr:1 row_mask:0xf bank_mask:0xf
	v_mov_b32_dpp v5, v17 row_shr:1 row_mask:0xf bank_mask:0xf
	v_mov_b32_dpp v6, v18 row_shr:1 row_mask:0xf bank_mask:0xf
	v_mov_b32_dpp v7, v19 row_shr:1 row_mask:0xf bank_mask:0xf
	v_mov_b32_dpp v32, v20 row_shr:1 row_mask:0xf bank_mask:0xf
	v_mov_b32_dpp v33, v21 row_shr:1 row_mask:0xf bank_mask:0xf
	v_mov_b32_dpp v34, v22 row_shr:1 row_mask:0xf bank_mask:0xf
	v_mov_b32_dpp v35, v23 row_shr:1 row_mask:0xf bank_mask:0xf
	v_mov_b32_dpp v68, v24 row_shl:1 row_mask:0xf bank_mask:0xf
	v_mov_b32_dpp v69, v25 row_shl:1 row_mask:0xf bank_mask:0xf
	v_mov_b32_dpp v70, v26 row_shl:1 row_mask:0xf bank_mask:0xf
	v_mov_b32_dpp v71, v27 row_shl:1 row_mask:0xf bank_mask:0xf
	v_mov_b32_dpp v80, v28 row_shl:1 row_mask:0xf bank_mask:0xf
	v_mov_b32_dpp v81, v29 row_shl:1 row_mask:0xf bank_mask:0xf
	v_mov_b32_dpp v82, v30 row_shl:1 row_mask:0xf bank_mask:0xf
	v_mov_b32_dpp v83, v31 row_shl:1 row_mask:0xf bank_mask:0xf
	v_mov_b32_e32 v235, v228
	v_cmp_gt_i32_e32 vcc, 0x4000, v235
	s_nop 1
	v_cndmask_b32_e32 v245, v222, v221, vcc
	v_and_b32_e32 v235, v235, v245
	v_cmp_eq_u32_e64 s[34:35], 0, v235
	v_cmp_eq_u32_e64 s[36:37], v235, v245
	s_nop 1
	v_cndmask_b32_e64 v4, v4, 0, s[34:35]
	v_cndmask_b32_e64 v5, v5, 0, s[34:35]
	v_cndmask_b32_e64 v6, v6, 0, s[34:35]
	v_cndmask_b32_e64 v7, v7, 0, s[34:35]
	v_cndmask_b32_e64 v32, v32, 0, s[34:35]
	v_cndmask_b32_e64 v33, v33, 0, s[34:35]
	v_cndmask_b32_e64 v34, v34, 0, s[34:35]
	v_cndmask_b32_e64 v35, v35, 0, s[34:35]
	v_pk_fma_f32 v[4:5], v[40:41], v[4:5], v[152:153]
	v_pk_fma_f32 v[6:7], v[42:43], v[6:7], v[154:155]
	v_pk_fma_f32 v[32:33], v[60:61], v[32:33], v[156:157]
	v_pk_fma_f32 v[34:35], v[62:63], v[34:35], v[158:159]
	v_pk_fma_f32 v[4:5], v[24:25], v[84:85], v[4:5]
	v_pk_fma_f32 v[6:7], v[26:27], v[86:87], v[6:7]
	v_pk_fma_f32 v[32:33], v[28:29], v[92:93], v[32:33]
	v_pk_fma_f32 v[34:35], v[30:31], v[94:95], v[34:35]
	s_mov_b64 s[30:31], exec
	s_andn2_b64 exec, exec, s[36:37]
	v_pk_fma_f32 v[4:5], v[124:125], v[120:121], v[4:5]
	v_pk_fma_f32 v[6:7], v[126:127], v[122:123], v[6:7]
	v_pk_fma_f32 v[32:33], v[132:133], v[108:109], v[32:33]
	v_pk_fma_f32 v[34:35], v[134:135], v[110:111], v[34:35]
	s_mov_b64 exec, s[30:31]
	v_and_b32_e32 v212, 0x7fffffff, v4
	v_and_b32_e32 v213, 0x7fffffff, v5
	v_and_b32_e32 v102, 0x7fffffff, v6
	v_and_b32_e32 v103, 0x7fffffff, v7
	v_pk_fma_f32 v[238:239], v[212:213], s[90:91], 1.0 op_sel_hi:[1,0,0]
	v_pk_fma_f32 v[112:113], v[102:103], s[90:91], 1.0 op_sel_hi:[1,0,0]
	v_pk_mul_f32 v[100:101], v[4:5], v[4:5]
	v_pk_mul_f32 v[168:169], v[6:7], v[6:7]
	v_rcp_f32_e32 v238, v238
	v_rcp_f32_e32 v239, v239
	v_rcp_f32_e32 v112, v112
	v_rcp_f32_e32 v113, v113
	v_pk_mul_f32 v[100:101], v[100:101], s[44:45] op_sel_hi:[1,0]
	v_pk_mul_f32 v[168:169], v[168:169], s[44:45] op_sel_hi:[1,0]
	v_pk_fma_f32 v[246:247], v[238:239], s[92:93], v[236:237] op_sel_hi:[1,0,0]
	v_pk_fma_f32 v[114:115], v[112:113], s[92:93], v[236:237] op_sel_hi:[1,0,0]
	v_exp_f32_e32 v100, v100
	v_exp_f32_e32 v101, v101
	v_exp_f32_e32 v168, v168
	v_exp_f32_e32 v169, v169
	v_pk_fma_f32 v[246:247], v[238:239], v[246:247], s[96:97] op_sel_hi:[1,1,0]
	v_pk_fma_f32 v[114:115], v[112:113], v[114:115], s[96:97] op_sel_hi:[1,1,0]
	v_pk_fma_f32 v[246:247], v[238:239], v[246:247], s[0:1] op_sel_hi:[1,1,0]
	v_pk_fma_f32 v[114:115], v[112:113], v[114:115], s[0:1] op_sel_hi:[1,1,0]
	v_pk_fma_f32 v[246:247], v[238:239], v[246:247], s[4:5] op_sel_hi:[1,1,0]
	v_pk_fma_f32 v[114:115], v[112:113], v[114:115], s[4:5] op_sel_hi:[1,1,0]
	v_pk_mul_f32 v[246:247], v[238:239], v[246:247]
	v_pk_mul_f32 v[114:115], v[112:113], v[114:115]
	v_max_f32_e32 v238, 0, v4
	v_max_f32_e32 v239, 0, v5
	v_max_f32_e32 v112, 0, v6
	v_max_f32_e32 v113, 0, v7
	v_pk_mul_f32 v[246:247], v[100:101], v[246:247]
	v_pk_mul_f32 v[114:115], v[168:169], v[114:115]
	v_pk_fma_f32 v[100:101], v[212:213], v[246:247], v[238:239] neg_lo:[1,0,0] neg_hi:[1,0,0]
	v_pk_fma_f32 v[168:169], v[102:103], v[114:115], v[112:113] neg_lo:[1,0,0] neg_hi:[1,0,0]
	v_pk_mul_f32 v[246:247], v[100:101], v[32:33]
	v_pk_mul_f32 v[114:115], v[168:169], v[34:35]
	v_cvt_pk_bf16_f32 v162, v246, v247
	v_cvt_pk_bf16_f32 v163, v114, v115
	v_add_u32_e32 v235, -1, v227
	v_mov_b32_e32 v245, v228
	v_cmp_gt_u32_e64 s[38:39], s64, v235
	v_cmp_gt_u32_e32 vcc, s88, v245
	v_mov_b32_e32 v235, v230
	s_and_b64 s[38:39], s[38:39], vcc
	s_and_saveexec_b64 s[30:31], s[38:39]
	global_store_dwordx4 v235, v[160:163], s[50:51]
	s_mov_b64 exec, s[30:31]
	s_nop 1
	v_add_u32_e32 v235, 1, v228
	v_cmp_gt_i32_e32 vcc, 0x4000, v235
	s_nop 1
	v_cndmask_b32_e32 v245, v222, v221, vcc
	v_and_b32_e32 v235, v235, v245
	v_cmp_eq_u32_e64 s[34:35], 0, v235
	v_cmp_eq_u32_e64 s[36:37], v235, v245
	s_nop 1
	v_cndmask_b32_e64 v24, v24, 0, s[34:35]
	v_cndmask_b32_e64 v25, v25, 0, s[34:35]
	v_cndmask_b32_e64 v26, v26, 0, s[34:35]
	v_cndmask_b32_e64 v27, v27, 0, s[34:35]
	v_cndmask_b32_e64 v28, v28, 0, s[34:35]
	v_cndmask_b32_e64 v29, v29, 0, s[34:35]
	v_cndmask_b32_e64 v30, v30, 0, s[34:35]
	v_cndmask_b32_e64 v31, v31, 0, s[34:35]
	v_pk_fma_f32 v[24:25], v[40:41], v[24:25], v[152:153]
	v_pk_fma_f32 v[26:27], v[42:43], v[26:27], v[154:155]
	v_pk_fma_f32 v[28:29], v[60:61], v[28:29], v[156:157]
	v_pk_fma_f32 v[30:31], v[62:63], v[30:31], v[158:159]
	v_pk_fma_f32 v[24:25], v[120:121], v[84:85], v[24:25]
	v_pk_fma_f32 v[26:27], v[122:123], v[86:87], v[26:27]
	v_pk_fma_f32 v[28:29], v[108:109], v[92:93], v[28:29]
	v_pk_fma_f32 v[30:31], v[110:111], v[94:95], v[30:31]
	s_mov_b64 s[30:31], exec
	s_andn2_b64 exec, exec, s[36:37]
	v_pk_fma_f32 v[24:25], v[124:125], v[104:105], v[24:25]
	v_pk_fma_f32 v[26:27], v[126:127], v[106:107], v[26:27]
	v_pk_fma_f32 v[28:29], v[132:133], v[96:97], v[28:29]
	v_pk_fma_f32 v[30:31], v[134:135], v[98:99], v[30:31]
	s_mov_b64 exec, s[30:31]
	v_and_b32_e32 v212, 0x7fffffff, v24
	v_and_b32_e32 v213, 0x7fffffff, v25
	v_and_b32_e32 v6, 0x7fffffff, v26
	v_and_b32_e32 v7, 0x7fffffff, v27
	v_pk_fma_f32 v[238:239], v[212:213], s[90:91], 1.0 op_sel_hi:[1,0,0]
	v_pk_fma_f32 v[32:33], v[6:7], s[90:91], 1.0 op_sel_hi:[1,0,0]
	v_pk_mul_f32 v[4:5], v[24:25], v[24:25]
	v_pk_mul_f32 v[100:101], v[26:27], v[26:27]
	v_rcp_f32_e32 v238, v238
	v_rcp_f32_e32 v239, v239
	v_rcp_f32_e32 v32, v32
	v_rcp_f32_e32 v33, v33
	v_pk_mul_f32 v[4:5], v[4:5], s[44:45] op_sel_hi:[1,0]
	v_pk_mul_f32 v[100:101], v[100:101], s[44:45] op_sel_hi:[1,0]
	v_pk_fma_f32 v[246:247], v[238:239], s[92:93], v[236:237] op_sel_hi:[1,0,0]
	v_pk_fma_f32 v[34:35], v[32:33], s[92:93], v[236:237] op_sel_hi:[1,0,0]
	v_exp_f32_e32 v4, v4
	v_exp_f32_e32 v5, v5
	v_exp_f32_e32 v100, v100
	v_exp_f32_e32 v101, v101
	v_pk_fma_f32 v[246:247], v[238:239], v[246:247], s[96:97] op_sel_hi:[1,1,0]
	v_pk_fma_f32 v[34:35], v[32:33], v[34:35], s[96:97] op_sel_hi:[1,1,0]
	v_pk_fma_f32 v[246:247], v[238:239], v[246:247], s[0:1] op_sel_hi:[1,1,0]
	v_pk_fma_f32 v[34:35], v[32:33], v[34:35], s[0:1] op_sel_hi:[1,1,0]
	v_pk_fma_f32 v[246:247], v[238:239], v[246:247], s[4:5] op_sel_hi:[1,1,0]
	v_pk_fma_f32 v[34:35], v[32:33], v[34:35], s[4:5] op_sel_hi:[1,1,0]
	v_pk_mul_f32 v[246:247], v[238:239], v[246:247]
	v_pk_mul_f32 v[34:35], v[32:33], v[34:35]
	v_max_f32_e32 v238, 0, v24
	v_max_f32_e32 v239, 0, v25
	v_max_f32_e32 v32, 0, v26
	v_max_f32_e32 v33, 0, v27
	v_pk_mul_f32 v[246:247], v[4:5], v[246:247]
	v_pk_mul_f32 v[34:35], v[100:101], v[34:35]
	v_pk_fma_f32 v[4:5], v[212:213], v[246:247], v[238:239] neg_lo:[1,0,0] neg_hi:[1,0,0]
	v_pk_fma_f32 v[100:101], v[6:7], v[34:35], v[32:33] neg_lo:[1,0,0] neg_hi:[1,0,0]
	v_pk_mul_f32 v[246:247], v[4:5], v[28:29]
	v_pk_mul_f32 v[34:35], v[100:101], v[30:31]
	v_cvt_pk_bf16_f32 v58, v246, v247
	v_cvt_pk_bf16_f32 v59, v34, v35
	v_add_u32_e32 v235, 0, v227
	v_add_u32_e32 v245, 1, v228
	v_cmp_gt_u32_e64 s[38:39], s64, v235
	v_cmp_gt_u32_e32 vcc, s88, v245
	v_add_u32_e32 v235, 5632, v230
	s_and_b64 s[38:39], s[38:39], vcc
	s_and_saveexec_b64 s[30:31], s[38:39]
	global_store_dwordx4 v235, v[56:59], s[50:51]
	s_mov_b64 exec, s[30:31]
	s_nop 1
	v_add_u32_e32 v235, 2, v228
	v_cmp_gt_i32_e32 vcc, 0x4000, v235
	s_nop 1
	v_cndmask_b32_e32 v245, v222, v221, vcc
	v_and_b32_e32 v235, v235, v245
	v_cmp_eq_u32_e64 s[34:35], 0, v235
	v_cmp_eq_u32_e64 s[36:37], v235, v245
	s_nop 1
	v_cndmask_b32_e64 v120, v120, 0, s[34:35]
	v_cndmask_b32_e64 v121, v121, 0, s[34:35]
	v_cndmask_b32_e64 v122, v122, 0, s[34:35]
	v_cndmask_b32_e64 v123, v123, 0, s[34:35]
	v_cndmask_b32_e64 v108, v108, 0, s[34:35]
	v_cndmask_b32_e64 v109, v109, 0, s[34:35]
	v_cndmask_b32_e64 v110, v110, 0, s[34:35]
	v_cndmask_b32_e64 v111, v111, 0, s[34:35]
	v_pk_fma_f32 v[120:121], v[40:41], v[120:121], v[152:153]
	v_pk_fma_f32 v[122:123], v[42:43], v[122:123], v[154:155]
	v_pk_fma_f32 v[108:109], v[60:61], v[108:109], v[156:157]
	v_pk_fma_f32 v[110:111], v[62:63], v[110:111], v[158:159]
	v_pk_fma_f32 v[120:121], v[104:105], v[84:85], v[120:121]
	v_pk_fma_f32 v[122:123], v[106:107], v[86:87], v[122:123]
	v_pk_fma_f32 v[108:109], v[96:97], v[92:93], v[108:109]
	v_pk_fma_f32 v[110:111], v[98:99], v[94:95], v[110:111]
	s_mov_b64 s[30:31], exec
	s_andn2_b64 exec, exec, s[36:37]
	v_pk_fma_f32 v[120:121], v[124:125], v[16:17], v[120:121]
	v_pk_fma_f32 v[122:123], v[126:127], v[18:19], v[122:123]
	v_pk_fma_f32 v[108:109], v[132:133], v[20:21], v[108:109]
	v_pk_fma_f32 v[110:111], v[134:135], v[22:23], v[110:111]
	s_mov_b64 exec, s[30:31]
	v_and_b32_e32 v212, 0x7fffffff, v120
	v_and_b32_e32 v213, 0x7fffffff, v121
	v_and_b32_e32 v6, 0x7fffffff, v122
	v_and_b32_e32 v7, 0x7fffffff, v123
	v_pk_fma_f32 v[238:239], v[212:213], s[90:91], 1.0 op_sel_hi:[1,0,0]
	v_pk_fma_f32 v[24:25], v[6:7], s[90:91], 1.0 op_sel_hi:[1,0,0]
	v_pk_mul_f32 v[4:5], v[120:121], v[120:121]
	v_pk_mul_f32 v[28:29], v[122:123], v[122:123]
	v_rcp_f32_e32 v238, v238
	v_rcp_f32_e32 v239, v239
	v_rcp_f32_e32 v24, v24
	v_rcp_f32_e32 v25, v25
	v_pk_mul_f32 v[4:5], v[4:5], s[44:45] op_sel_hi:[1,0]
	v_pk_mul_f32 v[28:29], v[28:29], s[44:45] op_sel_hi:[1,0]
	v_pk_fma_f32 v[246:247], v[238:239], s[92:93], v[236:237] op_sel_hi:[1,0,0]
	v_pk_fma_f32 v[26:27], v[24:25], s[92:93], v[236:237] op_sel_hi:[1,0,0]
	v_exp_f32_e32 v4, v4
	v_exp_f32_e32 v5, v5
	v_exp_f32_e32 v28, v28
	v_exp_f32_e32 v29, v29
	v_pk_fma_f32 v[246:247], v[238:239], v[246:247], s[96:97] op_sel_hi:[1,1,0]
	v_pk_fma_f32 v[26:27], v[24:25], v[26:27], s[96:97] op_sel_hi:[1,1,0]
	v_pk_fma_f32 v[246:247], v[238:239], v[246:247], s[0:1] op_sel_hi:[1,1,0]
	v_pk_fma_f32 v[26:27], v[24:25], v[26:27], s[0:1] op_sel_hi:[1,1,0]
	v_pk_fma_f32 v[246:247], v[238:239], v[246:247], s[4:5] op_sel_hi:[1,1,0]
	v_pk_fma_f32 v[26:27], v[24:25], v[26:27], s[4:5] op_sel_hi:[1,1,0]
	v_pk_mul_f32 v[246:247], v[238:239], v[246:247]
	v_pk_mul_f32 v[26:27], v[24:25], v[26:27]
	v_max_f32_e32 v238, 0, v120
	v_max_f32_e32 v239, 0, v121
	v_max_f32_e32 v24, 0, v122
	v_max_f32_e32 v25, 0, v123
	v_pk_mul_f32 v[246:247], v[4:5], v[246:247]
	v_pk_mul_f32 v[26:27], v[28:29], v[26:27]
	v_pk_fma_f32 v[4:5], v[212:213], v[246:247], v[238:239] neg_lo:[1,0,0] neg_hi:[1,0,0]
	v_pk_fma_f32 v[28:29], v[6:7], v[26:27], v[24:25] neg_lo:[1,0,0] neg_hi:[1,0,0]
	v_pk_mul_f32 v[246:247], v[4:5], v[108:109]
	v_pk_mul_f32 v[26:27], v[28:29], v[110:111]
	v_cvt_pk_bf16_f32 v50, v246, v247
	v_cvt_pk_bf16_f32 v51, v26, v27
	v_add_u32_e32 v235, 1, v227
	v_add_u32_e32 v245, 2, v228
	v_cmp_gt_u32_e64 s[38:39], s64, v235
	v_cmp_gt_u32_e32 vcc, s88, v245
	v_add_u32_e32 v235, 11264, v230
	s_and_b64 s[38:39], s[38:39], vcc
	s_and_saveexec_b64 s[30:31], s[38:39]
	global_store_dwordx4 v235, v[48:51], s[50:51]
	s_mov_b64 exec, s[30:31]
	s_nop 1
	v_add_u32_e32 v235, 3, v228
	v_cmp_gt_i32_e32 vcc, 0x4000, v235
	s_nop 1
	v_cndmask_b32_e32 v245, v222, v221, vcc
	v_and_b32_e32 v235, v235, v245
	v_cmp_eq_u32_e64 s[34:35], 0, v235
	v_cmp_eq_u32_e64 s[36:37], v235, v245
	s_nop 1
	v_cndmask_b32_e64 v104, v104, 0, s[34:35]
	v_cndmask_b32_e64 v105, v105, 0, s[34:35]
	v_cndmask_b32_e64 v106, v106, 0, s[34:35]
	v_cndmask_b32_e64 v107, v107, 0, s[34:35]
	v_cndmask_b32_e64 v96, v96, 0, s[34:35]
	v_cndmask_b32_e64 v97, v97, 0, s[34:35]
	v_cndmask_b32_e64 v98, v98, 0, s[34:35]
	v_cndmask_b32_e64 v99, v99, 0, s[34:35]
	v_pk_fma_f32 v[104:105], v[40:41], v[104:105], v[152:153]
	v_pk_fma_f32 v[106:107], v[42:43], v[106:107], v[154:155]
	v_pk_fma_f32 v[96:97], v[60:61], v[96:97], v[156:157]
	v_pk_fma_f32 v[98:99], v[62:63], v[98:99], v[158:159]
	v_pk_fma_f32 v[104:105], v[16:17], v[84:85], v[104:105]
	v_pk_fma_f32 v[106:107], v[18:19], v[86:87], v[106:107]
	v_pk_fma_f32 v[96:97], v[20:21], v[92:93], v[96:97]
	v_pk_fma_f32 v[98:99], v[22:23], v[94:95], v[98:99]
	s_mov_b64 s[30:31], exec
	s_andn2_b64 exec, exec, s[36:37]
	v_pk_fma_f32 v[104:105], v[124:125], v[68:69], v[104:105]
	v_pk_fma_f32 v[106:107], v[126:127], v[70:71], v[106:107]
	v_pk_fma_f32 v[96:97], v[132:133], v[80:81], v[96:97]
	v_pk_fma_f32 v[98:99], v[134:135], v[82:83], v[98:99]
	s_mov_b64 exec, s[30:31]
	v_and_b32_e32 v212, 0x7fffffff, v104
	v_and_b32_e32 v213, 0x7fffffff, v105
	v_and_b32_e32 v6, 0x7fffffff, v106
	v_and_b32_e32 v7, 0x7fffffff, v107
	v_pk_fma_f32 v[238:239], v[212:213], s[90:91], 1.0 op_sel_hi:[1,0,0]
	v_pk_fma_f32 v[24:25], v[6:7], s[90:91], 1.0 op_sel_hi:[1,0,0]
	v_pk_mul_f32 v[4:5], v[104:105], v[104:105]
	v_pk_mul_f32 v[28:29], v[106:107], v[106:107]
	v_rcp_f32_e32 v238, v238
	v_rcp_f32_e32 v239, v239
	v_rcp_f32_e32 v24, v24
	v_rcp_f32_e32 v25, v25
	v_pk_mul_f32 v[4:5], v[4:5], s[44:45] op_sel_hi:[1,0]
	v_pk_mul_f32 v[28:29], v[28:29], s[44:45] op_sel_hi:[1,0]
	v_pk_fma_f32 v[246:247], v[238:239], s[92:93], v[236:237] op_sel_hi:[1,0,0]
	v_pk_fma_f32 v[26:27], v[24:25], s[92:93], v[236:237] op_sel_hi:[1,0,0]
	v_exp_f32_e32 v4, v4
	v_exp_f32_e32 v5, v5
	v_exp_f32_e32 v28, v28
	v_exp_f32_e32 v29, v29
	v_pk_fma_f32 v[246:247], v[238:239], v[246:247], s[96:97] op_sel_hi:[1,1,0]
	v_pk_fma_f32 v[26:27], v[24:25], v[26:27], s[96:97] op_sel_hi:[1,1,0]
	v_pk_fma_f32 v[246:247], v[238:239], v[246:247], s[0:1] op_sel_hi:[1,1,0]
	v_pk_fma_f32 v[26:27], v[24:25], v[26:27], s[0:1] op_sel_hi:[1,1,0]
	v_pk_fma_f32 v[246:247], v[238:239], v[246:247], s[4:5] op_sel_hi:[1,1,0]
	v_pk_fma_f32 v[26:27], v[24:25], v[26:27], s[4:5] op_sel_hi:[1,1,0]
	v_pk_mul_f32 v[246:247], v[238:239], v[246:247]
	v_pk_mul_f32 v[26:27], v[24:25], v[26:27]
	v_max_f32_e32 v238, 0, v104
	v_max_f32_e32 v239, 0, v105
	v_max_f32_e32 v24, 0, v106
	v_max_f32_e32 v25, 0, v107
	v_pk_mul_f32 v[246:247], v[4:5], v[246:247]
	v_pk_mul_f32 v[26:27], v[28:29], v[26:27]
	v_pk_fma_f32 v[4:5], v[212:213], v[246:247], v[238:239] neg_lo:[1,0,0] neg_hi:[1,0,0]
	v_pk_fma_f32 v[28:29], v[6:7], v[26:27], v[24:25] neg_lo:[1,0,0] neg_hi:[1,0,0]
	v_pk_mul_f32 v[246:247], v[4:5], v[96:97]
	v_pk_mul_f32 v[26:27], v[28:29], v[98:99]
	v_cvt_pk_bf16_f32 v54, v246, v247
	v_cvt_pk_bf16_f32 v55, v26, v27
	v_add_u32_e32 v235, 2, v227
	v_add_u32_e32 v245, 3, v228
	v_cmp_gt_u32_e64 s[38:39], s64, v235
	v_cmp_gt_u32_e32 vcc, s88, v245
	v_add_u32_e32 v235, 16896, v230
	s_and_b64 s[38:39], s[38:39], vcc
	s_and_saveexec_b64 s[30:31], s[38:39]
	global_store_dwordx4 v235, v[52:55], s[50:51]
	s_mov_b64 exec, s[30:31]
	s_nop 1
	ds_read_b128 v[4:7], v232 offset:16
	ds_read_b128 v[16:19], v232 offset:528
	ds_read_b128 v[20:23], v234 offset:16
	ds_read_b128 v[24:27], v234 offset:528
	s_waitcnt lgkmcnt(0)
	v_mov_b32_dpp v4, v0 row_shr:1 row_mask:0xf bank_mask:0xf
	v_mov_b32_dpp v5, v1 row_shr:1 row_mask:0xf bank_mask:0xf
	v_mov_b32_dpp v6, v2 row_shr:1 row_mask:0xf bank_mask:0xf
	v_mov_b32_dpp v7, v3 row_shr:1 row_mask:0xf bank_mask:0xf
	v_mov_b32_dpp v16, v128 row_shr:1 row_mask:0xf bank_mask:0xf
	v_mov_b32_dpp v17, v129 row_shr:1 row_mask:0xf bank_mask:0xf
	v_mov_b32_dpp v18, v130 row_shr:1 row_mask:0xf bank_mask:0xf
	v_mov_b32_dpp v19, v131 row_shr:1 row_mask:0xf bank_mask:0xf
	v_mov_b32_dpp v20, v8 row_shl:1 row_mask:0xf bank_mask:0xf
	v_mov_b32_dpp v21, v9 row_shl:1 row_mask:0xf bank_mask:0xf
	v_mov_b32_dpp v22, v10 row_shl:1 row_mask:0xf bank_mask:0xf
	v_mov_b32_dpp v23, v11 row_shl:1 row_mask:0xf bank_mask:0xf
	v_mov_b32_dpp v24, v36 row_shl:1 row_mask:0xf bank_mask:0xf
	v_mov_b32_dpp v25, v37 row_shl:1 row_mask:0xf bank_mask:0xf
	v_mov_b32_dpp v26, v38 row_shl:1 row_mask:0xf bank_mask:0xf
	v_mov_b32_dpp v27, v39 row_shl:1 row_mask:0xf bank_mask:0xf
	v_add_u32_e32 v235, 128, v228
	v_cmp_gt_i32_e32 vcc, 0x4000, v235
	s_nop 1
	v_cndmask_b32_e32 v245, v222, v221, vcc
	v_and_b32_e32 v235, v235, v245
	v_cmp_eq_u32_e64 s[34:35], 0, v235
	v_cmp_eq_u32_e64 s[36:37], v235, v245
	s_nop 1
	v_cndmask_b32_e64 v4, v4, 0, s[34:35]
	v_cndmask_b32_e64 v5, v5, 0, s[34:35]
	v_cndmask_b32_e64 v6, v6, 0, s[34:35]
	v_cndmask_b32_e64 v7, v7, 0, s[34:35]
	v_cndmask_b32_e64 v16, v16, 0, s[34:35]
	v_cndmask_b32_e64 v17, v17, 0, s[34:35]
	v_cndmask_b32_e64 v18, v18, 0, s[34:35]
	v_cndmask_b32_e64 v19, v19, 0, s[34:35]
	v_pk_fma_f32 v[4:5], v[40:41], v[4:5], v[152:153]
	v_pk_fma_f32 v[6:7], v[42:43], v[6:7], v[154:155]
	v_pk_fma_f32 v[16:17], v[60:61], v[16:17], v[156:157]
	v_pk_fma_f32 v[18:19], v[62:63], v[18:19], v[158:159]
	v_pk_fma_f32 v[4:5], v[8:9], v[84:85], v[4:5]
	v_pk_fma_f32 v[6:7], v[10:11], v[86:87], v[6:7]
	v_pk_fma_f32 v[16:17], v[36:37], v[92:93], v[16:17]
	v_pk_fma_f32 v[18:19], v[38:39], v[94:95], v[18:19]
	s_mov_b64 s[30:31], exec
	s_andn2_b64 exec, exec, s[36:37]
	v_pk_fma_f32 v[4:5], v[124:125], v[88:89], v[4:5]
	v_pk_fma_f32 v[6:7], v[126:127], v[90:91], v[6:7]
	v_pk_fma_f32 v[16:17], v[132:133], v[76:77], v[16:17]
	v_pk_fma_f32 v[18:19], v[134:135], v[78:79], v[18:19]
	s_mov_b64 exec, s[30:31]
	v_and_b32_e32 v212, 0x7fffffff, v4
	v_and_b32_e32 v213, 0x7fffffff, v5
	v_and_b32_e32 v30, 0x7fffffff, v6
	v_and_b32_e32 v31, 0x7fffffff, v7
	v_pk_fma_f32 v[238:239], v[212:213], s[90:91], 1.0 op_sel_hi:[1,0,0]
	v_pk_fma_f32 v[32:33], v[30:31], s[90:91], 1.0 op_sel_hi:[1,0,0]
	v_pk_mul_f32 v[28:29], v[4:5], v[4:5]
	v_pk_mul_f32 v[48:49], v[6:7], v[6:7]
	v_rcp_f32_e32 v238, v238
	v_rcp_f32_e32 v239, v239
	v_rcp_f32_e32 v32, v32
	v_rcp_f32_e32 v33, v33
	v_pk_mul_f32 v[28:29], v[28:29], s[44:45] op_sel_hi:[1,0]
	v_pk_mul_f32 v[48:49], v[48:49], s[44:45] op_sel_hi:[1,0]
	v_pk_fma_f32 v[246:247], v[238:239], s[92:93], v[236:237] op_sel_hi:[1,0,0]
	v_pk_fma_f32 v[34:35], v[32:33], s[92:93], v[236:237] op_sel_hi:[1,0,0]
	v_exp_f32_e32 v28, v28
	v_exp_f32_e32 v29, v29
	v_exp_f32_e32 v48, v48
	v_exp_f32_e32 v49, v49
	v_pk_fma_f32 v[246:247], v[238:239], v[246:247], s[96:97] op_sel_hi:[1,1,0]
	v_pk_fma_f32 v[34:35], v[32:33], v[34:35], s[96:97] op_sel_hi:[1,1,0]
	v_pk_fma_f32 v[246:247], v[238:239], v[246:247], s[0:1] op_sel_hi:[1,1,0]
	v_pk_fma_f32 v[34:35], v[32:33], v[34:35], s[0:1] op_sel_hi:[1,1,0]
	v_pk_fma_f32 v[246:247], v[238:239], v[246:247], s[4:5] op_sel_hi:[1,1,0]
	v_pk_fma_f32 v[34:35], v[32:33], v[34:35], s[4:5] op_sel_hi:[1,1,0]
	v_pk_mul_f32 v[246:247], v[238:239], v[246:247]
	v_pk_mul_f32 v[34:35], v[32:33], v[34:35]
	v_max_f32_e32 v238, 0, v4
	v_max_f32_e32 v239, 0, v5
	v_max_f32_e32 v32, 0, v6
	v_max_f32_e32 v33, 0, v7
	v_pk_mul_f32 v[246:247], v[28:29], v[246:247]
	v_pk_mul_f32 v[34:35], v[48:49], v[34:35]
	v_pk_fma_f32 v[28:29], v[212:213], v[246:247], v[238:239] neg_lo:[1,0,0] neg_hi:[1,0,0]
	v_pk_fma_f32 v[48:49], v[30:31], v[34:35], v[32:33] neg_lo:[1,0,0] neg_hi:[1,0,0]
	v_pk_mul_f32 v[246:247], v[28:29], v[16:17]
	v_pk_mul_f32 v[34:35], v[48:49], v[18:19]
	v_cvt_pk_bf16_f32 v118, v246, v247
	v_cvt_pk_bf16_f32 v119, v34, v35
	v_add_u32_e32 v235, 127, v227
	v_add_u32_e32 v245, 128, v228
	v_cmp_gt_u32_e64 s[38:39], s64, v235
	v_cmp_gt_u32_e32 vcc, s88, v245
	v_add_u32_e32 v235, 720896, v230
	s_and_b64 s[38:39], s[38:39], vcc
	s_and_saveexec_b64 s[30:31], s[38:39]
	global_store_dwordx4 v235, v[116:119], s[50:51]
	s_mov_b64 exec, s[30:31]
	s_nop 1
	v_add_u32_e32 v235, 129, v228
	v_cmp_gt_i32_e32 vcc, 0x4000, v235
	s_nop 1
	v_cndmask_b32_e32 v245, v222, v221, vcc
	v_and_b32_e32 v235, v235, v245
	v_cmp_eq_u32_e64 s[34:35], 0, v235
	v_cmp_eq_u32_e64 s[36:37], v235, v245
	s_nop 1
	v_cndmask_b32_e64 v8, v8, 0, s[34:35]
	v_cndmask_b32_e64 v9, v9, 0, s[34:35]
	v_cndmask_b32_e64 v10, v10, 0, s[34:35]
	v_cndmask_b32_e64 v11, v11, 0, s[34:35]
	v_cndmask_b32_e64 v36, v36, 0, s[34:35]
	v_cndmask_b32_e64 v37, v37, 0, s[34:35]
	v_cndmask_b32_e64 v38, v38, 0, s[34:35]
	v_cndmask_b32_e64 v39, v39, 0, s[34:35]
	v_pk_fma_f32 v[8:9], v[40:41], v[8:9], v[152:153]
	v_pk_fma_f32 v[10:11], v[42:43], v[10:11], v[154:155]
	v_pk_fma_f32 v[36:37], v[60:61], v[36:37], v[156:157]
	v_pk_fma_f32 v[38:39], v[62:63], v[38:39], v[158:159]
	v_pk_fma_f32 v[8:9], v[88:89], v[84:85], v[8:9]
	v_pk_fma_f32 v[10:11], v[90:91], v[86:87], v[10:11]
	v_pk_fma_f32 v[36:37], v[76:77], v[92:93], v[36:37]
	v_pk_fma_f32 v[38:39], v[78:79], v[94:95], v[38:39]
	s_mov_b64 s[30:31], exec
	s_andn2_b64 exec, exec, s[36:37]
	v_pk_fma_f32 v[8:9], v[124:125], v[72:73], v[8:9]
	v_pk_fma_f32 v[10:11], v[126:127], v[74:75], v[10:11]
	v_pk_fma_f32 v[36:37], v[132:133], v[64:65], v[36:37]
	v_pk_fma_f32 v[38:39], v[134:135], v[66:67], v[38:39]
	s_mov_b64 exec, s[30:31]
	v_and_b32_e32 v212, 0x7fffffff, v8
	v_and_b32_e32 v213, 0x7fffffff, v9
	v_and_b32_e32 v6, 0x7fffffff, v10
	v_and_b32_e32 v7, 0x7fffffff, v11
	v_pk_fma_f32 v[238:239], v[212:213], s[90:91], 1.0 op_sel_hi:[1,0,0]
	v_pk_fma_f32 v[16:17], v[6:7], s[90:91], 1.0 op_sel_hi:[1,0,0]
	v_pk_mul_f32 v[4:5], v[8:9], v[8:9]
	v_pk_mul_f32 v[28:29], v[10:11], v[10:11]
	v_rcp_f32_e32 v238, v238
	v_rcp_f32_e32 v239, v239
	v_rcp_f32_e32 v16, v16
	v_rcp_f32_e32 v17, v17
	v_pk_mul_f32 v[4:5], v[4:5], s[44:45] op_sel_hi:[1,0]
	v_pk_mul_f32 v[28:29], v[28:29], s[44:45] op_sel_hi:[1,0]
	v_pk_fma_f32 v[246:247], v[238:239], s[92:93], v[236:237] op_sel_hi:[1,0,0]
	v_pk_fma_f32 v[18:19], v[16:17], s[92:93], v[236:237] op_sel_hi:[1,0,0]
	v_exp_f32_e32 v4, v4
	v_exp_f32_e32 v5, v5
	v_exp_f32_e32 v28, v28
	v_exp_f32_e32 v29, v29
	v_pk_fma_f32 v[246:247], v[238:239], v[246:247], s[96:97] op_sel_hi:[1,1,0]
	v_pk_fma_f32 v[18:19], v[16:17], v[18:19], s[96:97] op_sel_hi:[1,1,0]
	v_pk_fma_f32 v[246:247], v[238:239], v[246:247], s[0:1] op_sel_hi:[1,1,0]
	v_pk_fma_f32 v[18:19], v[16:17], v[18:19], s[0:1] op_sel_hi:[1,1,0]
	v_pk_fma_f32 v[246:247], v[238:239], v[246:247], s[4:5] op_sel_hi:[1,1,0]
	v_pk_fma_f32 v[18:19], v[16:17], v[18:19], s[4:5] op_sel_hi:[1,1,0]
	v_pk_mul_f32 v[246:247], v[238:239], v[246:247]
	v_pk_mul_f32 v[18:19], v[16:17], v[18:19]
	v_max_f32_e32 v238, 0, v8
	v_max_f32_e32 v239, 0, v9
	v_max_f32_e32 v16, 0, v10
	v_max_f32_e32 v17, 0, v11
	v_pk_mul_f32 v[246:247], v[4:5], v[246:247]
	v_pk_mul_f32 v[18:19], v[28:29], v[18:19]
	v_pk_fma_f32 v[4:5], v[212:213], v[246:247], v[238:239] neg_lo:[1,0,0] neg_hi:[1,0,0]
	v_pk_fma_f32 v[28:29], v[6:7], v[18:19], v[16:17] neg_lo:[1,0,0] neg_hi:[1,0,0]
	v_pk_mul_f32 v[246:247], v[4:5], v[36:37]
	v_pk_mul_f32 v[18:19], v[28:29], v[38:39]
	v_cvt_pk_bf16_f32 v46, v246, v247
	v_cvt_pk_bf16_f32 v47, v18, v19
	v_add_u32_e32 v235, 128, v227
	v_add_u32_e32 v245, 129, v228
	v_cmp_gt_u32_e64 s[38:39], s64, v235
	v_cmp_gt_u32_e32 vcc, s88, v245
	v_add_u32_e32 v235, 726528, v230
	s_and_b64 s[38:39], s[38:39], vcc
	s_and_saveexec_b64 s[30:31], s[38:39]
	global_store_dwordx4 v235, v[44:47], s[50:51]
	s_mov_b64 exec, s[30:31]
	s_nop 1
	v_add_u32_e32 v235, 130, v228
	v_cmp_gt_i32_e32 vcc, 0x4000, v235
	s_nop 1
	v_cndmask_b32_e32 v245, v222, v221, vcc
	v_and_b32_e32 v235, v235, v245
	v_cmp_eq_u32_e64 s[34:35], 0, v235
	v_cmp_eq_u32_e64 s[36:37], v235, v245
	s_nop 1
	v_cndmask_b32_e64 v88, v88, 0, s[34:35]
	v_cndmask_b32_e64 v89, v89, 0, s[34:35]
	v_cndmask_b32_e64 v90, v90, 0, s[34:35]
	v_cndmask_b32_e64 v91, v91, 0, s[34:35]
	v_cndmask_b32_e64 v76, v76, 0, s[34:35]
	v_cndmask_b32_e64 v77, v77, 0, s[34:35]
	v_cndmask_b32_e64 v78, v78, 0, s[34:35]
	v_cndmask_b32_e64 v79, v79, 0, s[34:35]
	v_pk_fma_f32 v[88:89], v[40:41], v[88:89], v[152:153]
	v_pk_fma_f32 v[90:91], v[42:43], v[90:91], v[154:155]
	v_pk_fma_f32 v[76:77], v[60:61], v[76:77], v[156:157]
	v_pk_fma_f32 v[78:79], v[62:63], v[78:79], v[158:159]
	v_pk_fma_f32 v[88:89], v[72:73], v[84:85], v[88:89]
	v_pk_fma_f32 v[90:91], v[74:75], v[86:87], v[90:91]
	v_pk_fma_f32 v[76:77], v[64:65], v[92:93], v[76:77]
	v_pk_fma_f32 v[78:79], v[66:67], v[94:95], v[78:79]
	s_mov_b64 s[30:31], exec
	s_andn2_b64 exec, exec, s[36:37]
	v_pk_fma_f32 v[88:89], v[124:125], v[0:1], v[88:89]
	v_pk_fma_f32 v[90:91], v[126:127], v[2:3], v[90:91]
	v_pk_fma_f32 v[76:77], v[132:133], v[128:129], v[76:77]
	v_pk_fma_f32 v[78:79], v[134:135], v[130:131], v[78:79]
	s_mov_b64 exec, s[30:31]
	v_and_b32_e32 v212, 0x7fffffff, v88
	v_and_b32_e32 v213, 0x7fffffff, v89
	v_and_b32_e32 v6, 0x7fffffff, v90
	v_and_b32_e32 v7, 0x7fffffff, v91
	v_pk_fma_f32 v[238:239], v[212:213], s[90:91], 1.0 op_sel_hi:[1,0,0]
	v_pk_fma_f32 v[8:9], v[6:7], s[90:91], 1.0 op_sel_hi:[1,0,0]
	v_pk_mul_f32 v[4:5], v[88:89], v[88:89]
	v_pk_mul_f32 v[16:17], v[90:91], v[90:91]
	v_rcp_f32_e32 v238, v238
	v_rcp_f32_e32 v239, v239
	v_rcp_f32_e32 v8, v8
	v_rcp_f32_e32 v9, v9
	v_pk_mul_f32 v[4:5], v[4:5], s[44:45] op_sel_hi:[1,0]
	v_pk_mul_f32 v[16:17], v[16:17], s[44:45] op_sel_hi:[1,0]
	v_pk_fma_f32 v[246:247], v[238:239], s[92:93], v[236:237] op_sel_hi:[1,0,0]
	v_pk_fma_f32 v[10:11], v[8:9], s[92:93], v[236:237] op_sel_hi:[1,0,0]
	v_exp_f32_e32 v4, v4
	v_exp_f32_e32 v5, v5
	v_exp_f32_e32 v16, v16
	v_exp_f32_e32 v17, v17
	v_pk_fma_f32 v[246:247], v[238:239], v[246:247], s[96:97] op_sel_hi:[1,1,0]
	v_pk_fma_f32 v[10:11], v[8:9], v[10:11], s[96:97] op_sel_hi:[1,1,0]
	v_pk_fma_f32 v[246:247], v[238:239], v[246:247], s[0:1] op_sel_hi:[1,1,0]
	v_pk_fma_f32 v[10:11], v[8:9], v[10:11], s[0:1] op_sel_hi:[1,1,0]
	v_pk_fma_f32 v[246:247], v[238:239], v[246:247], s[4:5] op_sel_hi:[1,1,0]
	v_pk_fma_f32 v[10:11], v[8:9], v[10:11], s[4:5] op_sel_hi:[1,1,0]
	v_pk_mul_f32 v[246:247], v[238:239], v[246:247]
	v_pk_mul_f32 v[10:11], v[8:9], v[10:11]
	v_max_f32_e32 v238, 0, v88
	v_max_f32_e32 v239, 0, v89
	v_max_f32_e32 v8, 0, v90
	v_max_f32_e32 v9, 0, v91
	v_pk_mul_f32 v[246:247], v[4:5], v[246:247]
	v_pk_mul_f32 v[10:11], v[16:17], v[10:11]
	v_pk_fma_f32 v[4:5], v[212:213], v[246:247], v[238:239] neg_lo:[1,0,0] neg_hi:[1,0,0]
	v_pk_fma_f32 v[16:17], v[6:7], v[10:11], v[8:9] neg_lo:[1,0,0] neg_hi:[1,0,0]
	v_pk_mul_f32 v[246:247], v[4:5], v[76:77]
	v_pk_mul_f32 v[10:11], v[16:17], v[78:79]
	v_cvt_pk_bf16_f32 v14, v246, v247
	v_cvt_pk_bf16_f32 v15, v10, v11
	v_add_u32_e32 v235, 129, v227
	v_add_u32_e32 v245, 130, v228
	v_cmp_gt_u32_e64 s[38:39], s64, v235
	v_cmp_gt_u32_e32 vcc, s88, v245
	v_add_u32_e32 v235, 732160, v230
	s_and_b64 s[38:39], s[38:39], vcc
	s_and_saveexec_b64 s[30:31], s[38:39]
	global_store_dwordx4 v235, v[12:15], s[50:51]
	s_mov_b64 exec, s[30:31]
	s_nop 1
	v_add_u32_e32 v235, 131, v228
	v_cmp_gt_i32_e32 vcc, 0x4000, v235
	s_nop 1
	v_cndmask_b32_e32 v245, v222, v221, vcc
	v_and_b32_e32 v235, v235, v245
	v_cmp_eq_u32_e64 s[34:35], 0, v235
	v_cmp_eq_u32_e64 s[36:37], v235, v245
	s_nop 1
	v_cndmask_b32_e64 v72, v72, 0, s[34:35]
	v_cndmask_b32_e64 v73, v73, 0, s[34:35]
	v_cndmask_b32_e64 v74, v74, 0, s[34:35]
	v_cndmask_b32_e64 v75, v75, 0, s[34:35]
	v_cndmask_b32_e64 v64, v64, 0, s[34:35]
	v_cndmask_b32_e64 v65, v65, 0, s[34:35]
	v_cndmask_b32_e64 v66, v66, 0, s[34:35]
	v_cndmask_b32_e64 v67, v67, 0, s[34:35]
	v_pk_fma_f32 v[72:73], v[40:41], v[72:73], v[152:153]
	v_pk_fma_f32 v[74:75], v[42:43], v[74:75], v[154:155]
	v_pk_fma_f32 v[64:65], v[60:61], v[64:65], v[156:157]
	v_pk_fma_f32 v[66:67], v[62:63], v[66:67], v[158:159]
	v_pk_fma_f32 v[72:73], v[0:1], v[84:85], v[72:73]
	v_pk_fma_f32 v[74:75], v[2:3], v[86:87], v[74:75]
	v_pk_fma_f32 v[64:65], v[128:129], v[92:93], v[64:65]
	v_pk_fma_f32 v[66:67], v[130:131], v[94:95], v[66:67]
	s_mov_b64 s[30:31], exec
	s_andn2_b64 exec, exec, s[36:37]
	v_pk_fma_f32 v[72:73], v[124:125], v[20:21], v[72:73]
	v_pk_fma_f32 v[74:75], v[126:127], v[22:23], v[74:75]
	v_pk_fma_f32 v[64:65], v[132:133], v[24:25], v[64:65]
	v_pk_fma_f32 v[66:67], v[134:135], v[26:27], v[66:67]
	s_mov_b64 exec, s[30:31]
	v_and_b32_e32 v212, 0x7fffffff, v72
	v_and_b32_e32 v213, 0x7fffffff, v73
	v_and_b32_e32 v6, 0x7fffffff, v74
	v_and_b32_e32 v7, 0x7fffffff, v75
	v_pk_fma_f32 v[238:239], v[212:213], s[90:91], 1.0 op_sel_hi:[1,0,0]
	v_pk_fma_f32 v[8:9], v[6:7], s[90:91], 1.0 op_sel_hi:[1,0,0]
	v_pk_mul_f32 v[4:5], v[72:73], v[72:73]
	v_pk_mul_f32 v[12:13], v[74:75], v[74:75]
	v_rcp_f32_e32 v238, v238
	v_rcp_f32_e32 v239, v239
	v_rcp_f32_e32 v8, v8
	v_rcp_f32_e32 v9, v9
	v_pk_mul_f32 v[4:5], v[4:5], s[44:45] op_sel_hi:[1,0]
	v_pk_mul_f32 v[12:13], v[12:13], s[44:45] op_sel_hi:[1,0]
	v_pk_fma_f32 v[246:247], v[238:239], s[92:93], v[236:237] op_sel_hi:[1,0,0]
	v_pk_fma_f32 v[10:11], v[8:9], s[92:93], v[236:237] op_sel_hi:[1,0,0]
	v_exp_f32_e32 v4, v4
	v_exp_f32_e32 v5, v5
	v_exp_f32_e32 v12, v12
	v_exp_f32_e32 v13, v13
	v_pk_fma_f32 v[246:247], v[238:239], v[246:247], s[96:97] op_sel_hi:[1,1,0]
	v_pk_fma_f32 v[10:11], v[8:9], v[10:11], s[96:97] op_sel_hi:[1,1,0]
	v_pk_fma_f32 v[246:247], v[238:239], v[246:247], s[0:1] op_sel_hi:[1,1,0]
	v_pk_fma_f32 v[10:11], v[8:9], v[10:11], s[0:1] op_sel_hi:[1,1,0]
	v_pk_fma_f32 v[246:247], v[238:239], v[246:247], s[4:5] op_sel_hi:[1,1,0]
	v_pk_fma_f32 v[10:11], v[8:9], v[10:11], s[4:5] op_sel_hi:[1,1,0]
	v_pk_mul_f32 v[246:247], v[238:239], v[246:247]
	v_pk_mul_f32 v[10:11], v[8:9], v[10:11]
	v_max_f32_e32 v238, 0, v72
	v_max_f32_e32 v239, 0, v73
	v_max_f32_e32 v8, 0, v74
	v_max_f32_e32 v9, 0, v75
	v_pk_mul_f32 v[246:247], v[4:5], v[246:247]
	v_pk_mul_f32 v[10:11], v[12:13], v[10:11]
	v_pk_fma_f32 v[4:5], v[212:213], v[246:247], v[238:239] neg_lo:[1,0,0] neg_hi:[1,0,0]
	v_pk_fma_f32 v[12:13], v[6:7], v[10:11], v[8:9] neg_lo:[1,0,0] neg_hi:[1,0,0]
	v_pk_mul_f32 v[246:247], v[4:5], v[64:65]
	v_pk_mul_f32 v[10:11], v[12:13], v[66:67]
	v_cvt_pk_bf16_f32 v166, v246, v247
	v_cvt_pk_bf16_f32 v167, v10, v11
	v_add_u32_e32 v235, 130, v227
	v_add_u32_e32 v245, 131, v228
	v_cmp_gt_u32_e64 s[38:39], s64, v235
	v_cmp_gt_u32_e32 vcc, s88, v245
	v_add_u32_e32 v235, 737792, v230
	s_and_b64 s[38:39], s[38:39], vcc
	s_and_saveexec_b64 s[30:31], s[38:39]
	global_store_dwordx4 v235, v[164:167], s[50:51]
	s_mov_b64 exec, s[30:31]
	s_nop 1
